# 4-phase GEMM loops with four deferred counted vmcnt waits per iteration (each staging gets >=2.5 phases before its wait)
# speedup vs baseline: 1.0125x; 1.0125x over previous
; #define PG8_STAGE(bufoff, gbase, voff) do { _Pragma("unroll") for (int _i = 0; _i < 2; ++_i) \
;         __builtin_amdgcn_global_load_lds((const unsigned*)((const char*)(gbase) + (voff)[_i]), (LAS unsigned*)(lds + (bufoff) + ldsw + _i * 8192), 16, 0, 0); } while (0)
; #define PG8_LDA(dst, b, h) do { _Pragma("unroll") for (int m = 0; m < 4; ++m) _Pragma("unroll") for (int k = 0; k < 2; ++k) dst[m][k] = *(const LAS bf16x8*)(lds + PG8_SA(b, h) + aoff + m * 2048 + k * 1024); } while (0)
; #define PG8_LDB(dst, b, h) do { _Pragma("unroll") for (int n = 0; n < 2; ++n) _Pragma("unroll") for (int k = 0; k < 2; ++k) dst[n][k] = *(const LAS bf16x8*)(lds + PG8_SB(b, h) + boff + n * 2048 + k * 1024); } while (0)
; #define PG8_MMA(ai, bj, At, Bt) do { __builtin_amdgcn_s_setprio(1); _Pragma("unroll") for (int m = 0; m < 4; ++m) _Pragma("unroll") for (int n = 0; n < 2; ++n) _Pragma("unroll") for (int k = 0; k < 2; ++k) \
;         acc[ai][bj][m][n] = __builtin_amdgcn_mfma_f32_16x16x32_bf16(Bt[n][k], At[m][k], acc[ai][bj][m][n], 0, 0, 0); __builtin_amdgcn_s_setprio(0); } while (0)
; #define PG8_WAIT_V(n) asm volatile("s_waitcnt vmcnt(" #n ")" ::: "memory")
; #define PG8_WAIT_L(n) asm volatile("s_waitcnt lgkmcnt(" #n ")" ::: "memory")
; template <class Epi, class Sched>
; __device__ __forceinline__ void gemm_phase(LAS unsigned char* lds, const Gemm g, const Sched& S, const Epi& E) {
;     ...
;         for (int t = 0; t < nt; t += 2) {
;             const bool last = (t == nt - 2);
;             const char* a1 = cA + (size_t)(t + 1) * kstep;
;             const char* a2 = last ? nA : cA + (size_t)(t + 2) * kstep; const char* b2 = last ? nB : cB + (size_t)(t + 2) * kstep;
;             const char* a3 = a2 + kstep; const char* b3 = b2 + kstep;
;             PG8_LDB(B0, 0, 0); PG8_SCHED; PG8_LDA(At, 0, 0); PG8_STAGE(PG8_SA(1, 1), a1 + hstep, voffA);
;             PG8_WAIT_L(8); PG8_BAR; PG8_WAIT_L(0); PG8_MMA(0, 0, At, B0); PG8_BAR; PG8_SCHED;
;             PG8_LDB(B1, 0, 1); PG8_STAGE(PG8_SB(0, 0), b2, voffB);
;             PG8_BAR; PG8_WAIT_L(0); PG8_MMA(0, 1, At, B1); PG8_BAR;
;             PG8_LDA(At, 0, 1); PG8_STAGE(PG8_SA(0, 0), a2, voffA);
;             PG8_BAR; PG8_WAIT_L(0); PG8_MMA(1, 0, At, B0); PG8_BAR; PG8_SCHED;
;             PG8_STAGE(PG8_SB(0, 1), b2 + hstep, voffB);
;             PG8_WAIT_V(6); PG8_BAR; PG8_MMA(1, 1, At, B1); PG8_BAR;
.LBB0_44:
	s_add_u32 s50, s28, 0x100
	s_addc_u32 s51, s29, 0
	s_cmpk_eq_i32 s75, 0x7c
	s_cselect_b32 s55, s27, s51
	s_cselect_b32 s54, s71, s50
	s_cselect_b32 s53, s25, s74
	s_cselect_b32 s52, s72, s73
	v_lshl_add_u64 v[156:157], s[28:29], 0, v[150:151]
	s_add_i32 m0, s9, 0xc000
	s_nop 0
	global_load_lds_dwordx4 v[156:157], off
	v_lshl_add_u64 v[156:157], s[28:29], 0, v[148:149]
	s_add_i32 m0, s9, 0xe000
	s_nop 0
	global_load_lds_dwordx4 v[156:157], off
	s_add_i32 s38, 0, 0x10000
	v_add_u32_e32 v78, s38, v163
	ds_read_b128 v[66:69], v78
	ds_read_b128 v[70:73], v78 offset:1024
	ds_read_b128 v[74:77], v78 offset:2048
	ds_read_b128 v[78:81], v78 offset:3072
	ds_read_b128 v[152:155], v165
	ds_read_b128 v[166:169], v165 offset:1024
	ds_read_b128 v[170:173], v165 offset:2048
	ds_read_b128 v[174:177], v165 offset:3072
	ds_read_b128 v[178:181], v165 offset:4096
	ds_read_b128 v[182:185], v165 offset:5120
	ds_read_b128 v[186:189], v165 offset:6144
	ds_read_b128 v[190:193], v165 offset:7168
	s_add_i32 s39, 0, 0x14000
	v_add_u32_e32 v156, s39, v163
	ds_read_b128 v[194:197], v156
	ds_read_b128 v[198:201], v156 offset:1024
	ds_read_b128 v[202:205], v156 offset:2048
	ds_read_b128 v[210:213], v156 offset:3072
	s_waitcnt vmcnt(8)
	s_waitcnt lgkmcnt(4)
	s_barrier
	s_waitcnt lgkmcnt(0)
	s_setprio 1
	v_mfma_f32_16x16x32_bf16 v[142:145], v[66:69], v[152:155], v[142:145]
	v_mfma_f32_16x16x32_bf16 v[138:141], v[74:77], v[152:155], v[138:141]
	v_mfma_f32_16x16x32_bf16 v[126:129], v[66:69], v[170:173], v[126:129]
	v_mfma_f32_16x16x32_bf16 v[122:125], v[74:77], v[170:173], v[122:125]
	v_mfma_f32_16x16x32_bf16 v[110:113], v[66:69], v[178:181], v[110:113]
	v_mfma_f32_16x16x32_bf16 v[106:109], v[74:77], v[178:181], v[106:109]
	v_mfma_f32_16x16x32_bf16 v[102:105], v[66:69], v[186:189], v[102:105]
	v_mfma_f32_16x16x32_bf16 v[98:101], v[74:77], v[186:189], v[98:101]
	v_mfma_f32_16x16x32_bf16 v[142:145], v[70:73], v[166:169], v[142:145]
	v_mfma_f32_16x16x32_bf16 v[138:141], v[78:81], v[166:169], v[138:141]
	v_mfma_f32_16x16x32_bf16 v[126:129], v[70:73], v[174:177], v[126:129]
	v_mfma_f32_16x16x32_bf16 v[122:125], v[78:81], v[174:177], v[122:125]
	v_mfma_f32_16x16x32_bf16 v[110:113], v[70:73], v[182:185], v[110:113]
	v_mfma_f32_16x16x32_bf16 v[106:109], v[78:81], v[182:185], v[106:109]
	v_mfma_f32_16x16x32_bf16 v[102:105], v[70:73], v[190:193], v[102:105]
	v_mfma_f32_16x16x32_bf16 v[98:101], v[78:81], v[190:193], v[98:101]
	v_mfma_f32_16x16x32_bf16 v[134:137], v[194:197], v[152:155], v[134:137]
	v_mfma_f32_16x16x32_bf16 v[130:133], v[202:205], v[152:155], v[130:133]
	v_mfma_f32_16x16x32_bf16 v[118:121], v[194:197], v[170:173], v[118:121]
	v_mfma_f32_16x16x32_bf16 v[114:117], v[202:205], v[170:173], v[114:117]
	v_mfma_f32_16x16x32_bf16 v[94:97], v[194:197], v[178:181], v[94:97]
	v_mfma_f32_16x16x32_bf16 v[90:93], v[202:205], v[178:181], v[90:93]
	v_mfma_f32_16x16x32_bf16 v[86:89], v[194:197], v[186:189], v[86:89]
	v_mfma_f32_16x16x32_bf16 v[82:85], v[202:205], v[186:189], v[82:85]
	v_mfma_f32_16x16x32_bf16 v[134:137], v[198:201], v[166:169], v[134:137]
	v_mfma_f32_16x16x32_bf16 v[130:133], v[210:213], v[166:169], v[130:133]
	v_mfma_f32_16x16x32_bf16 v[118:121], v[198:201], v[174:177], v[118:121]
	v_mfma_f32_16x16x32_bf16 v[114:117], v[210:213], v[174:177], v[114:117]
	v_mfma_f32_16x16x32_bf16 v[94:97], v[198:201], v[182:185], v[94:97]
	v_mfma_f32_16x16x32_bf16 v[90:93], v[210:213], v[182:185], v[90:93]
	v_mfma_f32_16x16x32_bf16 v[86:89], v[198:201], v[190:193], v[86:89]
	v_mfma_f32_16x16x32_bf16 v[82:85], v[210:213], v[190:193], v[82:85]
	s_setprio 0
	s_barrier
	s_add_i32 s28, s38, s60
	v_lshl_add_u64 v[156:157], s[52:53], 0, v[0:1]
	s_mov_b32 m0, s28
	v_lshl_add_u64 v[160:161], s[52:53], 0, v[146:147]
	global_load_lds_dwordx4 v[156:157], off
	s_add_i32 m0, s28, 0x2000
	s_nop 0
	global_load_lds_dwordx4 v[160:161], off
	s_mov_b32 m0, s9
	v_lshl_add_u64 v[206:207], s[54:55], 0, v[0:1]
	global_load_lds_dwordx4 v[206:207], off
	v_lshl_add_u64 v[214:215], s[54:55], 0, v[146:147]
	s_mov_b32 m0, s61
	s_nop 0
	global_load_lds_dwordx4 v[214:215], off
	ds_read_b128 v[152:155], v165 offset:16384
	ds_read_b128 v[166:169], v165 offset:17408
	ds_read_b128 v[170:173], v165 offset:18432
	ds_read_b128 v[174:177], v165 offset:19456
	ds_read_b128 v[178:181], v165 offset:20480
	ds_read_b128 v[182:185], v165 offset:21504
	ds_read_b128 v[186:189], v165 offset:22528
	ds_read_b128 v[190:193], v165 offset:23552
	s_waitcnt vmcnt(6)
	s_waitcnt lgkmcnt(0)
	s_barrier
	s_setprio 1
	v_mfma_f32_16x16x32_bf16 v[62:65], v[66:69], v[152:155], v[62:65]
	v_mfma_f32_16x16x32_bf16 v[58:61], v[74:77], v[152:155], v[58:61]
	v_mfma_f32_16x16x32_bf16 v[46:49], v[66:69], v[170:173], v[46:49]
	v_mfma_f32_16x16x32_bf16 v[42:45], v[74:77], v[170:173], v[42:45]
	v_mfma_f32_16x16x32_bf16 v[30:33], v[66:69], v[178:181], v[30:33]
	v_mfma_f32_16x16x32_bf16 v[26:29], v[74:77], v[178:181], v[26:29]
	v_mfma_f32_16x16x32_bf16 v[22:25], v[66:69], v[186:189], v[22:25]
	v_mfma_f32_16x16x32_bf16 v[14:17], v[74:77], v[186:189], v[14:17]
	v_mfma_f32_16x16x32_bf16 v[62:65], v[70:73], v[166:169], v[62:65]
	v_mfma_f32_16x16x32_bf16 v[58:61], v[78:81], v[166:169], v[58:61]
	v_mfma_f32_16x16x32_bf16 v[46:49], v[70:73], v[174:177], v[46:49]
	v_mfma_f32_16x16x32_bf16 v[42:45], v[78:81], v[174:177], v[42:45]
	v_mfma_f32_16x16x32_bf16 v[30:33], v[70:73], v[182:185], v[30:33]
	v_mfma_f32_16x16x32_bf16 v[26:29], v[78:81], v[182:185], v[26:29]
	v_mfma_f32_16x16x32_bf16 v[22:25], v[70:73], v[190:193], v[22:25]
	v_mfma_f32_16x16x32_bf16 v[14:17], v[78:81], v[190:193], v[14:17]
	v_mfma_f32_16x16x32_bf16 v[54:57], v[194:197], v[152:155], v[54:57]
	v_mfma_f32_16x16x32_bf16 v[50:53], v[202:205], v[152:155], v[50:53]
	v_mfma_f32_16x16x32_bf16 v[38:41], v[194:197], v[170:173], v[38:41]
	v_mfma_f32_16x16x32_bf16 v[34:37], v[202:205], v[170:173], v[34:37]
	v_mfma_f32_16x16x32_bf16 v[18:21], v[194:197], v[178:181], v[18:21]
	v_mfma_f32_16x16x32_bf16 v[10:13], v[202:205], v[178:181], v[10:13]
	v_mfma_f32_16x16x32_bf16 v[6:9], v[194:197], v[186:189], v[6:9]
	v_mfma_f32_16x16x32_bf16 v[2:5], v[202:205], v[186:189], v[2:5]
	v_mfma_f32_16x16x32_bf16 v[54:57], v[198:201], v[166:169], v[54:57]
	v_mfma_f32_16x16x32_bf16 v[50:53], v[210:213], v[166:169], v[50:53]
	v_mfma_f32_16x16x32_bf16 v[38:41], v[198:201], v[174:177], v[38:41]
	v_mfma_f32_16x16x32_bf16 v[34:37], v[210:213], v[174:177], v[34:37]
	v_mfma_f32_16x16x32_bf16 v[18:21], v[198:201], v[182:185], v[18:21]
	v_mfma_f32_16x16x32_bf16 v[10:13], v[210:213], v[182:185], v[10:13]
	v_mfma_f32_16x16x32_bf16 v[6:9], v[198:201], v[190:193], v[6:9]
	v_mfma_f32_16x16x32_bf16 v[2:5], v[210:213], v[190:193], v[2:5]
	s_setprio 0
	s_barrier
; #define PG8_STAGE(bufoff, gbase, voff) do { _Pragma("unroll") for (int _i = 0; _i < 2; ++_i) \
;         __builtin_amdgcn_global_load_lds((const unsigned*)((const char*)(gbase) + (voff)[_i]), (LAS unsigned*)(lds + (bufoff) + ldsw + _i * 8192), 16, 0, 0); } while (0)
; #define PG8_LDA(dst, b, h) do { _Pragma("unroll") for (int m = 0; m < 4; ++m) _Pragma("unroll") for (int k = 0; k < 2; ++k) dst[m][k] = *(const LAS bf16x8*)(lds + PG8_SA(b, h) + aoff + m * 2048 + k * 1024); } while (0)
; #define PG8_LDB(dst, b, h) do { _Pragma("unroll") for (int n = 0; n < 2; ++n) _Pragma("unroll") for (int k = 0; k < 2; ++k) dst[n][k] = *(const LAS bf16x8*)(lds + PG8_SB(b, h) + boff + n * 2048 + k * 1024); } while (0)
; #define PG8_MMA(ai, bj, At, Bt) do { __builtin_amdgcn_s_setprio(1); _Pragma("unroll") for (int m = 0; m < 4; ++m) _Pragma("unroll") for (int n = 0; n < 2; ++n) _Pragma("unroll") for (int k = 0; k < 2; ++k) \
;         acc[ai][bj][m][n] = __builtin_amdgcn_mfma_f32_16x16x32_bf16(Bt[n][k], At[m][k], acc[ai][bj][m][n], 0, 0, 0); __builtin_amdgcn_s_setprio(0); } while (0)
; #define PG8_WAIT_V(n) asm volatile("s_waitcnt vmcnt(" #n ")" ::: "memory")
; #define PG8_WAIT_L(n) asm volatile("s_waitcnt lgkmcnt(" #n ")" ::: "memory")
; #define PG8_BAR __builtin_amdgcn_s_barrier()
; #define PG8_SCHED __builtin_amdgcn_sched_barrier(0)
; template <class Epi, class Sched>
; __device__ __forceinline__ void gemm_phase(LAS unsigned char* lds, const Gemm g, const Sched& S, const Epi& E) {
;     ...
;             PG8_STAGE(PG8_SB(0, 1), b2 + hstep, voffB);
;             PG8_WAIT_V(6); PG8_BAR; PG8_MMA(1, 1, At, B1); PG8_BAR;
;             PG8_LDB(B0, 1, 0); PG8_SCHED; PG8_LDA(At, 1, 0); PG8_STAGE(PG8_SA(0, 1), a2 + hstep, voffA);
;             PG8_WAIT_L(8); PG8_BAR; PG8_WAIT_L(0); PG8_MMA(0, 0, At, B0); PG8_BAR; PG8_SCHED;
;             PG8_LDB(B1, 1, 1); PG8_STAGE(PG8_SB(1, 0), b3, voffB);
;             PG8_BAR; PG8_WAIT_L(0); PG8_MMA(0, 1, At, B1); PG8_BAR;
;             PG8_LDA(At, 1, 1); PG8_STAGE(PG8_SA(1, 0), a3, voffA);
;             PG8_BAR; PG8_WAIT_L(0); PG8_MMA(1, 0, At, B0); PG8_BAR; PG8_SCHED;
	s_add_u32 s28, s52, 0x200000
	s_addc_u32 s29, s53, 0
	s_add_i32 s38, s39, s60
	v_lshl_add_u64 v[66:67], s[28:29], 0, v[0:1]
	s_mov_b32 m0, s38
	s_nop 0
	global_load_lds_dwordx4 v[66:67], off
	v_lshl_add_u64 v[66:67], s[28:29], 0, v[146:147]
	s_add_i32 m0, s38, 0x2000
	s_nop 0
	global_load_lds_dwordx4 v[66:67], off
	s_add_u32 s28, s54, 0x200000
	s_addc_u32 s29, s55, 0
	s_mov_b32 m0, s62
	v_lshl_add_u64 v[194:195], s[28:29], 0, v[0:1]
	global_load_lds_dwordx4 v[194:195], off
	v_lshl_add_u64 v[194:195], s[28:29], 0, v[146:147]
	s_mov_b32 m0, s63
	s_nop 0
	global_load_lds_dwordx4 v[194:195], off
	s_add_i32 s38, 0, 0x18000
	v_add_u32_e32 v78, s38, v163
	ds_read_b128 v[66:69], v78
	ds_read_b128 v[70:73], v78 offset:1024
	ds_read_b128 v[74:77], v78 offset:2048
	ds_read_b128 v[78:81], v78 offset:3072
	ds_read_b128 v[152:155], v165 offset:32768
	ds_read_b128 v[166:169], v165 offset:33792
	ds_read_b128 v[170:173], v165 offset:34816
	ds_read_b128 v[174:177], v165 offset:35840
	ds_read_b128 v[178:181], v165 offset:36864
	ds_read_b128 v[182:185], v165 offset:37888
	ds_read_b128 v[186:189], v165 offset:38912
	ds_read_b128 v[190:193], v165 offset:39936
	s_add_i32 s39, 0, 0x1c000
	v_add_u32_e32 v210, s39, v163
	ds_read_b128 v[194:197], v210
	ds_read_b128 v[198:201], v210 offset:1024
	ds_read_b128 v[202:205], v210 offset:2048
	ds_read_b128 v[210:213], v210 offset:3072
	s_waitcnt vmcnt(8)
	s_waitcnt lgkmcnt(4)
	s_barrier
	s_waitcnt lgkmcnt(0)
	s_setprio 1
	v_mfma_f32_16x16x32_bf16 v[142:145], v[66:69], v[152:155], v[142:145]
	v_mfma_f32_16x16x32_bf16 v[138:141], v[74:77], v[152:155], v[138:141]
	v_mfma_f32_16x16x32_bf16 v[126:129], v[66:69], v[170:173], v[126:129]
	v_mfma_f32_16x16x32_bf16 v[122:125], v[74:77], v[170:173], v[122:125]
	v_mfma_f32_16x16x32_bf16 v[110:113], v[66:69], v[178:181], v[110:113]
	v_mfma_f32_16x16x32_bf16 v[106:109], v[74:77], v[178:181], v[106:109]
	v_mfma_f32_16x16x32_bf16 v[102:105], v[66:69], v[186:189], v[102:105]
	v_mfma_f32_16x16x32_bf16 v[98:101], v[74:77], v[186:189], v[98:101]
	v_mfma_f32_16x16x32_bf16 v[142:145], v[70:73], v[166:169], v[142:145]
	v_mfma_f32_16x16x32_bf16 v[138:141], v[78:81], v[166:169], v[138:141]
	v_mfma_f32_16x16x32_bf16 v[126:129], v[70:73], v[174:177], v[126:129]
	v_mfma_f32_16x16x32_bf16 v[122:125], v[78:81], v[174:177], v[122:125]
	v_mfma_f32_16x16x32_bf16 v[110:113], v[70:73], v[182:185], v[110:113]
	v_mfma_f32_16x16x32_bf16 v[106:109], v[78:81], v[182:185], v[106:109]
	v_mfma_f32_16x16x32_bf16 v[102:105], v[70:73], v[190:193], v[102:105]
	v_mfma_f32_16x16x32_bf16 v[98:101], v[78:81], v[190:193], v[98:101]
	v_mfma_f32_16x16x32_bf16 v[134:137], v[194:197], v[152:155], v[134:137]
	v_mfma_f32_16x16x32_bf16 v[130:133], v[202:205], v[152:155], v[130:133]
	v_mfma_f32_16x16x32_bf16 v[118:121], v[194:197], v[170:173], v[118:121]
	v_mfma_f32_16x16x32_bf16 v[114:117], v[202:205], v[170:173], v[114:117]
	v_mfma_f32_16x16x32_bf16 v[94:97], v[194:197], v[178:181], v[94:97]
	v_mfma_f32_16x16x32_bf16 v[90:93], v[202:205], v[178:181], v[90:93]
	v_mfma_f32_16x16x32_bf16 v[86:89], v[194:197], v[186:189], v[86:89]
	v_mfma_f32_16x16x32_bf16 v[82:85], v[202:205], v[186:189], v[82:85]
	v_mfma_f32_16x16x32_bf16 v[134:137], v[198:201], v[166:169], v[134:137]
	v_mfma_f32_16x16x32_bf16 v[130:133], v[210:213], v[166:169], v[130:133]
	v_mfma_f32_16x16x32_bf16 v[118:121], v[198:201], v[174:177], v[118:121]
	v_mfma_f32_16x16x32_bf16 v[114:117], v[210:213], v[174:177], v[114:117]
	v_mfma_f32_16x16x32_bf16 v[94:97], v[198:201], v[182:185], v[94:97]
	v_mfma_f32_16x16x32_bf16 v[90:93], v[210:213], v[182:185], v[90:93]
	v_mfma_f32_16x16x32_bf16 v[86:89], v[198:201], v[190:193], v[86:89]
	v_mfma_f32_16x16x32_bf16 v[82:85], v[210:213], v[190:193], v[82:85]
	s_setprio 0
	s_barrier
; #define PG8_STAGE(bufoff, gbase, voff) do { _Pragma("unroll") for (int _i = 0; _i < 2; ++_i) \
;         __builtin_amdgcn_global_load_lds((const unsigned*)((const char*)(gbase) + (voff)[_i]), (LAS unsigned*)(lds + (bufoff) + ldsw + _i * 8192), 16, 0, 0); } while (0)
; #define PG8_LDA(dst, b, h) do { _Pragma("unroll") for (int m = 0; m < 4; ++m) _Pragma("unroll") for (int k = 0; k < 2; ++k) dst[m][k] = *(const LAS bf16x8*)(lds + PG8_SA(b, h) + aoff + m * 2048 + k * 1024); } while (0)
; #define PG8_LDB(dst, b, h) do { _Pragma("unroll") for (int n = 0; n < 2; ++n) _Pragma("unroll") for (int k = 0; k < 2; ++k) dst[n][k] = *(const LAS bf16x8*)(lds + PG8_SB(b, h) + boff + n * 2048 + k * 1024); } while (0)
; #define PG8_MMA(ai, bj, At, Bt) do { __builtin_amdgcn_s_setprio(1); _Pragma("unroll") for (int m = 0; m < 4; ++m) _Pragma("unroll") for (int n = 0; n < 2; ++n) _Pragma("unroll") for (int k = 0; k < 2; ++k) \
;         acc[ai][bj][m][n] = __builtin_amdgcn_mfma_f32_16x16x32_bf16(Bt[n][k], At[m][k], acc[ai][bj][m][n], 0, 0, 0); __builtin_amdgcn_s_setprio(0); } while (0)
; #define PG8_WAIT_V(n) asm volatile("s_waitcnt vmcnt(" #n ")" ::: "memory")
; #define PG8_WAIT_L(n) asm volatile("s_waitcnt lgkmcnt(" #n ")" ::: "memory")
; #define PG8_BAR __builtin_amdgcn_s_barrier()
; #define PG8_SCHED __builtin_amdgcn_sched_barrier(0)
; template <class Epi, class Sched>
; __device__ __forceinline__ void gemm_phase(LAS unsigned char* lds, const Gemm g, const Sched& S, const Epi& E) {
;     ...
;             PG8_LDB(B1, 1, 1); PG8_STAGE(PG8_SB(1, 0), b3, voffB);
;             PG8_BAR; PG8_WAIT_L(0); PG8_MMA(0, 1, At, B1); PG8_BAR;
;             PG8_LDA(At, 1, 1); PG8_STAGE(PG8_SA(1, 0), a3, voffA);
;             PG8_BAR; PG8_WAIT_L(0); PG8_MMA(1, 0, At, B0); PG8_BAR; PG8_SCHED;
;             PG8_STAGE(PG8_SB(1, 1), b3 + hstep, voffB);
;             PG8_WAIT_V(6); PG8_BAR; PG8_MMA(1, 1, At, B1); PG8_BAR;
;         }
;         E(acc, cur, wr, wc, fr, fq);
;         if (!has_next) break;
	s_add_i32 s28, s38, s60
	v_lshl_add_u64 v[156:157], v[156:157], 0, s[36:37]
	s_mov_b32 m0, s28
	s_nop 0
	global_load_lds_dwordx4 v[156:157], off
	v_lshl_add_u64 v[156:157], v[160:161], 0, s[36:37]
	s_add_i32 m0, s28, 0x2000
	s_nop 0
	global_load_lds_dwordx4 v[156:157], off
	s_mov_b32 m0, s66
	v_lshl_add_u64 v[156:157], v[206:207], 0, s[36:37]
	global_load_lds_dwordx4 v[156:157], off
	v_lshl_add_u64 v[156:157], v[214:215], 0, s[36:37]
	s_mov_b32 m0, s67
	s_nop 0
	global_load_lds_dwordx4 v[156:157], off
	ds_read_b128 v[152:155], v165 offset:49152
	ds_read_b128 v[166:169], v165 offset:50176
	ds_read_b128 v[170:173], v165 offset:51200
	ds_read_b128 v[174:177], v165 offset:52224
	ds_read_b128 v[178:181], v165 offset:53248
	ds_read_b128 v[182:185], v165 offset:54272
	ds_read_b128 v[186:189], v165 offset:55296
	ds_read_b128 v[190:193], v165 offset:56320
	s_waitcnt vmcnt(6)
	s_waitcnt lgkmcnt(0)
	s_barrier
	s_setprio 1
	v_mfma_f32_16x16x32_bf16 v[62:65], v[66:69], v[152:155], v[62:65]
	v_mfma_f32_16x16x32_bf16 v[58:61], v[74:77], v[152:155], v[58:61]
	v_mfma_f32_16x16x32_bf16 v[46:49], v[66:69], v[170:173], v[46:49]
	v_mfma_f32_16x16x32_bf16 v[42:45], v[74:77], v[170:173], v[42:45]
	v_mfma_f32_16x16x32_bf16 v[30:33], v[66:69], v[178:181], v[30:33]
	v_mfma_f32_16x16x32_bf16 v[26:29], v[74:77], v[178:181], v[26:29]
	v_mfma_f32_16x16x32_bf16 v[22:25], v[66:69], v[186:189], v[22:25]
	v_mfma_f32_16x16x32_bf16 v[14:17], v[74:77], v[186:189], v[14:17]
	v_mfma_f32_16x16x32_bf16 v[62:65], v[70:73], v[166:169], v[62:65]
	v_mfma_f32_16x16x32_bf16 v[58:61], v[78:81], v[166:169], v[58:61]
	v_mfma_f32_16x16x32_bf16 v[46:49], v[70:73], v[174:177], v[46:49]
	v_mfma_f32_16x16x32_bf16 v[42:45], v[78:81], v[174:177], v[42:45]
	v_mfma_f32_16x16x32_bf16 v[30:33], v[70:73], v[182:185], v[30:33]
	v_mfma_f32_16x16x32_bf16 v[26:29], v[78:81], v[182:185], v[26:29]
	v_mfma_f32_16x16x32_bf16 v[22:25], v[70:73], v[190:193], v[22:25]
	v_mfma_f32_16x16x32_bf16 v[14:17], v[78:81], v[190:193], v[14:17]
	s_add_u32 s28, s52, 0x200080
	s_addc_u32 s29, s53, 0
	s_add_i32 s38, s39, s60
	v_lshl_add_u64 v[66:67], s[28:29], 0, v[0:1]
	s_mov_b32 m0, s38
	s_nop 0
	global_load_lds_dwordx4 v[66:67], off
	v_lshl_add_u64 v[66:67], s[28:29], 0, v[146:147]
	s_add_i32 m0, s38, 0x2000
	s_nop 0
	global_load_lds_dwordx4 v[66:67], off
	v_mfma_f32_16x16x32_bf16 v[54:57], v[194:197], v[152:155], v[54:57]
	v_mfma_f32_16x16x32_bf16 v[50:53], v[202:205], v[152:155], v[50:53]
	v_mfma_f32_16x16x32_bf16 v[38:41], v[194:197], v[170:173], v[38:41]
	v_mfma_f32_16x16x32_bf16 v[34:37], v[202:205], v[170:173], v[34:37]
	v_mfma_f32_16x16x32_bf16 v[18:21], v[194:197], v[178:181], v[18:21]
	v_mfma_f32_16x16x32_bf16 v[10:13], v[202:205], v[178:181], v[10:13]
	v_mfma_f32_16x16x32_bf16 v[6:9], v[194:197], v[186:189], v[6:9]
	v_mfma_f32_16x16x32_bf16 v[2:5], v[202:205], v[186:189], v[2:5]
	v_mfma_f32_16x16x32_bf16 v[54:57], v[198:201], v[166:169], v[54:57]
	v_mfma_f32_16x16x32_bf16 v[50:53], v[210:213], v[166:169], v[50:53]
	v_mfma_f32_16x16x32_bf16 v[38:41], v[198:201], v[174:177], v[38:41]
	v_mfma_f32_16x16x32_bf16 v[34:37], v[210:213], v[174:177], v[34:37]
	v_mfma_f32_16x16x32_bf16 v[18:21], v[198:201], v[182:185], v[18:21]
	v_mfma_f32_16x16x32_bf16 v[10:13], v[210:213], v[182:185], v[10:13]
	v_mfma_f32_16x16x32_bf16 v[6:9], v[198:201], v[190:193], v[6:9]
	v_mfma_f32_16x16x32_bf16 v[2:5], v[210:213], v[190:193], v[2:5]
	s_setprio 0
	s_add_i32 s75, s75, 2
	s_add_u32 s73, s73, 0x100
	s_addc_u32 s74, s74, 0
	s_cmpk_gt_u32 s75, 0x7d
	s_mov_b64 s[28:29], s[50:51]
	s_barrier
	s_cbranch_scc0 .LBB0_44
	s_cmp_lt_i32 s8, 64
	s_cselect_b64 s[50:51], -1, 0
	s_cmp_gt_i32 s8, 63
	s_cbranch_scc0 .LBB0_35
	s_mov_b64 s[52:53], 0x18000
	s_mov_b64 s[28:29], s[46:47]
	s_branch .LBB0_36

; #define PG8_STAGE(bufoff, gbase, voff) do { _Pragma("unroll") for (int _i = 0; _i < 2; ++_i) \
;         __builtin_amdgcn_global_load_lds((const unsigned*)((const char*)(gbase) + (voff)[_i]), (LAS unsigned*)(lds + (bufoff) + ldsw + _i * 8192), 16, 0, 0); } while (0)
; #define PG8_LDA(dst, b, h) do { _Pragma("unroll") for (int m = 0; m < 4; ++m) _Pragma("unroll") for (int k = 0; k < 2; ++k) dst[m][k] = *(const LAS bf16x8*)(lds + PG8_SA(b, h) + aoff + m * 2048 + k * 1024); } while (0)
; #define PG8_LDB(dst, b, h) do { _Pragma("unroll") for (int n = 0; n < 2; ++n) _Pragma("unroll") for (int k = 0; k < 2; ++k) dst[n][k] = *(const LAS bf16x8*)(lds + PG8_SB(b, h) + boff + n * 2048 + k * 1024); } while (0)
; #define PG8_MMA(ai, bj, At, Bt) do { __builtin_amdgcn_s_setprio(1); _Pragma("unroll") for (int m = 0; m < 4; ++m) _Pragma("unroll") for (int n = 0; n < 2; ++n) _Pragma("unroll") for (int k = 0; k < 2; ++k) \
;         acc[ai][bj][m][n] = __builtin_amdgcn_mfma_f32_16x16x32_bf16(Bt[n][k], At[m][k], acc[ai][bj][m][n], 0, 0, 0); __builtin_amdgcn_s_setprio(0); } while (0)
; #define PG8_WAIT_V(n) asm volatile("s_waitcnt vmcnt(" #n ")" ::: "memory")
; #define PG8_WAIT_L(n) asm volatile("s_waitcnt lgkmcnt(" #n ")" ::: "memory")
; #define PG8_BAR __builtin_amdgcn_s_barrier()
; template <class Epi, class Sched>
; __device__ __forceinline__ void gemm_phase(LAS unsigned char* lds, const Gemm g, const Sched& S, const Epi& E) {
;     ...
;             const bool last = (t == nt - 2);
;             const char* a1 = cA + (size_t)(t + 1) * kstep;
;             const char* a2 = last ? nA : cA + (size_t)(t + 2) * kstep; const char* b2 = last ? nB : cB + (size_t)(t + 2) * kstep;
;             const char* a3 = a2 + kstep; const char* b3 = b2 + kstep;
;             PG8_LDB(B0, 0, 0); PG8_SCHED; PG8_LDA(At, 0, 0); PG8_STAGE(PG8_SA(1, 1), a1 + hstep, voffA);
;             PG8_WAIT_L(8); PG8_BAR; PG8_WAIT_L(0); PG8_MMA(0, 0, At, B0); PG8_BAR; PG8_SCHED;
;             PG8_LDB(B1, 0, 1); PG8_STAGE(PG8_SB(0, 0), b2, voffB);
;             PG8_BAR; PG8_WAIT_L(0); PG8_MMA(0, 1, At, B1); PG8_BAR;
;             PG8_LDA(At, 0, 1); PG8_STAGE(PG8_SA(0, 0), a2, voffA);
;             PG8_BAR; PG8_WAIT_L(0); PG8_MMA(1, 0, At, B0); PG8_BAR; PG8_SCHED;
;             PG8_STAGE(PG8_SB(0, 1), b2 + hstep, voffB);
;             PG8_WAIT_V(6); PG8_BAR; PG8_MMA(1, 1, At, B1); PG8_BAR;
.LBB0_58:
	s_add_u32 s52, s50, 0x100
	s_addc_u32 s53, s51, 0
	s_cmp_eq_u32 s71, 28
	s_cselect_b32 s57, s11, s53
	s_cselect_b32 s56, s29, s52
	s_cselect_b32 s55, s41, s70
	s_cselect_b32 s54, s43, s69
	v_lshl_add_u64 v[156:157], s[50:51], 0, v[134:135]
	s_add_i32 m0, s25, 0xc000
	s_nop 0
	global_load_lds_dwordx4 v[156:157], off
	v_lshl_add_u64 v[156:157], s[50:51], 0, v[132:133]
	s_add_i32 m0, s25, 0xe000
	s_nop 0
	global_load_lds_dwordx4 v[156:157], off
	s_add_i32 s38, 0, 0x10000
	v_add_u32_e32 v152, s38, v137
	ds_read_b128 v[140:143], v152
	ds_read_b128 v[144:147], v152 offset:1024
	ds_read_b128 v[148:151], v152 offset:2048
	ds_read_b128 v[152:155], v152 offset:3072
	ds_read_b128 v[160:163], v139
	ds_read_b128 v[164:167], v139 offset:1024
	ds_read_b128 v[168:171], v139 offset:2048
	ds_read_b128 v[172:175], v139 offset:3072
	ds_read_b128 v[176:179], v139 offset:4096
	ds_read_b128 v[180:183], v139 offset:5120
	ds_read_b128 v[184:187], v139 offset:6144
	ds_read_b128 v[188:191], v139 offset:7168
	s_add_i32 s50, 0, 0x14000
	v_add_u32_e32 v156, s50, v137
	ds_read_b128 v[192:195], v156
	ds_read_b128 v[196:199], v156 offset:1024
	ds_read_b128 v[200:203], v156 offset:2048
	ds_read_b128 v[204:207], v156 offset:3072
	s_waitcnt vmcnt(8)
	s_waitcnt lgkmcnt(4)
	s_barrier
	s_waitcnt lgkmcnt(0)
	s_setprio 1
	v_mfma_f32_16x16x32_bf16 v[126:129], v[140:143], v[160:163], v[126:129]
	v_mfma_f32_16x16x32_bf16 v[122:125], v[148:151], v[160:163], v[122:125]
	v_mfma_f32_16x16x32_bf16 v[118:121], v[140:143], v[168:171], v[118:121]
	v_mfma_f32_16x16x32_bf16 v[114:117], v[148:151], v[168:171], v[114:117]
	v_mfma_f32_16x16x32_bf16 v[106:109], v[140:143], v[176:179], v[106:109]
	v_mfma_f32_16x16x32_bf16 v[98:101], v[148:151], v[176:179], v[98:101]
	v_mfma_f32_16x16x32_bf16 v[90:93], v[140:143], v[184:187], v[90:93]
	v_mfma_f32_16x16x32_bf16 v[82:85], v[148:151], v[184:187], v[82:85]
	v_mfma_f32_16x16x32_bf16 v[126:129], v[144:147], v[164:167], v[126:129]
	v_mfma_f32_16x16x32_bf16 v[122:125], v[152:155], v[164:167], v[122:125]
	v_mfma_f32_16x16x32_bf16 v[118:121], v[144:147], v[172:175], v[118:121]
	v_mfma_f32_16x16x32_bf16 v[114:117], v[152:155], v[172:175], v[114:117]
	v_mfma_f32_16x16x32_bf16 v[106:109], v[144:147], v[180:183], v[106:109]
	v_mfma_f32_16x16x32_bf16 v[98:101], v[152:155], v[180:183], v[98:101]
	v_mfma_f32_16x16x32_bf16 v[90:93], v[144:147], v[188:191], v[90:93]
	v_mfma_f32_16x16x32_bf16 v[82:85], v[152:155], v[188:191], v[82:85]
	v_mfma_f32_16x16x32_bf16 v[110:113], v[192:195], v[160:163], v[110:113]
	v_mfma_f32_16x16x32_bf16 v[102:105], v[200:203], v[160:163], v[102:105]
	v_mfma_f32_16x16x32_bf16 v[94:97], v[192:195], v[168:171], v[94:97]
	v_mfma_f32_16x16x32_bf16 v[86:89], v[200:203], v[168:171], v[86:89]
	v_mfma_f32_16x16x32_bf16 v[78:81], v[192:195], v[176:179], v[78:81]
	v_mfma_f32_16x16x32_bf16 v[74:77], v[200:203], v[176:179], v[74:77]
	v_mfma_f32_16x16x32_bf16 v[70:73], v[192:195], v[184:187], v[70:73]
	v_mfma_f32_16x16x32_bf16 v[66:69], v[200:203], v[184:187], v[66:69]
	v_mfma_f32_16x16x32_bf16 v[110:113], v[196:199], v[164:167], v[110:113]
	v_mfma_f32_16x16x32_bf16 v[102:105], v[204:207], v[164:167], v[102:105]
	v_mfma_f32_16x16x32_bf16 v[94:97], v[196:199], v[172:175], v[94:97]
	v_mfma_f32_16x16x32_bf16 v[86:89], v[204:207], v[172:175], v[86:89]
	v_mfma_f32_16x16x32_bf16 v[78:81], v[196:199], v[180:183], v[78:81]
	v_mfma_f32_16x16x32_bf16 v[74:77], v[204:207], v[180:183], v[74:77]
	v_mfma_f32_16x16x32_bf16 v[70:73], v[196:199], v[188:191], v[70:73]
	v_mfma_f32_16x16x32_bf16 v[66:69], v[204:207], v[188:191], v[66:69]
	s_setprio 0
	s_barrier
	s_add_i32 s38, s38, s63
	v_lshl_add_u64 v[156:157], s[54:55], 0, v[0:1]
	s_mov_b32 m0, s38
	v_lshl_add_u64 v[210:211], s[54:55], 0, v[130:131]
	global_load_lds_dwordx4 v[156:157], off
	s_add_i32 m0, s38, 0x2000
	s_nop 0
	global_load_lds_dwordx4 v[210:211], off
	s_mov_b32 m0, s25
	v_lshl_add_u64 v[212:213], s[56:57], 0, v[0:1]
	global_load_lds_dwordx4 v[212:213], off
	v_lshl_add_u64 v[214:215], s[56:57], 0, v[130:131]
	s_mov_b32 m0, s27
	s_nop 0
	global_load_lds_dwordx4 v[214:215], off
	ds_read_b128 v[160:163], v139 offset:16384
	ds_read_b128 v[164:167], v139 offset:17408
	ds_read_b128 v[168:171], v139 offset:18432
	ds_read_b128 v[172:175], v139 offset:19456
	ds_read_b128 v[176:179], v139 offset:20480
	ds_read_b128 v[180:183], v139 offset:21504
	ds_read_b128 v[184:187], v139 offset:22528
	ds_read_b128 v[188:191], v139 offset:23552
	s_waitcnt vmcnt(6)
	s_waitcnt lgkmcnt(0)
	s_barrier
	s_setprio 1
	v_mfma_f32_16x16x32_bf16 v[62:65], v[140:143], v[160:163], v[62:65]
	v_mfma_f32_16x16x32_bf16 v[58:61], v[148:151], v[160:163], v[58:61]
	v_mfma_f32_16x16x32_bf16 v[54:57], v[140:143], v[168:171], v[54:57]
	v_mfma_f32_16x16x32_bf16 v[50:53], v[148:151], v[168:171], v[50:53]
	v_mfma_f32_16x16x32_bf16 v[38:41], v[140:143], v[176:179], v[38:41]
	v_mfma_f32_16x16x32_bf16 v[34:37], v[148:151], v[176:179], v[34:37]
	v_mfma_f32_16x16x32_bf16 v[22:25], v[140:143], v[184:187], v[22:25]
	v_mfma_f32_16x16x32_bf16 v[18:21], v[148:151], v[184:187], v[18:21]
	v_mfma_f32_16x16x32_bf16 v[62:65], v[144:147], v[164:167], v[62:65]
	v_mfma_f32_16x16x32_bf16 v[58:61], v[152:155], v[164:167], v[58:61]
	v_mfma_f32_16x16x32_bf16 v[54:57], v[144:147], v[172:175], v[54:57]
	v_mfma_f32_16x16x32_bf16 v[50:53], v[152:155], v[172:175], v[50:53]
	v_mfma_f32_16x16x32_bf16 v[38:41], v[144:147], v[180:183], v[38:41]
	v_mfma_f32_16x16x32_bf16 v[34:37], v[152:155], v[180:183], v[34:37]
	v_mfma_f32_16x16x32_bf16 v[22:25], v[144:147], v[188:191], v[22:25]
	v_mfma_f32_16x16x32_bf16 v[18:21], v[152:155], v[188:191], v[18:21]
	v_mfma_f32_16x16x32_bf16 v[46:49], v[192:195], v[160:163], v[46:49]
	v_mfma_f32_16x16x32_bf16 v[42:45], v[200:203], v[160:163], v[42:45]
	v_mfma_f32_16x16x32_bf16 v[30:33], v[192:195], v[168:171], v[30:33]
	v_mfma_f32_16x16x32_bf16 v[26:29], v[200:203], v[168:171], v[26:29]
	v_mfma_f32_16x16x32_bf16 v[14:17], v[192:195], v[176:179], v[14:17]
	v_mfma_f32_16x16x32_bf16 v[10:13], v[200:203], v[176:179], v[10:13]
	v_mfma_f32_16x16x32_bf16 v[6:9], v[192:195], v[184:187], v[6:9]
	v_mfma_f32_16x16x32_bf16 v[2:5], v[200:203], v[184:187], v[2:5]
	v_mfma_f32_16x16x32_bf16 v[46:49], v[196:199], v[164:167], v[46:49]
	v_mfma_f32_16x16x32_bf16 v[42:45], v[204:207], v[164:167], v[42:45]
	v_mfma_f32_16x16x32_bf16 v[30:33], v[196:199], v[172:175], v[30:33]
	v_mfma_f32_16x16x32_bf16 v[26:29], v[204:207], v[172:175], v[26:29]
	v_mfma_f32_16x16x32_bf16 v[14:17], v[196:199], v[180:183], v[14:17]
	v_mfma_f32_16x16x32_bf16 v[10:13], v[204:207], v[180:183], v[10:13]
	v_mfma_f32_16x16x32_bf16 v[6:9], v[196:199], v[188:191], v[6:9]
	v_mfma_f32_16x16x32_bf16 v[2:5], v[204:207], v[188:191], v[2:5]
	s_setprio 0
	s_barrier
; #define PG8_STAGE(bufoff, gbase, voff) do { _Pragma("unroll") for (int _i = 0; _i < 2; ++_i) \
;         __builtin_amdgcn_global_load_lds((const unsigned*)((const char*)(gbase) + (voff)[_i]), (LAS unsigned*)(lds + (bufoff) + ldsw + _i * 8192), 16, 0, 0); } while (0)
; #define PG8_LDA(dst, b, h) do { _Pragma("unroll") for (int m = 0; m < 4; ++m) _Pragma("unroll") for (int k = 0; k < 2; ++k) dst[m][k] = *(const LAS bf16x8*)(lds + PG8_SA(b, h) + aoff + m * 2048 + k * 1024); } while (0)
; #define PG8_LDB(dst, b, h) do { _Pragma("unroll") for (int n = 0; n < 2; ++n) _Pragma("unroll") for (int k = 0; k < 2; ++k) dst[n][k] = *(const LAS bf16x8*)(lds + PG8_SB(b, h) + boff + n * 2048 + k * 1024); } while (0)
; #define PG8_MMA(ai, bj, At, Bt) do { __builtin_amdgcn_s_setprio(1); _Pragma("unroll") for (int m = 0; m < 4; ++m) _Pragma("unroll") for (int n = 0; n < 2; ++n) _Pragma("unroll") for (int k = 0; k < 2; ++k) \
;         acc[ai][bj][m][n] = __builtin_amdgcn_mfma_f32_16x16x32_bf16(Bt[n][k], At[m][k], acc[ai][bj][m][n], 0, 0, 0); __builtin_amdgcn_s_setprio(0); } while (0)
; #define PG8_WAIT_V(n) asm volatile("s_waitcnt vmcnt(" #n ")" ::: "memory")
; #define PG8_WAIT_L(n) asm volatile("s_waitcnt lgkmcnt(" #n ")" ::: "memory")
; #define PG8_BAR __builtin_amdgcn_s_barrier()
; #define PG8_SCHED __builtin_amdgcn_sched_barrier(0)
; template <class Epi, class Sched>
; __device__ __forceinline__ void gemm_phase(LAS unsigned char* lds, const Gemm g, const Sched& S, const Epi& E) {
;     ...
;             PG8_STAGE(PG8_SB(0, 1), b2 + hstep, voffB);
;             PG8_WAIT_V(6); PG8_BAR; PG8_MMA(1, 1, At, B1); PG8_BAR;
;             PG8_LDB(B0, 1, 0); PG8_SCHED; PG8_LDA(At, 1, 0); PG8_STAGE(PG8_SA(0, 1), a2 + hstep, voffA);
;             PG8_WAIT_L(8); PG8_BAR; PG8_WAIT_L(0); PG8_MMA(0, 0, At, B0); PG8_BAR; PG8_SCHED;
;             PG8_LDB(B1, 1, 1); PG8_STAGE(PG8_SB(1, 0), b3, voffB);
;             PG8_BAR; PG8_WAIT_L(0); PG8_MMA(0, 1, At, B1); PG8_BAR;
;             PG8_LDA(At, 1, 1); PG8_STAGE(PG8_SA(1, 0), a3, voffA);
;             PG8_BAR; PG8_WAIT_L(0); PG8_MMA(1, 0, At, B0); PG8_BAR; PG8_SCHED;
	s_add_u32 s38, s54, 0x200000
	s_addc_u32 s39, s55, 0
	s_add_i32 s50, s50, s63
	v_lshl_add_u64 v[140:141], s[38:39], 0, v[0:1]
	s_mov_b32 m0, s50
	s_nop 0
	global_load_lds_dwordx4 v[140:141], off
	v_lshl_add_u64 v[140:141], s[38:39], 0, v[130:131]
	s_add_i32 m0, s50, 0x2000
	s_nop 0
	global_load_lds_dwordx4 v[140:141], off
	s_add_u32 s38, s56, 0x200000
	s_addc_u32 s39, s57, 0
	s_mov_b32 m0, s64
	v_lshl_add_u64 v[192:193], s[38:39], 0, v[0:1]
	global_load_lds_dwordx4 v[192:193], off
	v_lshl_add_u64 v[192:193], s[38:39], 0, v[130:131]
	s_mov_b32 m0, s65
	s_nop 0
	global_load_lds_dwordx4 v[192:193], off
	s_add_i32 s50, 0, 0x18000
	v_add_u32_e32 v152, s50, v137
	ds_read_b128 v[140:143], v152
	ds_read_b128 v[144:147], v152 offset:1024
	ds_read_b128 v[148:151], v152 offset:2048
	ds_read_b128 v[152:155], v152 offset:3072
	ds_read_b128 v[160:163], v139 offset:32768
	ds_read_b128 v[164:167], v139 offset:33792
	ds_read_b128 v[168:171], v139 offset:34816
	ds_read_b128 v[172:175], v139 offset:35840
	ds_read_b128 v[176:179], v139 offset:36864
	ds_read_b128 v[180:183], v139 offset:37888
	ds_read_b128 v[184:187], v139 offset:38912
	ds_read_b128 v[188:191], v139 offset:39936
	s_add_i32 s51, 0, 0x1c000
	v_add_u32_e32 v204, s51, v137
	ds_read_b128 v[192:195], v204
	ds_read_b128 v[196:199], v204 offset:1024
	ds_read_b128 v[200:203], v204 offset:2048
	ds_read_b128 v[204:207], v204 offset:3072
	s_waitcnt vmcnt(8)
	s_waitcnt lgkmcnt(4)
	s_barrier
	s_waitcnt lgkmcnt(0)
	s_setprio 1
	v_mfma_f32_16x16x32_bf16 v[126:129], v[140:143], v[160:163], v[126:129]
	v_mfma_f32_16x16x32_bf16 v[122:125], v[148:151], v[160:163], v[122:125]
	v_mfma_f32_16x16x32_bf16 v[118:121], v[140:143], v[168:171], v[118:121]
	v_mfma_f32_16x16x32_bf16 v[114:117], v[148:151], v[168:171], v[114:117]
	v_mfma_f32_16x16x32_bf16 v[106:109], v[140:143], v[176:179], v[106:109]
	v_mfma_f32_16x16x32_bf16 v[98:101], v[148:151], v[176:179], v[98:101]
	v_mfma_f32_16x16x32_bf16 v[90:93], v[140:143], v[184:187], v[90:93]
	v_mfma_f32_16x16x32_bf16 v[82:85], v[148:151], v[184:187], v[82:85]
	v_mfma_f32_16x16x32_bf16 v[126:129], v[144:147], v[164:167], v[126:129]
	v_mfma_f32_16x16x32_bf16 v[122:125], v[152:155], v[164:167], v[122:125]
	v_mfma_f32_16x16x32_bf16 v[118:121], v[144:147], v[172:175], v[118:121]
	v_mfma_f32_16x16x32_bf16 v[114:117], v[152:155], v[172:175], v[114:117]
	v_mfma_f32_16x16x32_bf16 v[106:109], v[144:147], v[180:183], v[106:109]
	v_mfma_f32_16x16x32_bf16 v[98:101], v[152:155], v[180:183], v[98:101]
	v_mfma_f32_16x16x32_bf16 v[90:93], v[144:147], v[188:191], v[90:93]
	v_mfma_f32_16x16x32_bf16 v[82:85], v[152:155], v[188:191], v[82:85]
	v_mfma_f32_16x16x32_bf16 v[110:113], v[192:195], v[160:163], v[110:113]
	v_mfma_f32_16x16x32_bf16 v[102:105], v[200:203], v[160:163], v[102:105]
	v_mfma_f32_16x16x32_bf16 v[94:97], v[192:195], v[168:171], v[94:97]
	v_mfma_f32_16x16x32_bf16 v[86:89], v[200:203], v[168:171], v[86:89]
	v_mfma_f32_16x16x32_bf16 v[78:81], v[192:195], v[176:179], v[78:81]
	v_mfma_f32_16x16x32_bf16 v[74:77], v[200:203], v[176:179], v[74:77]
	v_mfma_f32_16x16x32_bf16 v[70:73], v[192:195], v[184:187], v[70:73]
	v_mfma_f32_16x16x32_bf16 v[66:69], v[200:203], v[184:187], v[66:69]
	v_mfma_f32_16x16x32_bf16 v[110:113], v[196:199], v[164:167], v[110:113]
	v_mfma_f32_16x16x32_bf16 v[102:105], v[204:207], v[164:167], v[102:105]
	v_mfma_f32_16x16x32_bf16 v[94:97], v[196:199], v[172:175], v[94:97]
	v_mfma_f32_16x16x32_bf16 v[86:89], v[204:207], v[172:175], v[86:89]
	v_mfma_f32_16x16x32_bf16 v[78:81], v[196:199], v[180:183], v[78:81]
	v_mfma_f32_16x16x32_bf16 v[74:77], v[204:207], v[180:183], v[74:77]
	v_mfma_f32_16x16x32_bf16 v[70:73], v[196:199], v[188:191], v[70:73]
	v_mfma_f32_16x16x32_bf16 v[66:69], v[204:207], v[188:191], v[66:69]
	s_setprio 0
	s_barrier
	s_add_i32 s38, s50, s63
	v_lshl_add_u64 v[156:157], v[156:157], 0, s[36:37]
	s_mov_b32 m0, s38
	s_nop 0
	global_load_lds_dwordx4 v[156:157], off
	v_lshl_add_u64 v[156:157], v[210:211], 0, s[36:37]
	s_add_i32 m0, s38, 0x2000
	s_nop 0
	global_load_lds_dwordx4 v[156:157], off
	s_mov_b32 m0, s66
	v_lshl_add_u64 v[156:157], v[212:213], 0, s[36:37]
	global_load_lds_dwordx4 v[156:157], off
	v_lshl_add_u64 v[156:157], v[214:215], 0, s[36:37]
	s_mov_b32 m0, s67
	s_nop 0
	global_load_lds_dwordx4 v[156:157], off
	ds_read_b128 v[160:163], v139 offset:49152
	ds_read_b128 v[164:167], v139 offset:50176
	ds_read_b128 v[168:171], v139 offset:51200
	ds_read_b128 v[172:175], v139 offset:52224
	ds_read_b128 v[176:179], v139 offset:53248
	ds_read_b128 v[180:183], v139 offset:54272
	ds_read_b128 v[184:187], v139 offset:55296
	ds_read_b128 v[188:191], v139 offset:56320
	s_waitcnt vmcnt(6)
	s_waitcnt lgkmcnt(0)
	s_barrier
; #define PG8_STAGE(bufoff, gbase, voff) do { _Pragma("unroll") for (int _i = 0; _i < 2; ++_i) \
;         __builtin_amdgcn_global_load_lds((const unsigned*)((const char*)(gbase) + (voff)[_i]), (LAS unsigned*)(lds + (bufoff) + ldsw + _i * 8192), 16, 0, 0); } while (0)
; #define PG8_LDA(dst, b, h) do { _Pragma("unroll") for (int m = 0; m < 4; ++m) _Pragma("unroll") for (int k = 0; k < 2; ++k) dst[m][k] = *(const LAS bf16x8*)(lds + PG8_SA(b, h) + aoff + m * 2048 + k * 1024); } while (0)
; #define PG8_LDB(dst, b, h) do { _Pragma("unroll") for (int n = 0; n < 2; ++n) _Pragma("unroll") for (int k = 0; k < 2; ++k) dst[n][k] = *(const LAS bf16x8*)(lds + PG8_SB(b, h) + boff + n * 2048 + k * 1024); } while (0)
; #define PG8_MMA(ai, bj, At, Bt) do { __builtin_amdgcn_s_setprio(1); _Pragma("unroll") for (int m = 0; m < 4; ++m) _Pragma("unroll") for (int n = 0; n < 2; ++n) _Pragma("unroll") for (int k = 0; k < 2; ++k) \
;         acc[ai][bj][m][n] = __builtin_amdgcn_mfma_f32_16x16x32_bf16(Bt[n][k], At[m][k], acc[ai][bj][m][n], 0, 0, 0); __builtin_amdgcn_s_setprio(0); } while (0)
; #define PG8_BAR __builtin_amdgcn_s_barrier()
;     __device__ __forceinline__ void operator()(const f32x4 (&acc)[2][2][4][2], const Unit& u, int wr, int wc, int fr, int fq) const {
;         const int row0 = u.pm * BM + wr * 64 + fr, col0 = u.pn * BM + wc * 32 + 4 * fq;
;         float* base = part + (size_t)u.ks * Mp * ldc;
; #pragma unroll
;         for (int ai = 0; ai < 2; ++ai)
; #pragma unroll
;             for (int m = 0; m < 4; ++m) { float* rowp = base + (size_t)(row0 + ai * HALF + m * 16) * ldc + col0;
; #pragma unroll
;                 for (int bj = 0; bj < 2; ++bj)
; #pragma unroll
;                     for (int n = 0; n < 2; ++n) *(f32x4*)(rowp + bj * HALF + n * 16) = acc[ai][bj][m][n]; }
;     }
; template <class Epi, class Sched>
; __device__ __forceinline__ void gemm_phase(LAS unsigned char* lds, const Gemm g, const Sched& S, const Epi& E) {
;     ...
;             PG8_LDB(B1, 1, 1); PG8_STAGE(PG8_SB(1, 0), b3, voffB);
;             PG8_BAR; PG8_WAIT_L(0); PG8_MMA(0, 1, At, B1); PG8_BAR;
;             PG8_LDA(At, 1, 1); PG8_STAGE(PG8_SA(1, 0), a3, voffA);
;             PG8_BAR; PG8_WAIT_L(0); PG8_MMA(1, 0, At, B0); PG8_BAR; PG8_SCHED;
;             PG8_STAGE(PG8_SB(1, 1), b3 + hstep, voffB);
;             PG8_WAIT_V(6); PG8_BAR; PG8_MMA(1, 1, At, B1); PG8_BAR;
	s_setprio 1
	v_mfma_f32_16x16x32_bf16 v[62:65], v[140:143], v[160:163], v[62:65]
	v_mfma_f32_16x16x32_bf16 v[58:61], v[148:151], v[160:163], v[58:61]
	v_mfma_f32_16x16x32_bf16 v[54:57], v[140:143], v[168:171], v[54:57]
	v_mfma_f32_16x16x32_bf16 v[50:53], v[148:151], v[168:171], v[50:53]
	v_mfma_f32_16x16x32_bf16 v[38:41], v[140:143], v[176:179], v[38:41]
	v_mfma_f32_16x16x32_bf16 v[34:37], v[148:151], v[176:179], v[34:37]
	v_mfma_f32_16x16x32_bf16 v[22:25], v[140:143], v[184:187], v[22:25]
	v_mfma_f32_16x16x32_bf16 v[18:21], v[148:151], v[184:187], v[18:21]
	v_mfma_f32_16x16x32_bf16 v[62:65], v[144:147], v[164:167], v[62:65]
	v_mfma_f32_16x16x32_bf16 v[58:61], v[152:155], v[164:167], v[58:61]
	v_mfma_f32_16x16x32_bf16 v[54:57], v[144:147], v[172:175], v[54:57]
	v_mfma_f32_16x16x32_bf16 v[50:53], v[152:155], v[172:175], v[50:53]
	v_mfma_f32_16x16x32_bf16 v[38:41], v[144:147], v[180:183], v[38:41]
	v_mfma_f32_16x16x32_bf16 v[34:37], v[152:155], v[180:183], v[34:37]
	v_mfma_f32_16x16x32_bf16 v[22:25], v[144:147], v[188:191], v[22:25]
	v_mfma_f32_16x16x32_bf16 v[18:21], v[152:155], v[188:191], v[18:21]
	s_add_u32 s38, s54, 0x200080
	s_addc_u32 s39, s55, 0
	s_add_i32 s50, s51, s63
	v_lshl_add_u64 v[140:141], s[38:39], 0, v[0:1]
	s_mov_b32 m0, s50
	s_nop 0
	global_load_lds_dwordx4 v[140:141], off
	v_lshl_add_u64 v[140:141], s[38:39], 0, v[130:131]
	s_add_i32 m0, s50, 0x2000
	s_nop 0
	global_load_lds_dwordx4 v[140:141], off
	v_mfma_f32_16x16x32_bf16 v[46:49], v[192:195], v[160:163], v[46:49]
	v_mfma_f32_16x16x32_bf16 v[42:45], v[200:203], v[160:163], v[42:45]
	v_mfma_f32_16x16x32_bf16 v[30:33], v[192:195], v[168:171], v[30:33]
	v_mfma_f32_16x16x32_bf16 v[26:29], v[200:203], v[168:171], v[26:29]
	v_mfma_f32_16x16x32_bf16 v[14:17], v[192:195], v[176:179], v[14:17]
	v_mfma_f32_16x16x32_bf16 v[10:13], v[200:203], v[176:179], v[10:13]
	v_mfma_f32_16x16x32_bf16 v[6:9], v[192:195], v[184:187], v[6:9]
	v_mfma_f32_16x16x32_bf16 v[2:5], v[200:203], v[184:187], v[2:5]
	v_mfma_f32_16x16x32_bf16 v[46:49], v[196:199], v[164:167], v[46:49]
	v_mfma_f32_16x16x32_bf16 v[42:45], v[204:207], v[164:167], v[42:45]
	v_mfma_f32_16x16x32_bf16 v[30:33], v[196:199], v[172:175], v[30:33]
	v_mfma_f32_16x16x32_bf16 v[26:29], v[204:207], v[172:175], v[26:29]
	v_mfma_f32_16x16x32_bf16 v[14:17], v[196:199], v[180:183], v[14:17]
	v_mfma_f32_16x16x32_bf16 v[10:13], v[204:207], v[180:183], v[10:13]
	v_mfma_f32_16x16x32_bf16 v[6:9], v[196:199], v[188:191], v[6:9]
	v_mfma_f32_16x16x32_bf16 v[2:5], v[204:207], v[188:191], v[2:5]
	s_setprio 0
	s_add_i32 s71, s71, 2
	s_add_u32 s69, s69, 0x100
	s_addc_u32 s70, s70, 0
	s_cmp_gt_u32 s71, 29
	s_mov_b64 s[50:51], s[52:53]
	s_barrier
	s_cbranch_scc0 .LBB0_58
	s_ashr_i32 s11, s10, 31
	s_lshl_b64 s[10:11], s[10:11], 24
	v_lshl_or_b32 v140, s26, 8, v138
	s_add_u32 s10, s8, s10
	v_lshl_add_u32 v142, s24, 8, v136
	s_addc_u32 s11, s9, s11
	v_ashrrev_i32_e32 v141, 31, v140
	v_ashrrev_i32_e32 v143, 31, v142
	v_lshl_add_u64 v[140:141], v[140:141], 2, s[10:11]
	v_lshlrev_b64 v[144:145], 13, v[142:143]
	v_lshl_add_u64 v[144:145], v[140:141], 0, v[144:145]
	global_store_dwordx4 v[144:145], v[126:129], off
	global_store_dwordx4 v[144:145], v[122:125], off offset:64
	global_store_dwordx4 v[144:145], v[110:113], off offset:512
	global_store_dwordx4 v[144:145], v[102:105], off offset:576
	s_mov_b64 s[10:11], 0x100000
	s_mov_b32 s26, s40
	v_or_b32_e32 v102, 16, v142
	v_ashrrev_i32_e32 v103, 31, v102
	v_lshlrev_b64 v[102:103], 13, v[102:103]
	v_lshl_add_u64 v[102:103], v[140:141], 0, v[102:103]
	global_store_dwordx4 v[102:103], v[118:121], off
	global_store_dwordx4 v[102:103], v[114:117], off offset:64
	global_store_dwordx4 v[102:103], v[94:97], off offset:512
	global_store_dwordx4 v[102:103], v[86:89], off offset:576
	s_mov_b32 s24, s42
	s_mov_b64 s[52:53], s[48:49]
	v_or_b32_e32 v86, 32, v142
	v_ashrrev_i32_e32 v87, 31, v86
	v_lshlrev_b64 v[86:87], 13, v[86:87]
	v_lshl_add_u64 v[86:87], v[140:141], 0, v[86:87]
	global_store_dwordx4 v[86:87], v[106:109], off
	global_store_dwordx4 v[86:87], v[98:101], off offset:64
	global_store_dwordx4 v[86:87], v[78:81], off offset:512
	global_store_dwordx4 v[86:87], v[74:77], off offset:576
	s_mov_b64 s[50:51], s[46:47]
	s_nop 0
	v_or_b32_e32 v74, 48, v142
	v_ashrrev_i32_e32 v75, 31, v74
	v_lshlrev_b64 v[74:75], 13, v[74:75]
	v_lshl_add_u64 v[74:75], v[140:141], 0, v[74:75]
	global_store_dwordx4 v[74:75], v[90:93], off
	global_store_dwordx4 v[74:75], v[82:85], off offset:64
	global_store_dwordx4 v[74:75], v[70:73], off offset:512
	global_store_dwordx4 v[74:75], v[66:69], off offset:576
	s_nop 1
	v_add_co_u32_e32 v68, vcc, s93, v144
	v_lshl_add_u64 v[66:67], v[144:145], 0, s[10:11]
	s_nop 0
	v_addc_co_u32_e32 v69, vcc, 0, v145, vcc
	s_mov_b64 s[10:11], 0x120000
	global_store_dwordx4 v[68:69], v[62:65], off
	global_store_dwordx4 v[66:67], v[58:61], off offset:64
	global_store_dwordx4 v[66:67], v[46:49], off offset:512
	global_store_dwordx4 v[66:67], v[42:45], off offset:576
	s_nop 1
	v_lshl_add_u64 v[42:43], v[144:145], 0, s[10:11]
	s_mov_b32 s10, 0x120000
	v_add_co_u32_e32 v44, vcc, s10, v144
	s_mov_b64 s[10:11], 0x140000
	s_nop 0
	v_addc_co_u32_e32 v45, vcc, 0, v145, vcc
	global_store_dwordx4 v[44:45], v[54:57], off
	global_store_dwordx4 v[42:43], v[50:53], off offset:64
	global_store_dwordx4 v[42:43], v[30:33], off offset:512
	global_store_dwordx4 v[42:43], v[26:29], off offset:576
	s_nop 1
	v_lshl_add_u64 v[26:27], v[144:145], 0, s[10:11]
	s_mov_b32 s10, 0x140000
	v_add_co_u32_e32 v28, vcc, s10, v144
	s_mov_b64 s[10:11], 0x160000
	s_nop 0
	v_addc_co_u32_e32 v29, vcc, 0, v145, vcc
	global_store_dwordx4 v[28:29], v[38:41], off
	global_store_dwordx4 v[26:27], v[34:37], off offset:64
	global_store_dwordx4 v[26:27], v[14:17], off offset:512
	global_store_dwordx4 v[26:27], v[10:13], off offset:576
	s_nop 1
	v_add_co_u32_e32 v12, vcc, 0x160000, v144
	v_lshl_add_u64 v[10:11], v[144:145], 0, s[10:11]
	s_nop 0
	v_addc_co_u32_e32 v13, vcc, 0, v145, vcc
	s_and_b64 vcc, exec, s[44:45]
	s_mov_b32 s10, s28
	global_store_dwordx4 v[12:13], v[22:25], off
	global_store_dwordx4 v[10:11], v[18:21], off offset:64
	global_store_dwordx4 v[10:11], v[6:9], off offset:512
	global_store_dwordx4 v[10:11], v[2:5], off offset:576
	s_cbranch_vccz .LBB0_55
	s_waitcnt vmcnt(0)
	s_cmpk_gt_u32 s60, 0xff
	s_cbranch_scc1 .LBB0_62
	s_barrier

; #define PG8_STAGE(bufoff, gbase, voff) do { _Pragma("unroll") for (int _i = 0; _i < 2; ++_i) \
;         __builtin_amdgcn_global_load_lds((const unsigned*)((const char*)(gbase) + (voff)[_i]), (LAS unsigned*)(lds + (bufoff) + ldsw + _i * 8192), 16, 0, 0); } while (0)
; #define PG8_LDA(dst, b, h) do { _Pragma("unroll") for (int m = 0; m < 4; ++m) _Pragma("unroll") for (int k = 0; k < 2; ++k) dst[m][k] = *(const LAS bf16x8*)(lds + PG8_SA(b, h) + aoff + m * 2048 + k * 1024); } while (0)
; #define PG8_LDB(dst, b, h) do { _Pragma("unroll") for (int n = 0; n < 2; ++n) _Pragma("unroll") for (int k = 0; k < 2; ++k) dst[n][k] = *(const LAS bf16x8*)(lds + PG8_SB(b, h) + boff + n * 2048 + k * 1024); } while (0)
; #define PG8_MMA(ai, bj, At, Bt) do { __builtin_amdgcn_s_setprio(1); _Pragma("unroll") for (int m = 0; m < 4; ++m) _Pragma("unroll") for (int n = 0; n < 2; ++n) _Pragma("unroll") for (int k = 0; k < 2; ++k) \
;         acc[ai][bj][m][n] = __builtin_amdgcn_mfma_f32_16x16x32_bf16(Bt[n][k], At[m][k], acc[ai][bj][m][n], 0, 0, 0); __builtin_amdgcn_s_setprio(0); } while (0)
; #define PG8_WAIT_V(n) asm volatile("s_waitcnt vmcnt(" #n ")" ::: "memory")
; #define PG8_WAIT_L(n) asm volatile("s_waitcnt lgkmcnt(" #n ")" ::: "memory")
; #define PG8_BAR __builtin_amdgcn_s_barrier()
; template <class Epi, class Sched>
; __device__ __forceinline__ void gemm_phase(LAS unsigned char* lds, const Gemm g, const Sched& S, const Epi& E) {
;     ...
;             const bool last = (t == nt - 2);
;             const char* a1 = cA + (size_t)(t + 1) * kstep;
;             const char* a2 = last ? nA : cA + (size_t)(t + 2) * kstep; const char* b2 = last ? nB : cB + (size_t)(t + 2) * kstep;
;             const char* a3 = a2 + kstep; const char* b3 = b2 + kstep;
;             PG8_LDB(B0, 0, 0); PG8_SCHED; PG8_LDA(At, 0, 0); PG8_STAGE(PG8_SA(1, 1), a1 + hstep, voffA);
;             PG8_WAIT_L(8); PG8_BAR; PG8_WAIT_L(0); PG8_MMA(0, 0, At, B0); PG8_BAR; PG8_SCHED;
;             PG8_LDB(B1, 0, 1); PG8_STAGE(PG8_SB(0, 0), b2, voffB);
;             PG8_BAR; PG8_WAIT_L(0); PG8_MMA(0, 1, At, B1); PG8_BAR;
;             PG8_LDA(At, 0, 1); PG8_STAGE(PG8_SA(0, 0), a2, voffA);
;             PG8_BAR; PG8_WAIT_L(0); PG8_MMA(1, 0, At, B0); PG8_BAR; PG8_SCHED;
;             PG8_STAGE(PG8_SB(0, 1), b2 + hstep, voffB);
;             PG8_WAIT_V(6); PG8_BAR; PG8_MMA(1, 1, At, B1); PG8_BAR;
.LBB0_73:
	s_add_u32 s38, s46, 0xfff80080
	s_addc_u32 s39, s47, -1
	s_cmp_eq_u32 s73, 28
	s_cselect_b32 s51, s29, s39
	s_cselect_b32 s50, s69, s38
	s_cselect_b32 s49, s27, s72
	s_cselect_b32 s48, s70, s71
	v_lshl_add_u64 v[140:141], s[46:47], 0, v[138:139]
	s_add_i32 m0, s9, 0xc000
	s_nop 0
	global_load_lds_dwordx4 v[140:141], off
	v_lshl_add_u64 v[140:141], s[46:47], 0, v[136:137]
	s_add_i32 m0, s9, 0xe000
	s_nop 0
	global_load_lds_dwordx4 v[140:141], off
	s_add_i32 s74, 0, 0x10000
	v_add_u32_e32 v140, s74, v143
	ds_read_b128 v[146:149], v140
	ds_read_b128 v[150:153], v140 offset:1024
	ds_read_b128 v[154:157], v140 offset:2048
	ds_read_b128 v[160:163], v140 offset:3072
	ds_read_b128 v[164:167], v145
	ds_read_b128 v[168:171], v145 offset:1024
	ds_read_b128 v[172:175], v145 offset:2048
	ds_read_b128 v[176:179], v145 offset:3072
	ds_read_b128 v[180:183], v145 offset:4096
	ds_read_b128 v[184:187], v145 offset:5120
	ds_read_b128 v[188:191], v145 offset:6144
	ds_read_b128 v[192:195], v145 offset:7168
	s_add_i32 s75, 0, 0x14000
	v_add_u32_e32 v140, s75, v143
	ds_read_b128 v[196:199], v140
	ds_read_b128 v[200:203], v140 offset:1024
	ds_read_b128 v[204:207], v140 offset:2048
	ds_read_b128 v[210:213], v140 offset:3072
	s_waitcnt vmcnt(8)
	s_waitcnt lgkmcnt(4)
	s_barrier
	s_waitcnt lgkmcnt(0)
	s_setprio 1
	v_mfma_f32_16x16x32_bf16 v[126:129], v[146:149], v[164:167], v[126:129]
	v_mfma_f32_16x16x32_bf16 v[122:125], v[154:157], v[164:167], v[122:125]
	v_mfma_f32_16x16x32_bf16 v[110:113], v[146:149], v[172:175], v[110:113]
	v_mfma_f32_16x16x32_bf16 v[106:109], v[154:157], v[172:175], v[106:109]
	v_mfma_f32_16x16x32_bf16 v[94:97], v[146:149], v[180:183], v[94:97]
	v_mfma_f32_16x16x32_bf16 v[90:93], v[154:157], v[180:183], v[90:93]
	v_mfma_f32_16x16x32_bf16 v[78:81], v[146:149], v[188:191], v[78:81]
	v_mfma_f32_16x16x32_bf16 v[74:77], v[154:157], v[188:191], v[74:77]
	v_mfma_f32_16x16x32_bf16 v[126:129], v[150:153], v[168:171], v[126:129]
	v_mfma_f32_16x16x32_bf16 v[122:125], v[160:163], v[168:171], v[122:125]
	v_mfma_f32_16x16x32_bf16 v[110:113], v[150:153], v[176:179], v[110:113]
	v_mfma_f32_16x16x32_bf16 v[106:109], v[160:163], v[176:179], v[106:109]
	v_mfma_f32_16x16x32_bf16 v[94:97], v[150:153], v[184:187], v[94:97]
	v_mfma_f32_16x16x32_bf16 v[90:93], v[160:163], v[184:187], v[90:93]
	v_mfma_f32_16x16x32_bf16 v[78:81], v[150:153], v[192:195], v[78:81]
	v_mfma_f32_16x16x32_bf16 v[74:77], v[160:163], v[192:195], v[74:77]
	v_mfma_f32_16x16x32_bf16 v[118:121], v[196:199], v[164:167], v[118:121]
	v_mfma_f32_16x16x32_bf16 v[114:117], v[204:207], v[164:167], v[114:117]
	v_mfma_f32_16x16x32_bf16 v[102:105], v[196:199], v[172:175], v[102:105]
	v_mfma_f32_16x16x32_bf16 v[98:101], v[204:207], v[172:175], v[98:101]
	v_mfma_f32_16x16x32_bf16 v[86:89], v[196:199], v[180:183], v[86:89]
	v_mfma_f32_16x16x32_bf16 v[82:85], v[204:207], v[180:183], v[82:85]
	v_mfma_f32_16x16x32_bf16 v[70:73], v[196:199], v[188:191], v[70:73]
	v_mfma_f32_16x16x32_bf16 v[66:69], v[204:207], v[188:191], v[66:69]
	v_mfma_f32_16x16x32_bf16 v[118:121], v[200:203], v[168:171], v[118:121]
	v_mfma_f32_16x16x32_bf16 v[114:117], v[210:213], v[168:171], v[114:117]
	v_mfma_f32_16x16x32_bf16 v[102:105], v[200:203], v[176:179], v[102:105]
	v_mfma_f32_16x16x32_bf16 v[98:101], v[210:213], v[176:179], v[98:101]
	v_mfma_f32_16x16x32_bf16 v[86:89], v[200:203], v[184:187], v[86:89]
	v_mfma_f32_16x16x32_bf16 v[82:85], v[210:213], v[184:187], v[82:85]
	v_mfma_f32_16x16x32_bf16 v[70:73], v[200:203], v[192:195], v[70:73]
	v_mfma_f32_16x16x32_bf16 v[66:69], v[210:213], v[192:195], v[66:69]
	s_setprio 0
	s_barrier
	s_add_i32 s38, s74, s56
	v_lshl_add_u64 v[140:141], s[48:49], 0, v[0:1]
	s_mov_b32 m0, s38
	v_lshl_add_u64 v[214:215], s[48:49], 0, v[130:131]
	global_load_lds_dwordx4 v[140:141], off
	s_add_i32 m0, s38, 0x2000
	s_nop 0
	global_load_lds_dwordx4 v[214:215], off
	s_mov_b32 m0, s9
	v_lshl_add_u64 v[216:217], s[50:51], 0, v[134:135]
	global_load_lds_dwordx4 v[216:217], off
	v_lshl_add_u64 v[224:225], s[50:51], 0, v[132:133]
	s_mov_b32 m0, s60
	s_nop 0
	global_load_lds_dwordx4 v[224:225], off
	ds_read_b128 v[164:167], v145 offset:16384
	ds_read_b128 v[168:171], v145 offset:17408
	ds_read_b128 v[172:175], v145 offset:18432
	ds_read_b128 v[176:179], v145 offset:19456
	ds_read_b128 v[180:183], v145 offset:20480
	ds_read_b128 v[184:187], v145 offset:21504
	ds_read_b128 v[188:191], v145 offset:22528
	ds_read_b128 v[192:195], v145 offset:23552
	s_waitcnt vmcnt(6)
	s_waitcnt lgkmcnt(0)
	s_barrier
	s_setprio 1
	v_mfma_f32_16x16x32_bf16 v[62:65], v[146:149], v[164:167], v[62:65]
	v_mfma_f32_16x16x32_bf16 v[58:61], v[154:157], v[164:167], v[58:61]
	v_mfma_f32_16x16x32_bf16 v[46:49], v[146:149], v[172:175], v[46:49]
	v_mfma_f32_16x16x32_bf16 v[42:45], v[154:157], v[172:175], v[42:45]
	v_mfma_f32_16x16x32_bf16 v[30:33], v[146:149], v[180:183], v[30:33]
	v_mfma_f32_16x16x32_bf16 v[26:29], v[154:157], v[180:183], v[26:29]
	v_mfma_f32_16x16x32_bf16 v[14:17], v[146:149], v[188:191], v[14:17]
	v_mfma_f32_16x16x32_bf16 v[10:13], v[154:157], v[188:191], v[10:13]
	v_mfma_f32_16x16x32_bf16 v[62:65], v[150:153], v[168:171], v[62:65]
	v_mfma_f32_16x16x32_bf16 v[58:61], v[160:163], v[168:171], v[58:61]
	v_mfma_f32_16x16x32_bf16 v[46:49], v[150:153], v[176:179], v[46:49]
	v_mfma_f32_16x16x32_bf16 v[42:45], v[160:163], v[176:179], v[42:45]
	v_mfma_f32_16x16x32_bf16 v[30:33], v[150:153], v[184:187], v[30:33]
	v_mfma_f32_16x16x32_bf16 v[26:29], v[160:163], v[184:187], v[26:29]
	v_mfma_f32_16x16x32_bf16 v[14:17], v[150:153], v[192:195], v[14:17]
	v_mfma_f32_16x16x32_bf16 v[10:13], v[160:163], v[192:195], v[10:13]
	v_mfma_f32_16x16x32_bf16 v[54:57], v[196:199], v[164:167], v[54:57]
	v_mfma_f32_16x16x32_bf16 v[50:53], v[204:207], v[164:167], v[50:53]
	v_mfma_f32_16x16x32_bf16 v[38:41], v[196:199], v[172:175], v[38:41]
	v_mfma_f32_16x16x32_bf16 v[34:37], v[204:207], v[172:175], v[34:37]
	v_mfma_f32_16x16x32_bf16 v[22:25], v[196:199], v[180:183], v[22:25]
	v_mfma_f32_16x16x32_bf16 v[18:21], v[204:207], v[180:183], v[18:21]
	v_mfma_f32_16x16x32_bf16 v[6:9], v[196:199], v[188:191], v[6:9]
	v_mfma_f32_16x16x32_bf16 v[2:5], v[204:207], v[188:191], v[2:5]
	v_mfma_f32_16x16x32_bf16 v[54:57], v[200:203], v[168:171], v[54:57]
	v_mfma_f32_16x16x32_bf16 v[50:53], v[210:213], v[168:171], v[50:53]
	v_mfma_f32_16x16x32_bf16 v[38:41], v[200:203], v[176:179], v[38:41]
	v_mfma_f32_16x16x32_bf16 v[34:37], v[210:213], v[176:179], v[34:37]
	v_mfma_f32_16x16x32_bf16 v[22:25], v[200:203], v[184:187], v[22:25]
	v_mfma_f32_16x16x32_bf16 v[18:21], v[210:213], v[184:187], v[18:21]
	v_mfma_f32_16x16x32_bf16 v[6:9], v[200:203], v[192:195], v[6:9]
	v_mfma_f32_16x16x32_bf16 v[2:5], v[210:213], v[192:195], v[2:5]
	s_setprio 0
	s_barrier
; #define PG8_STAGE(bufoff, gbase, voff) do { _Pragma("unroll") for (int _i = 0; _i < 2; ++_i) \
;         __builtin_amdgcn_global_load_lds((const unsigned*)((const char*)(gbase) + (voff)[_i]), (LAS unsigned*)(lds + (bufoff) + ldsw + _i * 8192), 16, 0, 0); } while (0)
; #define PG8_LDA(dst, b, h) do { _Pragma("unroll") for (int m = 0; m < 4; ++m) _Pragma("unroll") for (int k = 0; k < 2; ++k) dst[m][k] = *(const LAS bf16x8*)(lds + PG8_SA(b, h) + aoff + m * 2048 + k * 1024); } while (0)
; #define PG8_LDB(dst, b, h) do { _Pragma("unroll") for (int n = 0; n < 2; ++n) _Pragma("unroll") for (int k = 0; k < 2; ++k) dst[n][k] = *(const LAS bf16x8*)(lds + PG8_SB(b, h) + boff + n * 2048 + k * 1024); } while (0)
; #define PG8_MMA(ai, bj, At, Bt) do { __builtin_amdgcn_s_setprio(1); _Pragma("unroll") for (int m = 0; m < 4; ++m) _Pragma("unroll") for (int n = 0; n < 2; ++n) _Pragma("unroll") for (int k = 0; k < 2; ++k) \
;         acc[ai][bj][m][n] = __builtin_amdgcn_mfma_f32_16x16x32_bf16(Bt[n][k], At[m][k], acc[ai][bj][m][n], 0, 0, 0); __builtin_amdgcn_s_setprio(0); } while (0)
; #define PG8_WAIT_V(n) asm volatile("s_waitcnt vmcnt(" #n ")" ::: "memory")
; #define PG8_WAIT_L(n) asm volatile("s_waitcnt lgkmcnt(" #n ")" ::: "memory")
; #define PG8_BAR __builtin_amdgcn_s_barrier()
; #define PG8_SCHED __builtin_amdgcn_sched_barrier(0)
; template <class Epi, class Sched>
; __device__ __forceinline__ void gemm_phase(LAS unsigned char* lds, const Gemm g, const Sched& S, const Epi& E) {
;     ...
;             PG8_STAGE(PG8_SB(0, 1), b2 + hstep, voffB);
;             PG8_WAIT_V(6); PG8_BAR; PG8_MMA(1, 1, At, B1); PG8_BAR;
;             PG8_LDB(B0, 1, 0); PG8_SCHED; PG8_LDA(At, 1, 0); PG8_STAGE(PG8_SA(0, 1), a2 + hstep, voffA);
;             PG8_WAIT_L(8); PG8_BAR; PG8_WAIT_L(0); PG8_MMA(0, 0, At, B0); PG8_BAR; PG8_SCHED;
;             PG8_LDB(B1, 1, 1); PG8_STAGE(PG8_SB(1, 0), b3, voffB);
;             PG8_BAR; PG8_WAIT_L(0); PG8_MMA(0, 1, At, B1); PG8_BAR;
;             PG8_LDA(At, 1, 1); PG8_STAGE(PG8_SA(1, 0), a3, voffA);
;             PG8_BAR; PG8_WAIT_L(0); PG8_MMA(1, 0, At, B0); PG8_BAR; PG8_SCHED;
	s_add_u32 s38, s48, 0x80000
	s_addc_u32 s39, s49, 0
	s_add_i32 s74, s75, s56
	v_lshl_add_u64 v[146:147], s[38:39], 0, v[0:1]
	s_mov_b32 m0, s74
	s_nop 0
	global_load_lds_dwordx4 v[146:147], off
	v_lshl_add_u64 v[146:147], s[38:39], 0, v[130:131]
	s_add_i32 m0, s74, 0x2000
	s_nop 0
	global_load_lds_dwordx4 v[146:147], off
	s_add_u32 s38, s50, 0x80000
	s_addc_u32 s39, s51, 0
	s_mov_b32 m0, s61
	v_lshl_add_u64 v[196:197], s[38:39], 0, v[134:135]
	global_load_lds_dwordx4 v[196:197], off
	v_lshl_add_u64 v[196:197], s[38:39], 0, v[132:133]
	s_mov_b32 m0, s62
	s_nop 0
	global_load_lds_dwordx4 v[196:197], off
	s_add_i32 s74, 0, 0x18000
	v_add_u32_e32 v160, s74, v143
	ds_read_b128 v[146:149], v160
	ds_read_b128 v[150:153], v160 offset:1024
	ds_read_b128 v[154:157], v160 offset:2048
	ds_read_b128 v[160:163], v160 offset:3072
	ds_read_b128 v[164:167], v145 offset:32768
	ds_read_b128 v[168:171], v145 offset:33792
	ds_read_b128 v[172:175], v145 offset:34816
	ds_read_b128 v[176:179], v145 offset:35840
	ds_read_b128 v[180:183], v145 offset:36864
	ds_read_b128 v[184:187], v145 offset:37888
	ds_read_b128 v[188:191], v145 offset:38912
	ds_read_b128 v[192:195], v145 offset:39936
	s_add_i32 s50, 0, 0x1c000
	v_add_u32_e32 v210, s50, v143
	ds_read_b128 v[196:199], v210
	ds_read_b128 v[200:203], v210 offset:1024
	ds_read_b128 v[204:207], v210 offset:2048
	ds_read_b128 v[210:213], v210 offset:3072
	s_waitcnt vmcnt(8)
	s_waitcnt lgkmcnt(4)
	s_barrier
	s_waitcnt lgkmcnt(0)
	s_setprio 1
	v_mfma_f32_16x16x32_bf16 v[126:129], v[146:149], v[164:167], v[126:129]
	v_mfma_f32_16x16x32_bf16 v[122:125], v[154:157], v[164:167], v[122:125]
	v_mfma_f32_16x16x32_bf16 v[110:113], v[146:149], v[172:175], v[110:113]
	v_mfma_f32_16x16x32_bf16 v[106:109], v[154:157], v[172:175], v[106:109]
	v_mfma_f32_16x16x32_bf16 v[94:97], v[146:149], v[180:183], v[94:97]
	v_mfma_f32_16x16x32_bf16 v[90:93], v[154:157], v[180:183], v[90:93]
	v_mfma_f32_16x16x32_bf16 v[78:81], v[146:149], v[188:191], v[78:81]
	v_mfma_f32_16x16x32_bf16 v[74:77], v[154:157], v[188:191], v[74:77]
	v_mfma_f32_16x16x32_bf16 v[126:129], v[150:153], v[168:171], v[126:129]
	v_mfma_f32_16x16x32_bf16 v[122:125], v[160:163], v[168:171], v[122:125]
	v_mfma_f32_16x16x32_bf16 v[110:113], v[150:153], v[176:179], v[110:113]
	v_mfma_f32_16x16x32_bf16 v[106:109], v[160:163], v[176:179], v[106:109]
	v_mfma_f32_16x16x32_bf16 v[94:97], v[150:153], v[184:187], v[94:97]
	v_mfma_f32_16x16x32_bf16 v[90:93], v[160:163], v[184:187], v[90:93]
	v_mfma_f32_16x16x32_bf16 v[78:81], v[150:153], v[192:195], v[78:81]
	v_mfma_f32_16x16x32_bf16 v[74:77], v[160:163], v[192:195], v[74:77]
	v_mfma_f32_16x16x32_bf16 v[118:121], v[196:199], v[164:167], v[118:121]
	v_mfma_f32_16x16x32_bf16 v[114:117], v[204:207], v[164:167], v[114:117]
	v_mfma_f32_16x16x32_bf16 v[102:105], v[196:199], v[172:175], v[102:105]
	v_mfma_f32_16x16x32_bf16 v[98:101], v[204:207], v[172:175], v[98:101]
	v_mfma_f32_16x16x32_bf16 v[86:89], v[196:199], v[180:183], v[86:89]
	v_mfma_f32_16x16x32_bf16 v[82:85], v[204:207], v[180:183], v[82:85]
	v_mfma_f32_16x16x32_bf16 v[70:73], v[196:199], v[188:191], v[70:73]
	v_mfma_f32_16x16x32_bf16 v[66:69], v[204:207], v[188:191], v[66:69]
	v_mfma_f32_16x16x32_bf16 v[118:121], v[200:203], v[168:171], v[118:121]
	v_mfma_f32_16x16x32_bf16 v[114:117], v[210:213], v[168:171], v[114:117]
	v_mfma_f32_16x16x32_bf16 v[102:105], v[200:203], v[176:179], v[102:105]
	v_mfma_f32_16x16x32_bf16 v[98:101], v[210:213], v[176:179], v[98:101]
	v_mfma_f32_16x16x32_bf16 v[86:89], v[200:203], v[184:187], v[86:89]
	v_mfma_f32_16x16x32_bf16 v[82:85], v[210:213], v[184:187], v[82:85]
	v_mfma_f32_16x16x32_bf16 v[70:73], v[200:203], v[192:195], v[70:73]
	v_mfma_f32_16x16x32_bf16 v[66:69], v[210:213], v[192:195], v[66:69]
	s_setprio 0
	s_barrier
	s_add_i32 s38, s74, s56
	v_lshl_add_u64 v[140:141], v[140:141], 0, s[36:37]
	s_mov_b32 m0, s38
	s_nop 0
	global_load_lds_dwordx4 v[140:141], off
	v_lshl_add_u64 v[140:141], v[214:215], 0, s[36:37]
	s_add_i32 m0, s38, 0x2000
	s_nop 0
	global_load_lds_dwordx4 v[140:141], off
	s_mov_b32 m0, s64
	v_lshl_add_u64 v[140:141], v[216:217], 0, s[36:37]
	global_load_lds_dwordx4 v[140:141], off
	v_lshl_add_u64 v[140:141], v[224:225], 0, s[36:37]
	s_mov_b32 m0, s65
	s_nop 0
	global_load_lds_dwordx4 v[140:141], off
	ds_read_b128 v[164:167], v145 offset:49152
	ds_read_b128 v[168:171], v145 offset:50176
	ds_read_b128 v[172:175], v145 offset:51200
	ds_read_b128 v[176:179], v145 offset:52224
	ds_read_b128 v[180:183], v145 offset:53248
	ds_read_b128 v[184:187], v145 offset:54272
	ds_read_b128 v[188:191], v145 offset:55296
	ds_read_b128 v[192:195], v145 offset:56320
	s_waitcnt vmcnt(6)
	s_waitcnt lgkmcnt(0)
	s_barrier
; __device__ __forceinline__ unsigned cvt_pk_bf16(float lo, float hi) { unsigned r; asm("v_cvt_pk_bf16_f32 %0, %1, %2" : "=v"(r) : "v"(lo), "v"(hi)); return r; }
; #define PG8_STAGE(bufoff, gbase, voff) do { _Pragma("unroll") for (int _i = 0; _i < 2; ++_i) \
;         __builtin_amdgcn_global_load_lds((const unsigned*)((const char*)(gbase) + (voff)[_i]), (LAS unsigned*)(lds + (bufoff) + ldsw + _i * 8192), 16, 0, 0); } while (0)
; #define PG8_LDA(dst, b, h) do { _Pragma("unroll") for (int m = 0; m < 4; ++m) _Pragma("unroll") for (int k = 0; k < 2; ++k) dst[m][k] = *(const LAS bf16x8*)(lds + PG8_SA(b, h) + aoff + m * 2048 + k * 1024); } while (0)
; #define PG8_WAIT_V(n) asm volatile("s_waitcnt vmcnt(" #n ")" ::: "memory")
; #define PG8_BAR __builtin_amdgcn_s_barrier()
;     __device__ __forceinline__ void operator()(const f32x4 (&acc)[2][2][4][2], const Unit& u, int wr, int wc, int fr, int fq) const {
;         const int row0 = u.pm * BM + wr * 64 + fr, col0 = u.pn * BM + wc * 32 + 8 * fq;
; #pragma unroll
;         for (int ai = 0; ai < 2; ++ai)
; #pragma unroll
;             for (int m = 0; m < 4; ++m) { bf16_t* rowp = O + (size_t)(row0 + ai * HALF + m * 16) * ldc + col0;
; #pragma unroll
;                 for (int bj = 0; bj < 2; ++bj) { f32x4 v0 = acc[ai][bj][m][0], v1 = acc[ai][bj][m][1];
;                     if (ACT == 1) {
; #pragma unroll
;                         for (int j = 0; j < 4; ++j) { float a = fmaxf(v0[j], 0.f), b = fmaxf(v1[j], 0.f); v0[j] = a * a; v1[j] = b * b; } }
;                     u32x4 w; w.x = cvt_pk_bf16(v0[0], v0[1]); w.y = cvt_pk_bf16(v0[2], v0[3]); w.z = cvt_pk_bf16(v1[0], v1[1]); w.w = cvt_pk_bf16(v1[2], v1[3]);
;                     if (ACT == 1) __builtin_nontemporal_store(w, (u32x4*)(rowp + bj * HALF));
;                     else *(u32x4*)(rowp + bj * HALF) = w; } }
; template <class Epi, class Sched>
; __device__ __forceinline__ void gemm_phase(LAS unsigned char* lds, const Gemm g, const Sched& S, const Epi& E) {
;     ...
;             PG8_LDB(B1, 1, 1); PG8_STAGE(PG8_SB(1, 0), b3, voffB);
;             PG8_BAR; PG8_WAIT_L(0); PG8_MMA(0, 1, At, B1); PG8_BAR;
;             PG8_LDA(At, 1, 1); PG8_STAGE(PG8_SA(1, 0), a3, voffA);
;             PG8_BAR; PG8_WAIT_L(0); PG8_MMA(1, 0, At, B0); PG8_BAR; PG8_SCHED;
;             PG8_STAGE(PG8_SB(1, 1), b3 + hstep, voffB);
;             PG8_WAIT_V(6); PG8_BAR; PG8_MMA(1, 1, At, B1); PG8_BAR;
	s_setprio 1
	v_mfma_f32_16x16x32_bf16 v[62:65], v[146:149], v[164:167], v[62:65]
	v_mfma_f32_16x16x32_bf16 v[58:61], v[154:157], v[164:167], v[58:61]
	v_mfma_f32_16x16x32_bf16 v[46:49], v[146:149], v[172:175], v[46:49]
	v_mfma_f32_16x16x32_bf16 v[42:45], v[154:157], v[172:175], v[42:45]
	v_mfma_f32_16x16x32_bf16 v[30:33], v[146:149], v[180:183], v[30:33]
	v_mfma_f32_16x16x32_bf16 v[26:29], v[154:157], v[180:183], v[26:29]
	v_mfma_f32_16x16x32_bf16 v[14:17], v[146:149], v[188:191], v[14:17]
	v_mfma_f32_16x16x32_bf16 v[10:13], v[154:157], v[188:191], v[10:13]
	v_mfma_f32_16x16x32_bf16 v[62:65], v[150:153], v[168:171], v[62:65]
	v_mfma_f32_16x16x32_bf16 v[58:61], v[160:163], v[168:171], v[58:61]
	v_mfma_f32_16x16x32_bf16 v[46:49], v[150:153], v[176:179], v[46:49]
	v_mfma_f32_16x16x32_bf16 v[42:45], v[160:163], v[176:179], v[42:45]
	v_mfma_f32_16x16x32_bf16 v[30:33], v[150:153], v[184:187], v[30:33]
	v_mfma_f32_16x16x32_bf16 v[26:29], v[160:163], v[184:187], v[26:29]
	v_mfma_f32_16x16x32_bf16 v[14:17], v[150:153], v[192:195], v[14:17]
	v_mfma_f32_16x16x32_bf16 v[10:13], v[160:163], v[192:195], v[10:13]
	s_add_u32 s38, s48, 0x80080
	s_addc_u32 s39, s49, 0
	s_add_i32 s48, s50, s56
	v_lshl_add_u64 v[140:141], s[38:39], 0, v[0:1]
	s_mov_b32 m0, s48
	s_nop 0
	global_load_lds_dwordx4 v[140:141], off
	v_lshl_add_u64 v[140:141], s[38:39], 0, v[130:131]
	s_add_i32 m0, s48, 0x2000
	s_nop 0
	global_load_lds_dwordx4 v[140:141], off
	v_mfma_f32_16x16x32_bf16 v[54:57], v[196:199], v[164:167], v[54:57]
	v_mfma_f32_16x16x32_bf16 v[50:53], v[204:207], v[164:167], v[50:53]
	v_mfma_f32_16x16x32_bf16 v[38:41], v[196:199], v[172:175], v[38:41]
	v_mfma_f32_16x16x32_bf16 v[34:37], v[204:207], v[172:175], v[34:37]
	v_mfma_f32_16x16x32_bf16 v[22:25], v[196:199], v[180:183], v[22:25]
	v_mfma_f32_16x16x32_bf16 v[18:21], v[204:207], v[180:183], v[18:21]
	v_mfma_f32_16x16x32_bf16 v[6:9], v[196:199], v[188:191], v[6:9]
	v_mfma_f32_16x16x32_bf16 v[2:5], v[204:207], v[188:191], v[2:5]
	v_mfma_f32_16x16x32_bf16 v[54:57], v[200:203], v[168:171], v[54:57]
	v_mfma_f32_16x16x32_bf16 v[50:53], v[210:213], v[168:171], v[50:53]
	v_mfma_f32_16x16x32_bf16 v[38:41], v[200:203], v[176:179], v[38:41]
	v_mfma_f32_16x16x32_bf16 v[34:37], v[210:213], v[176:179], v[34:37]
	v_mfma_f32_16x16x32_bf16 v[22:25], v[200:203], v[184:187], v[22:25]
	v_mfma_f32_16x16x32_bf16 v[18:21], v[210:213], v[184:187], v[18:21]
	v_mfma_f32_16x16x32_bf16 v[6:9], v[200:203], v[192:195], v[6:9]
	v_mfma_f32_16x16x32_bf16 v[2:5], v[210:213], v[192:195], v[2:5]
	s_setprio 0
	s_add_i32 s73, s73, 2
	s_add_u32 s71, s71, 0x100
	s_addc_u32 s72, s72, 0
	s_add_u32 s46, s46, 0x100
	s_addc_u32 s47, s47, 0
	s_cmp_gt_u32 s73, 29
	s_barrier
	s_cbranch_scc0 .LBB0_73
	v_lshl_add_u32 v146, s8, 8, v142
	v_max_f32_e32 v122, v122, v122
	v_ashrrev_i32_e32 v147, 31, v146
	v_max_f32_e32 v122, 0, v122
	v_max_f32_e32 v123, v123, v123
	v_max_f32_e32 v124, v124, v124
	v_lshl_or_b32 v140, s68, 8, v144
	v_lshlrev_b64 v[148:149], 14, v[146:147]
	v_mul_f32_e32 v147, v122, v122
	v_max_f32_e32 v122, v127, v127
	v_max_f32_e32 v123, 0, v123
	v_max_f32_e32 v124, 0, v124
	v_ashrrev_i32_e32 v141, 31, v140
	v_max_f32_e32 v126, v126, v126
	v_max_f32_e32 v122, 0, v122
	v_mul_f32_e32 v127, v123, v123
	v_max_f32_e32 v123, v128, v128
	v_mul_f32_e32 v128, v124, v124
	v_max_f32_e32 v124, v129, v129
	v_max_f32_e32 v125, v125, v125
	v_lshl_add_u64 v[148:149], s[24:25], 0, v[148:149]
	v_lshlrev_b64 v[150:151], 1, v[140:141]
	v_max_f32_e32 v126, 0, v126
	v_mul_f32_e32 v122, v122, v122
	v_max_f32_e32 v123, 0, v123
	v_max_f32_e32 v124, 0, v124
	v_max_f32_e32 v125, 0, v125
	v_max_f32_e32 v114, v114, v114
	v_lshl_add_u64 v[140:141], v[148:149], 0, v[150:151]
	v_mul_f32_e32 v126, v126, v126
	v_mul_f32_e32 v123, v123, v123
	v_mul_f32_e32 v124, v124, v124
	v_mul_f32_e32 v125, v125, v125
	v_cvt_pk_bf16_f32 v122, v126, v122
	v_max_f32_e32 v114, 0, v114
	v_max_f32_e32 v115, v115, v115
	v_max_f32_e32 v116, v116, v116
	v_cvt_pk_bf16_f32 v123, v123, v124
	v_cvt_pk_bf16_f32 v124, v147, v127
	v_cvt_pk_bf16_f32 v125, v128, v125
	global_store_dwordx4 v[140:141], v[122:125], off nt
	v_max_f32_e32 v115, 0, v115
	v_max_f32_e32 v116, 0, v116
	v_mul_f32_e32 v122, v114, v114
	v_max_f32_e32 v114, v119, v119
	v_max_f32_e32 v118, v118, v118
	v_max_f32_e32 v114, 0, v114
	v_mul_f32_e32 v119, v115, v115
	v_max_f32_e32 v115, v120, v120
	v_mul_f32_e32 v120, v116, v116
	v_max_f32_e32 v116, v121, v121
	v_max_f32_e32 v117, v117, v117
	v_max_f32_e32 v118, 0, v118
	v_mul_f32_e32 v114, v114, v114
	v_max_f32_e32 v115, 0, v115
	v_max_f32_e32 v116, 0, v116
	v_max_f32_e32 v117, 0, v117
	v_mul_f32_e32 v118, v118, v118
	v_mul_f32_e32 v115, v115, v115
	v_mul_f32_e32 v116, v116, v116
	v_mul_f32_e32 v117, v117, v117
	v_cvt_pk_bf16_f32 v114, v118, v114
	v_max_f32_e32 v106, v106, v106
	v_cvt_pk_bf16_f32 v115, v115, v116
	v_cvt_pk_bf16_f32 v116, v122, v119
	v_cvt_pk_bf16_f32 v117, v120, v117
	global_store_dwordx4 v[140:141], v[114:117], off offset:256 nt
	v_max_f32_e32 v106, 0, v106
	v_max_f32_e32 v107, v107, v107
	v_or_b32_e32 v114, 16, v146
	v_max_f32_e32 v108, v108, v108
	v_ashrrev_i32_e32 v115, 31, v114
	v_mul_f32_e32 v116, v106, v106
	v_max_f32_e32 v106, v111, v111
	v_max_f32_e32 v107, 0, v107
	v_max_f32_e32 v108, 0, v108
	v_lshlrev_b64 v[114:115], 14, v[114:115]
	v_max_f32_e32 v110, v110, v110
	v_max_f32_e32 v106, 0, v106
	v_mul_f32_e32 v111, v107, v107
	v_max_f32_e32 v107, v112, v112
	v_mul_f32_e32 v112, v108, v108
	v_max_f32_e32 v108, v113, v113
	v_max_f32_e32 v109, v109, v109
	v_lshl_add_u64 v[114:115], s[24:25], 0, v[114:115]
	v_max_f32_e32 v110, 0, v110
	v_mul_f32_e32 v106, v106, v106
; __device__ __forceinline__ unsigned cvt_pk_bf16(float lo, float hi) { unsigned r; asm("v_cvt_pk_bf16_f32 %0, %1, %2" : "=v"(r) : "v"(lo), "v"(hi)); return r; }
;     __device__ __forceinline__ void operator()(const f32x4 (&acc)[2][2][4][2], const Unit& u, int wr, int wc, int fr, int fq) const {
;     ...
;             for (int m = 0; m < 4; ++m) { bf16_t* rowp = O + (size_t)(row0 + ai * HALF + m * 16) * ldc + col0;
; #pragma unroll
;                 for (int bj = 0; bj < 2; ++bj) { f32x4 v0 = acc[ai][bj][m][0], v1 = acc[ai][bj][m][1];
;                     if (ACT == 1) {
; #pragma unroll
;                         for (int j = 0; j < 4; ++j) { float a = fmaxf(v0[j], 0.f), b = fmaxf(v1[j], 0.f); v0[j] = a * a; v1[j] = b * b; } }
;                     u32x4 w; w.x = cvt_pk_bf16(v0[0], v0[1]); w.y = cvt_pk_bf16(v0[2], v0[3]); w.z = cvt_pk_bf16(v1[0], v1[1]); w.w = cvt_pk_bf16(v1[2], v1[3]);
;                     if (ACT == 1) __builtin_nontemporal_store(w, (u32x4*)(rowp + bj * HALF));
;                     else *(u32x4*)(rowp + bj * HALF) = w; } }
	v_max_f32_e32 v107, 0, v107
	v_max_f32_e32 v108, 0, v108
	v_max_f32_e32 v109, 0, v109
	v_max_f32_e32 v98, v98, v98
	v_lshl_add_u64 v[114:115], v[114:115], 0, v[150:151]
	v_mul_f32_e32 v110, v110, v110
	v_mul_f32_e32 v107, v107, v107
	v_mul_f32_e32 v108, v108, v108
	v_mul_f32_e32 v109, v109, v109
	v_cvt_pk_bf16_f32 v106, v110, v106
	v_max_f32_e32 v98, 0, v98
	v_max_f32_e32 v99, v99, v99
	v_max_f32_e32 v100, v100, v100
	v_cvt_pk_bf16_f32 v107, v107, v108
	v_cvt_pk_bf16_f32 v108, v116, v111
	v_cvt_pk_bf16_f32 v109, v112, v109
	global_store_dwordx4 v[114:115], v[106:109], off nt
	v_max_f32_e32 v99, 0, v99
	v_max_f32_e32 v100, 0, v100
	v_mul_f32_e32 v106, v98, v98
	v_max_f32_e32 v98, v103, v103
	v_max_f32_e32 v102, v102, v102
	v_max_f32_e32 v98, 0, v98
	v_mul_f32_e32 v103, v99, v99
	v_max_f32_e32 v99, v104, v104
	v_mul_f32_e32 v104, v100, v100
	v_max_f32_e32 v100, v105, v105
	v_max_f32_e32 v101, v101, v101
	v_max_f32_e32 v102, 0, v102
	v_mul_f32_e32 v98, v98, v98
	v_max_f32_e32 v99, 0, v99
	v_max_f32_e32 v100, 0, v100
	v_max_f32_e32 v101, 0, v101
	v_mul_f32_e32 v102, v102, v102
	v_mul_f32_e32 v99, v99, v99
	v_mul_f32_e32 v100, v100, v100
	v_mul_f32_e32 v101, v101, v101
	v_cvt_pk_bf16_f32 v98, v102, v98
	v_max_f32_e32 v90, v90, v90
	v_cvt_pk_bf16_f32 v99, v99, v100
	v_cvt_pk_bf16_f32 v100, v106, v103
	v_cvt_pk_bf16_f32 v101, v104, v101
	global_store_dwordx4 v[114:115], v[98:101], off offset:256 nt
	v_max_f32_e32 v90, 0, v90
	v_max_f32_e32 v91, v91, v91
	v_or_b32_e32 v98, 32, v146
	v_max_f32_e32 v92, v92, v92
	v_ashrrev_i32_e32 v99, 31, v98
	v_mul_f32_e32 v100, v90, v90
	v_max_f32_e32 v90, v95, v95
	v_max_f32_e32 v91, 0, v91
	v_max_f32_e32 v92, 0, v92
	v_lshlrev_b64 v[98:99], 14, v[98:99]
	v_max_f32_e32 v94, v94, v94
	v_max_f32_e32 v90, 0, v90
	v_mul_f32_e32 v95, v91, v91
	v_max_f32_e32 v91, v96, v96
	v_mul_f32_e32 v96, v92, v92
	v_max_f32_e32 v92, v97, v97
	v_max_f32_e32 v93, v93, v93
	v_lshl_add_u64 v[98:99], s[24:25], 0, v[98:99]
	v_max_f32_e32 v94, 0, v94
	v_mul_f32_e32 v90, v90, v90
	v_max_f32_e32 v91, 0, v91
	v_max_f32_e32 v92, 0, v92
	v_max_f32_e32 v93, 0, v93
	v_max_f32_e32 v82, v82, v82
	v_lshl_add_u64 v[98:99], v[98:99], 0, v[150:151]
	v_mul_f32_e32 v94, v94, v94
	v_mul_f32_e32 v91, v91, v91
	v_mul_f32_e32 v92, v92, v92
	v_mul_f32_e32 v93, v93, v93
	v_cvt_pk_bf16_f32 v90, v94, v90
	v_max_f32_e32 v82, 0, v82
	v_max_f32_e32 v83, v83, v83
	v_max_f32_e32 v84, v84, v84
	v_cvt_pk_bf16_f32 v91, v91, v92
	v_cvt_pk_bf16_f32 v92, v100, v95
	v_cvt_pk_bf16_f32 v93, v96, v93
	global_store_dwordx4 v[98:99], v[90:93], off nt
	v_max_f32_e32 v83, 0, v83
	v_max_f32_e32 v84, 0, v84
	v_mul_f32_e32 v90, v82, v82
	v_max_f32_e32 v82, v87, v87
	v_max_f32_e32 v86, v86, v86
	v_max_f32_e32 v82, 0, v82
	v_mul_f32_e32 v87, v83, v83
	v_max_f32_e32 v83, v88, v88
	v_mul_f32_e32 v88, v84, v84
	v_max_f32_e32 v84, v89, v89
	v_max_f32_e32 v85, v85, v85
	v_max_f32_e32 v86, 0, v86
	v_mul_f32_e32 v82, v82, v82
	v_max_f32_e32 v83, 0, v83
	v_max_f32_e32 v84, 0, v84
	v_max_f32_e32 v85, 0, v85
	v_mul_f32_e32 v86, v86, v86
	v_mul_f32_e32 v83, v83, v83
	v_mul_f32_e32 v84, v84, v84
	v_mul_f32_e32 v85, v85, v85
	v_cvt_pk_bf16_f32 v82, v86, v82
	v_max_f32_e32 v74, v74, v74
	v_cvt_pk_bf16_f32 v83, v83, v84
	v_cvt_pk_bf16_f32 v84, v90, v87
	v_cvt_pk_bf16_f32 v85, v88, v85
	global_store_dwordx4 v[98:99], v[82:85], off offset:256 nt
	v_max_f32_e32 v74, 0, v74
	v_max_f32_e32 v75, v75, v75
	v_or_b32_e32 v82, 48, v146
	v_max_f32_e32 v76, v76, v76
	v_ashrrev_i32_e32 v83, 31, v82
	v_mul_f32_e32 v84, v74, v74
	v_max_f32_e32 v74, v79, v79
	v_max_f32_e32 v75, 0, v75
	v_max_f32_e32 v76, 0, v76
	v_lshlrev_b64 v[82:83], 14, v[82:83]
	v_max_f32_e32 v78, v78, v78
	v_max_f32_e32 v74, 0, v74
	v_mul_f32_e32 v79, v75, v75
	v_max_f32_e32 v75, v80, v80
	v_mul_f32_e32 v80, v76, v76
	v_max_f32_e32 v76, v81, v81
	v_max_f32_e32 v77, v77, v77
	v_lshl_add_u64 v[82:83], s[24:25], 0, v[82:83]
	v_max_f32_e32 v78, 0, v78
	v_mul_f32_e32 v74, v74, v74
	v_max_f32_e32 v75, 0, v75
	v_max_f32_e32 v76, 0, v76
	v_max_f32_e32 v77, 0, v77
	v_max_f32_e32 v66, v66, v66
	v_max_f32_e32 v67, v67, v67
	v_max_f32_e32 v68, v68, v68
	v_lshl_add_u64 v[82:83], v[82:83], 0, v[150:151]
	v_mul_f32_e32 v78, v78, v78
	v_mul_f32_e32 v75, v75, v75
	v_mul_f32_e32 v76, v76, v76
	v_mul_f32_e32 v77, v77, v77
	v_cvt_pk_bf16_f32 v74, v78, v74
	v_max_f32_e32 v66, 0, v66
	v_max_f32_e32 v67, 0, v67
	v_max_f32_e32 v68, 0, v68
	v_cvt_pk_bf16_f32 v75, v75, v76
	v_cvt_pk_bf16_f32 v76, v84, v79
	v_cvt_pk_bf16_f32 v77, v80, v77
	global_store_dwordx4 v[82:83], v[74:77], off nt
	v_max_f32_e32 v69, v69, v69
	v_max_f32_e32 v70, v70, v70
	v_mul_f32_e32 v74, v66, v66
	v_max_f32_e32 v66, v71, v71
	v_mul_f32_e32 v71, v67, v67
	v_max_f32_e32 v67, v72, v72
	v_mul_f32_e32 v72, v68, v68
	v_max_f32_e32 v68, v73, v73
	v_max_f32_e32 v67, 0, v67
	v_max_f32_e32 v68, 0, v68
	v_max_f32_e32 v66, 0, v66
	v_mul_f32_e32 v67, v67, v67
	v_max_f32_e32 v69, 0, v69
	v_mul_f32_e32 v68, v68, v68
	v_max_f32_e32 v58, v58, v58
	v_max_f32_e32 v70, 0, v70
	v_mul_f32_e32 v66, v66, v66
	v_mul_f32_e32 v69, v69, v69
	v_cvt_pk_bf16_f32 v67, v67, v68
	v_cvt_pk_bf16_f32 v68, v74, v71
	v_max_f32_e32 v58, 0, v58
	v_max_f32_e32 v59, v59, v59
	v_max_f32_e32 v60, v60, v60
	v_mul_f32_e32 v70, v70, v70
	v_cvt_pk_bf16_f32 v66, v70, v66
	v_cvt_pk_bf16_f32 v69, v72, v69
	global_store_dwordx4 v[82:83], v[66:69], off offset:256 nt
	v_max_f32_e32 v62, v62, v62
	v_max_f32_e32 v59, 0, v59
	v_mul_f32_e32 v68, v58, v58
	v_max_f32_e32 v58, v63, v63
	v_max_f32_e32 v60, 0, v60
	v_max_f32_e32 v62, 0, v62
	v_max_f32_e32 v58, 0, v58
	v_mul_f32_e32 v63, v59, v59
	v_max_f32_e32 v59, v64, v64
	v_mul_f32_e32 v64, v60, v60
; __device__ __forceinline__ unsigned cvt_pk_bf16(float lo, float hi) { unsigned r; asm("v_cvt_pk_bf16_f32 %0, %1, %2" : "=v"(r) : "v"(lo), "v"(hi)); return r; }
;     __device__ __forceinline__ void operator()(const f32x4 (&acc)[2][2][4][2], const Unit& u, int wr, int wc, int fr, int fq) const {
;     ...
;             for (int m = 0; m < 4; ++m) { bf16_t* rowp = O + (size_t)(row0 + ai * HALF + m * 16) * ldc + col0;
; #pragma unroll
;                 for (int bj = 0; bj < 2; ++bj) { f32x4 v0 = acc[ai][bj][m][0], v1 = acc[ai][bj][m][1];
;                     if (ACT == 1) {
; #pragma unroll
;                         for (int j = 0; j < 4; ++j) { float a = fmaxf(v0[j], 0.f), b = fmaxf(v1[j], 0.f); v0[j] = a * a; v1[j] = b * b; } }
;                     u32x4 w; w.x = cvt_pk_bf16(v0[0], v0[1]); w.y = cvt_pk_bf16(v0[2], v0[3]); w.z = cvt_pk_bf16(v1[0], v1[1]); w.w = cvt_pk_bf16(v1[2], v1[3]);
;                     if (ACT == 1) __builtin_nontemporal_store(w, (u32x4*)(rowp + bj * HALF));
;                     else *(u32x4*)(rowp + bj * HALF) = w; } }
	v_max_f32_e32 v60, v65, v65
	v_mul_f32_e32 v62, v62, v62
	v_mul_f32_e32 v58, v58, v58
	v_max_f32_e32 v59, 0, v59
	v_max_f32_e32 v60, 0, v60
	v_max_f32_e32 v61, v61, v61
	s_mov_b32 s8, 0x200000
	v_mul_f32_e32 v59, v59, v59
	v_max_f32_e32 v61, 0, v61
	v_mul_f32_e32 v60, v60, v60
	v_cvt_pk_bf16_f32 v58, v62, v58
	v_add_co_u32_e32 v62, vcc, s8, v140
	v_max_f32_e32 v50, v50, v50
	v_max_f32_e32 v51, v51, v51
	v_max_f32_e32 v52, v52, v52
	v_mul_f32_e32 v61, v61, v61
	v_cvt_pk_bf16_f32 v59, v59, v60
	v_cvt_pk_bf16_f32 v60, v68, v63
	v_addc_co_u32_e32 v63, vcc, 0, v141, vcc
	v_max_f32_e32 v50, 0, v50
	v_max_f32_e32 v51, 0, v51
	v_max_f32_e32 v52, 0, v52
	v_cvt_pk_bf16_f32 v61, v64, v61
	global_store_dwordx4 v[62:63], v[58:61], off nt
	v_max_f32_e32 v53, v53, v53
	s_mov_b64 s[38:39], 0x200000
	v_mul_f32_e32 v58, v50, v50
	v_max_f32_e32 v50, v55, v55
	v_mul_f32_e32 v55, v51, v51
	v_max_f32_e32 v51, v56, v56
	v_mul_f32_e32 v56, v52, v52
	v_max_f32_e32 v52, v57, v57
	v_max_f32_e32 v51, 0, v51
	v_max_f32_e32 v52, 0, v52
	v_max_f32_e32 v54, v54, v54
	v_max_f32_e32 v50, 0, v50
	v_mul_f32_e32 v51, v51, v51
	v_max_f32_e32 v53, 0, v53
	v_mul_f32_e32 v52, v52, v52
	v_max_f32_e32 v42, v42, v42
	v_lshl_add_u64 v[66:67], v[140:141], 0, s[38:39]
	v_max_f32_e32 v54, 0, v54
	v_mul_f32_e32 v50, v50, v50
	v_mul_f32_e32 v53, v53, v53
	v_cvt_pk_bf16_f32 v51, v51, v52
	v_cvt_pk_bf16_f32 v52, v58, v55
	v_max_f32_e32 v42, 0, v42
	v_max_f32_e32 v43, v43, v43
	v_max_f32_e32 v44, v44, v44
	v_mul_f32_e32 v54, v54, v54
	v_cvt_pk_bf16_f32 v50, v54, v50
	v_cvt_pk_bf16_f32 v53, v56, v53
	global_store_dwordx4 v[66:67], v[50:53], off offset:256 nt
	v_max_f32_e32 v46, v46, v46
	v_max_f32_e32 v43, 0, v43
	v_mul_f32_e32 v52, v42, v42
	v_max_f32_e32 v42, v47, v47
	v_max_f32_e32 v44, 0, v44
	v_max_f32_e32 v46, 0, v46
	v_max_f32_e32 v42, 0, v42
	v_mul_f32_e32 v47, v43, v43
	v_max_f32_e32 v43, v48, v48
	v_mul_f32_e32 v48, v44, v44
	v_max_f32_e32 v44, v49, v49
	v_mul_f32_e32 v46, v46, v46
	v_mul_f32_e32 v42, v42, v42
	v_max_f32_e32 v43, 0, v43
	v_max_f32_e32 v44, 0, v44
	v_max_f32_e32 v45, v45, v45
	s_mov_b32 s8, 0x240000
	v_mul_f32_e32 v43, v43, v43
	v_max_f32_e32 v45, 0, v45
	v_mul_f32_e32 v44, v44, v44
	v_cvt_pk_bf16_f32 v42, v46, v42
	v_add_co_u32_e32 v46, vcc, s8, v140
	v_max_f32_e32 v34, v34, v34
	v_max_f32_e32 v35, v35, v35
	v_max_f32_e32 v36, v36, v36
	v_mul_f32_e32 v45, v45, v45
	v_cvt_pk_bf16_f32 v43, v43, v44
	v_cvt_pk_bf16_f32 v44, v52, v47
	v_addc_co_u32_e32 v47, vcc, 0, v141, vcc
	v_max_f32_e32 v34, 0, v34
	v_max_f32_e32 v35, 0, v35
	v_max_f32_e32 v36, 0, v36
	v_cvt_pk_bf16_f32 v45, v48, v45
	global_store_dwordx4 v[46:47], v[42:45], off nt
	v_max_f32_e32 v37, v37, v37
	s_mov_b64 s[38:39], 0x240000
	v_mul_f32_e32 v42, v34, v34
	v_max_f32_e32 v34, v39, v39
	v_mul_f32_e32 v39, v35, v35
	v_max_f32_e32 v35, v40, v40
	v_mul_f32_e32 v40, v36, v36
	v_max_f32_e32 v36, v41, v41
	v_max_f32_e32 v35, 0, v35
	v_max_f32_e32 v36, 0, v36
	v_max_f32_e32 v38, v38, v38
	v_max_f32_e32 v34, 0, v34
	v_mul_f32_e32 v35, v35, v35
	v_max_f32_e32 v37, 0, v37
	v_mul_f32_e32 v36, v36, v36
	v_max_f32_e32 v26, v26, v26
	v_lshl_add_u64 v[50:51], v[140:141], 0, s[38:39]
	v_max_f32_e32 v38, 0, v38
	v_mul_f32_e32 v34, v34, v34
	v_mul_f32_e32 v37, v37, v37
	v_cvt_pk_bf16_f32 v35, v35, v36
	v_cvt_pk_bf16_f32 v36, v42, v39
	v_max_f32_e32 v26, 0, v26
	v_max_f32_e32 v27, v27, v27
	v_max_f32_e32 v28, v28, v28
	v_mul_f32_e32 v38, v38, v38
	v_cvt_pk_bf16_f32 v34, v38, v34
	v_cvt_pk_bf16_f32 v37, v40, v37
	global_store_dwordx4 v[50:51], v[34:37], off offset:256 nt
	v_max_f32_e32 v30, v30, v30
	v_max_f32_e32 v27, 0, v27
	v_mul_f32_e32 v36, v26, v26
	v_max_f32_e32 v26, v31, v31
	v_max_f32_e32 v28, 0, v28
	v_max_f32_e32 v30, 0, v30
; __device__ __forceinline__ unsigned cvt_pk_bf16(float lo, float hi) { unsigned r; asm("v_cvt_pk_bf16_f32 %0, %1, %2" : "=v"(r) : "v"(lo), "v"(hi)); return r; }
;     __device__ __forceinline__ void operator()(const f32x4 (&acc)[2][2][4][2], const Unit& u, int wr, int wc, int fr, int fq) const {
;     ...
;             for (int m = 0; m < 4; ++m) { bf16_t* rowp = O + (size_t)(row0 + ai * HALF + m * 16) * ldc + col0;
; #pragma unroll
;                 for (int bj = 0; bj < 2; ++bj) { f32x4 v0 = acc[ai][bj][m][0], v1 = acc[ai][bj][m][1];
;                     if (ACT == 1) {
; #pragma unroll
;                         for (int j = 0; j < 4; ++j) { float a = fmaxf(v0[j], 0.f), b = fmaxf(v1[j], 0.f); v0[j] = a * a; v1[j] = b * b; } }
;                     u32x4 w; w.x = cvt_pk_bf16(v0[0], v0[1]); w.y = cvt_pk_bf16(v0[2], v0[3]); w.z = cvt_pk_bf16(v1[0], v1[1]); w.w = cvt_pk_bf16(v1[2], v1[3]);
;                     if (ACT == 1) __builtin_nontemporal_store(w, (u32x4*)(rowp + bj * HALF));
;                     else *(u32x4*)(rowp + bj * HALF) = w; } }
	v_max_f32_e32 v26, 0, v26
	v_mul_f32_e32 v31, v27, v27
	v_max_f32_e32 v27, v32, v32
	v_mul_f32_e32 v32, v28, v28
	v_max_f32_e32 v28, v33, v33
	v_mul_f32_e32 v30, v30, v30
	v_mul_f32_e32 v26, v26, v26
	v_max_f32_e32 v27, 0, v27
	v_max_f32_e32 v28, 0, v28
	v_max_f32_e32 v29, v29, v29
	s_mov_b32 s8, 0x280000
	v_mul_f32_e32 v27, v27, v27
	v_max_f32_e32 v29, 0, v29
	v_mul_f32_e32 v28, v28, v28
	v_cvt_pk_bf16_f32 v26, v30, v26
	v_add_co_u32_e32 v30, vcc, s8, v140
	v_max_f32_e32 v18, v18, v18
	v_max_f32_e32 v19, v19, v19
	v_max_f32_e32 v20, v20, v20
	v_mul_f32_e32 v29, v29, v29
	v_cvt_pk_bf16_f32 v27, v27, v28
	v_cvt_pk_bf16_f32 v28, v36, v31
	v_addc_co_u32_e32 v31, vcc, 0, v141, vcc
	v_max_f32_e32 v18, 0, v18
	v_max_f32_e32 v19, 0, v19
	v_max_f32_e32 v20, 0, v20
	v_cvt_pk_bf16_f32 v29, v32, v29
	global_store_dwordx4 v[30:31], v[26:29], off nt
	v_max_f32_e32 v21, v21, v21
	s_mov_b64 s[38:39], 0x280000
	v_mul_f32_e32 v26, v18, v18
	v_max_f32_e32 v18, v23, v23
	v_mul_f32_e32 v23, v19, v19
	v_max_f32_e32 v19, v24, v24
	v_mul_f32_e32 v24, v20, v20
	v_max_f32_e32 v20, v25, v25
	v_max_f32_e32 v19, 0, v19
	v_max_f32_e32 v20, 0, v20
	v_max_f32_e32 v22, v22, v22
	v_max_f32_e32 v18, 0, v18
	v_mul_f32_e32 v19, v19, v19
	v_max_f32_e32 v21, 0, v21
	v_mul_f32_e32 v20, v20, v20
	v_max_f32_e32 v10, v10, v10
	v_lshl_add_u64 v[34:35], v[140:141], 0, s[38:39]
	v_max_f32_e32 v22, 0, v22
	v_mul_f32_e32 v18, v18, v18
	v_mul_f32_e32 v21, v21, v21
	v_cvt_pk_bf16_f32 v19, v19, v20
	v_cvt_pk_bf16_f32 v20, v26, v23
	v_max_f32_e32 v10, 0, v10
	v_max_f32_e32 v11, v11, v11
	v_max_f32_e32 v12, v12, v12
	v_mul_f32_e32 v22, v22, v22
	v_cvt_pk_bf16_f32 v18, v22, v18
	v_cvt_pk_bf16_f32 v21, v24, v21
	global_store_dwordx4 v[34:35], v[18:21], off offset:256 nt
	v_max_f32_e32 v14, v14, v14
	v_max_f32_e32 v11, 0, v11
	v_mul_f32_e32 v20, v10, v10
	v_max_f32_e32 v10, v15, v15
	v_max_f32_e32 v12, 0, v12
	v_max_f32_e32 v14, 0, v14
	v_max_f32_e32 v10, 0, v10
	v_mul_f32_e32 v15, v11, v11
	v_max_f32_e32 v11, v16, v16
	v_mul_f32_e32 v16, v12, v12
	v_max_f32_e32 v12, v17, v17
	v_mul_f32_e32 v14, v14, v14
	v_mul_f32_e32 v10, v10, v10
	v_max_f32_e32 v11, 0, v11
	v_max_f32_e32 v12, 0, v12
	v_max_f32_e32 v13, v13, v13
	s_mov_b32 s8, 0x2c0000
	v_mul_f32_e32 v11, v11, v11
	v_max_f32_e32 v13, 0, v13
	v_mul_f32_e32 v12, v12, v12
	v_cvt_pk_bf16_f32 v10, v14, v10
	v_add_co_u32_e32 v14, vcc, s8, v140
	v_max_f32_e32 v2, v2, v2
	v_max_f32_e32 v3, v3, v3
	v_max_f32_e32 v4, v4, v4
	v_mul_f32_e32 v13, v13, v13
	v_cvt_pk_bf16_f32 v11, v11, v12
	v_cvt_pk_bf16_f32 v12, v20, v15
	v_addc_co_u32_e32 v15, vcc, 0, v141, vcc
	v_max_f32_e32 v2, 0, v2
	v_max_f32_e32 v3, 0, v3
	v_max_f32_e32 v4, 0, v4
	v_cvt_pk_bf16_f32 v13, v16, v13
	global_store_dwordx4 v[14:15], v[10:13], off nt
	v_max_f32_e32 v5, v5, v5
	s_mov_b64 s[38:39], 0x2c0000
	v_mul_f32_e32 v10, v2, v2
	v_max_f32_e32 v2, v7, v7
	v_mul_f32_e32 v7, v3, v3
	v_max_f32_e32 v3, v8, v8
	v_mul_f32_e32 v8, v4, v4
	v_max_f32_e32 v4, v9, v9
	v_max_f32_e32 v6, v6, v6
	v_max_f32_e32 v2, 0, v2
	v_max_f32_e32 v3, 0, v3
	v_max_f32_e32 v4, 0, v4
	v_max_f32_e32 v5, 0, v5
	v_lshl_add_u64 v[18:19], v[140:141], 0, s[38:39]
	v_max_f32_e32 v6, 0, v6
	v_mul_f32_e32 v2, v2, v2
	v_mul_f32_e32 v3, v3, v3
	v_mul_f32_e32 v4, v4, v4
	v_mul_f32_e32 v5, v5, v5
	s_and_b64 vcc, exec, s[40:41]
	s_mov_b32 s68, s26
	s_mov_b32 s8, s28
	s_mov_b64 s[46:47], s[44:45]
	s_mov_b64 s[48:49], s[42:43]
	v_mul_f32_e32 v6, v6, v6
	v_cvt_pk_bf16_f32 v2, v6, v2
	v_cvt_pk_bf16_f32 v3, v3, v4
	v_cvt_pk_bf16_f32 v4, v10, v7
	v_cvt_pk_bf16_f32 v5, v8, v5
	global_store_dwordx4 v[18:19], v[2:5], off offset:256 nt
	s_cbranch_vccz .LBB0_70
	s_waitcnt vmcnt(0)
	s_cmpk_gt_u32 s52, 0xff
	s_cbranch_scc1 .LBB0_77
	s_barrier

; #define PG8_STAGE(bufoff, gbase, voff) do { _Pragma("unroll") for (int _i = 0; _i < 2; ++_i) \
;         __builtin_amdgcn_global_load_lds((const unsigned*)((const char*)(gbase) + (voff)[_i]), (LAS unsigned*)(lds + (bufoff) + ldsw + _i * 8192), 16, 0, 0); } while (0)
; #define PG8_LDA(dst, b, h) do { _Pragma("unroll") for (int m = 0; m < 4; ++m) _Pragma("unroll") for (int k = 0; k < 2; ++k) dst[m][k] = *(const LAS bf16x8*)(lds + PG8_SA(b, h) + aoff + m * 2048 + k * 1024); } while (0)
; #define PG8_LDB(dst, b, h) do { _Pragma("unroll") for (int n = 0; n < 2; ++n) _Pragma("unroll") for (int k = 0; k < 2; ++k) dst[n][k] = *(const LAS bf16x8*)(lds + PG8_SB(b, h) + boff + n * 2048 + k * 1024); } while (0)
; #define PG8_MMA(ai, bj, At, Bt) do { __builtin_amdgcn_s_setprio(1); _Pragma("unroll") for (int m = 0; m < 4; ++m) _Pragma("unroll") for (int n = 0; n < 2; ++n) _Pragma("unroll") for (int k = 0; k < 2; ++k) \
;         acc[ai][bj][m][n] = __builtin_amdgcn_mfma_f32_16x16x32_bf16(Bt[n][k], At[m][k], acc[ai][bj][m][n], 0, 0, 0); __builtin_amdgcn_s_setprio(0); } while (0)
; #define PG8_WAIT_V(n) asm volatile("s_waitcnt vmcnt(" #n ")" ::: "memory")
; #define PG8_WAIT_L(n) asm volatile("s_waitcnt lgkmcnt(" #n ")" ::: "memory")
; #define PG8_BAR __builtin_amdgcn_s_barrier()
; template <class Epi, class Sched>
; __device__ __forceinline__ void gemm_phase(LAS unsigned char* lds, const Gemm g, const Sched& S, const Epi& E) {
;     ...
;             const bool last = (t == nt - 2);
;             const char* a1 = cA + (size_t)(t + 1) * kstep;
;             const char* a2 = last ? nA : cA + (size_t)(t + 2) * kstep; const char* b2 = last ? nB : cB + (size_t)(t + 2) * kstep;
;             const char* a3 = a2 + kstep; const char* b3 = b2 + kstep;
;             PG8_LDB(B0, 0, 0); PG8_SCHED; PG8_LDA(At, 0, 0); PG8_STAGE(PG8_SA(1, 1), a1 + hstep, voffA);
;             PG8_WAIT_L(8); PG8_BAR; PG8_WAIT_L(0); PG8_MMA(0, 0, At, B0); PG8_BAR; PG8_SCHED;
;             PG8_LDB(B1, 0, 1); PG8_STAGE(PG8_SB(0, 0), b2, voffB);
;             PG8_BAR; PG8_WAIT_L(0); PG8_MMA(0, 1, At, B1); PG8_BAR;
;             PG8_LDA(At, 0, 1); PG8_STAGE(PG8_SA(0, 0), a2, voffA);
;             PG8_BAR; PG8_WAIT_L(0); PG8_MMA(1, 0, At, B0); PG8_BAR; PG8_SCHED;
;             PG8_STAGE(PG8_SB(0, 1), b2 + hstep, voffB);
;             PG8_WAIT_V(6); PG8_BAR; PG8_MMA(1, 1, At, B1); PG8_BAR;
.LBB0_99:
	s_add_u32 s56, s28, 0x100
	s_addc_u32 s57, s29, 0
	s_cmp_eq_u32 s81, 28
	s_cselect_b32 s61, s51, s57
	s_cselect_b32 s60, s77, s56
	s_cselect_b32 s59, s49, s80
	s_cselect_b32 s58, s78, s79
	v_lshl_add_u64 v[156:157], s[28:29], 0, v[150:151]
	s_add_i32 m0, s9, 0xc000
	s_nop 0
	global_load_lds_dwordx4 v[156:157], off
	v_lshl_add_u64 v[156:157], s[28:29], 0, v[148:149]
	s_add_i32 m0, s9, 0xe000
	s_nop 0
	global_load_lds_dwordx4 v[156:157], off
	s_add_i32 s38, 0, 0x10000
	v_add_u32_e32 v110, s38, v169
	ds_read_b128 v[98:101], v110
	ds_read_b128 v[102:105], v110 offset:1024
	ds_read_b128 v[106:109], v110 offset:2048
	ds_read_b128 v[110:113], v110 offset:3072
	ds_read_b128 v[152:155], v171
	ds_read_b128 v[160:163], v171 offset:1024
	ds_read_b128 v[164:167], v171 offset:2048
	ds_read_b128 v[172:175], v171 offset:3072
	ds_read_b128 v[176:179], v171 offset:4096
	ds_read_b128 v[180:183], v171 offset:5120
	ds_read_b128 v[184:187], v171 offset:6144
	ds_read_b128 v[188:191], v171 offset:7168
	s_add_i32 s39, 0, 0x14000
	v_add_u32_e32 v156, s39, v169
	ds_read_b128 v[192:195], v156
	ds_read_b128 v[196:199], v156 offset:1024
	ds_read_b128 v[200:203], v156 offset:2048
	ds_read_b128 v[204:207], v156 offset:3072
	s_waitcnt vmcnt(8)
	s_waitcnt lgkmcnt(4)
	s_barrier
	s_waitcnt lgkmcnt(0)
	s_setprio 1
	v_mfma_f32_16x16x32_bf16 v[142:145], v[98:101], v[152:155], v[142:145]
	v_mfma_f32_16x16x32_bf16 v[138:141], v[106:109], v[152:155], v[138:141]
	v_mfma_f32_16x16x32_bf16 v[126:129], v[98:101], v[164:167], v[126:129]
	v_mfma_f32_16x16x32_bf16 v[122:125], v[106:109], v[164:167], v[122:125]
	v_mfma_f32_16x16x32_bf16 v[94:97], v[98:101], v[176:179], v[94:97]
	v_mfma_f32_16x16x32_bf16 v[90:93], v[106:109], v[176:179], v[90:93]
	v_mfma_f32_16x16x32_bf16 v[86:89], v[98:101], v[184:187], v[86:89]
	v_mfma_f32_16x16x32_bf16 v[82:85], v[106:109], v[184:187], v[82:85]
	v_mfma_f32_16x16x32_bf16 v[142:145], v[102:105], v[160:163], v[142:145]
	v_mfma_f32_16x16x32_bf16 v[138:141], v[110:113], v[160:163], v[138:141]
	v_mfma_f32_16x16x32_bf16 v[126:129], v[102:105], v[172:175], v[126:129]
	v_mfma_f32_16x16x32_bf16 v[122:125], v[110:113], v[172:175], v[122:125]
	v_mfma_f32_16x16x32_bf16 v[94:97], v[102:105], v[180:183], v[94:97]
	v_mfma_f32_16x16x32_bf16 v[90:93], v[110:113], v[180:183], v[90:93]
	v_mfma_f32_16x16x32_bf16 v[86:89], v[102:105], v[188:191], v[86:89]
	v_mfma_f32_16x16x32_bf16 v[82:85], v[110:113], v[188:191], v[82:85]
	v_mfma_f32_16x16x32_bf16 v[134:137], v[192:195], v[152:155], v[134:137]
	v_mfma_f32_16x16x32_bf16 v[130:133], v[200:203], v[152:155], v[130:133]
	v_mfma_f32_16x16x32_bf16 v[118:121], v[192:195], v[164:167], v[118:121]
	v_mfma_f32_16x16x32_bf16 v[114:117], v[200:203], v[164:167], v[114:117]
	v_mfma_f32_16x16x32_bf16 v[78:81], v[192:195], v[176:179], v[78:81]
	v_mfma_f32_16x16x32_bf16 v[74:77], v[200:203], v[176:179], v[74:77]
	v_mfma_f32_16x16x32_bf16 v[70:73], v[192:195], v[184:187], v[70:73]
	v_mfma_f32_16x16x32_bf16 v[66:69], v[200:203], v[184:187], v[66:69]
	v_mfma_f32_16x16x32_bf16 v[134:137], v[196:199], v[160:163], v[134:137]
	v_mfma_f32_16x16x32_bf16 v[130:133], v[204:207], v[160:163], v[130:133]
	v_mfma_f32_16x16x32_bf16 v[118:121], v[196:199], v[172:175], v[118:121]
	v_mfma_f32_16x16x32_bf16 v[114:117], v[204:207], v[172:175], v[114:117]
	v_mfma_f32_16x16x32_bf16 v[78:81], v[196:199], v[180:183], v[78:81]
	v_mfma_f32_16x16x32_bf16 v[74:77], v[204:207], v[180:183], v[74:77]
	v_mfma_f32_16x16x32_bf16 v[70:73], v[196:199], v[188:191], v[70:73]
	v_mfma_f32_16x16x32_bf16 v[66:69], v[204:207], v[188:191], v[66:69]
	s_setprio 0
	s_barrier
	s_add_i32 s28, s38, s67
	v_lshl_add_u64 v[156:157], s[58:59], 0, v[0:1]
	s_mov_b32 m0, s28
	v_lshl_add_u64 v[210:211], s[58:59], 0, v[146:147]
	global_load_lds_dwordx4 v[156:157], off
	s_add_i32 m0, s28, 0x2000
	s_nop 0
	global_load_lds_dwordx4 v[210:211], off
	s_mov_b32 m0, s9
	v_lshl_add_u64 v[212:213], s[60:61], 0, v[0:1]
	global_load_lds_dwordx4 v[212:213], off
	v_lshl_add_u64 v[214:215], s[60:61], 0, v[146:147]
	s_mov_b32 m0, s68
	s_nop 0
	global_load_lds_dwordx4 v[214:215], off
	ds_read_b128 v[152:155], v171 offset:16384
	ds_read_b128 v[160:163], v171 offset:17408
	ds_read_b128 v[164:167], v171 offset:18432
	ds_read_b128 v[172:175], v171 offset:19456
	ds_read_b128 v[176:179], v171 offset:20480
	ds_read_b128 v[180:183], v171 offset:21504
	ds_read_b128 v[184:187], v171 offset:22528
	ds_read_b128 v[188:191], v171 offset:23552
	s_waitcnt vmcnt(6)
	s_waitcnt lgkmcnt(0)
	s_barrier
	s_setprio 1
	v_mfma_f32_16x16x32_bf16 v[62:65], v[98:101], v[152:155], v[62:65]
	v_mfma_f32_16x16x32_bf16 v[58:61], v[106:109], v[152:155], v[58:61]
	v_mfma_f32_16x16x32_bf16 v[46:49], v[98:101], v[164:167], v[46:49]
	v_mfma_f32_16x16x32_bf16 v[42:45], v[106:109], v[164:167], v[42:45]
	v_mfma_f32_16x16x32_bf16 v[30:33], v[98:101], v[176:179], v[30:33]
	v_mfma_f32_16x16x32_bf16 v[26:29], v[106:109], v[176:179], v[26:29]
	v_mfma_f32_16x16x32_bf16 v[22:25], v[98:101], v[184:187], v[22:25]
	v_mfma_f32_16x16x32_bf16 v[18:21], v[106:109], v[184:187], v[18:21]
	v_mfma_f32_16x16x32_bf16 v[62:65], v[102:105], v[160:163], v[62:65]
	v_mfma_f32_16x16x32_bf16 v[58:61], v[110:113], v[160:163], v[58:61]
	v_mfma_f32_16x16x32_bf16 v[46:49], v[102:105], v[172:175], v[46:49]
	v_mfma_f32_16x16x32_bf16 v[42:45], v[110:113], v[172:175], v[42:45]
	v_mfma_f32_16x16x32_bf16 v[30:33], v[102:105], v[180:183], v[30:33]
	v_mfma_f32_16x16x32_bf16 v[26:29], v[110:113], v[180:183], v[26:29]
	v_mfma_f32_16x16x32_bf16 v[22:25], v[102:105], v[188:191], v[22:25]
	v_mfma_f32_16x16x32_bf16 v[18:21], v[110:113], v[188:191], v[18:21]
	v_mfma_f32_16x16x32_bf16 v[54:57], v[192:195], v[152:155], v[54:57]
	v_mfma_f32_16x16x32_bf16 v[50:53], v[200:203], v[152:155], v[50:53]
	v_mfma_f32_16x16x32_bf16 v[38:41], v[192:195], v[164:167], v[38:41]
	v_mfma_f32_16x16x32_bf16 v[34:37], v[200:203], v[164:167], v[34:37]
	v_mfma_f32_16x16x32_bf16 v[14:17], v[192:195], v[176:179], v[14:17]
	v_mfma_f32_16x16x32_bf16 v[10:13], v[200:203], v[176:179], v[10:13]
	v_mfma_f32_16x16x32_bf16 v[6:9], v[192:195], v[184:187], v[6:9]
	v_mfma_f32_16x16x32_bf16 v[2:5], v[200:203], v[184:187], v[2:5]
	v_mfma_f32_16x16x32_bf16 v[54:57], v[196:199], v[160:163], v[54:57]
	v_mfma_f32_16x16x32_bf16 v[50:53], v[204:207], v[160:163], v[50:53]
	v_mfma_f32_16x16x32_bf16 v[38:41], v[196:199], v[172:175], v[38:41]
	v_mfma_f32_16x16x32_bf16 v[34:37], v[204:207], v[172:175], v[34:37]
	v_mfma_f32_16x16x32_bf16 v[14:17], v[196:199], v[180:183], v[14:17]
	v_mfma_f32_16x16x32_bf16 v[10:13], v[204:207], v[180:183], v[10:13]
	v_mfma_f32_16x16x32_bf16 v[6:9], v[196:199], v[188:191], v[6:9]
	v_mfma_f32_16x16x32_bf16 v[2:5], v[204:207], v[188:191], v[2:5]
	s_setprio 0
	s_barrier
; #define PG8_STAGE(bufoff, gbase, voff) do { _Pragma("unroll") for (int _i = 0; _i < 2; ++_i) \
;         __builtin_amdgcn_global_load_lds((const unsigned*)((const char*)(gbase) + (voff)[_i]), (LAS unsigned*)(lds + (bufoff) + ldsw + _i * 8192), 16, 0, 0); } while (0)
; #define PG8_LDA(dst, b, h) do { _Pragma("unroll") for (int m = 0; m < 4; ++m) _Pragma("unroll") for (int k = 0; k < 2; ++k) dst[m][k] = *(const LAS bf16x8*)(lds + PG8_SA(b, h) + aoff + m * 2048 + k * 1024); } while (0)
; #define PG8_LDB(dst, b, h) do { _Pragma("unroll") for (int n = 0; n < 2; ++n) _Pragma("unroll") for (int k = 0; k < 2; ++k) dst[n][k] = *(const LAS bf16x8*)(lds + PG8_SB(b, h) + boff + n * 2048 + k * 1024); } while (0)
; #define PG8_MMA(ai, bj, At, Bt) do { __builtin_amdgcn_s_setprio(1); _Pragma("unroll") for (int m = 0; m < 4; ++m) _Pragma("unroll") for (int n = 0; n < 2; ++n) _Pragma("unroll") for (int k = 0; k < 2; ++k) \
;         acc[ai][bj][m][n] = __builtin_amdgcn_mfma_f32_16x16x32_bf16(Bt[n][k], At[m][k], acc[ai][bj][m][n], 0, 0, 0); __builtin_amdgcn_s_setprio(0); } while (0)
; #define PG8_WAIT_V(n) asm volatile("s_waitcnt vmcnt(" #n ")" ::: "memory")
; #define PG8_WAIT_L(n) asm volatile("s_waitcnt lgkmcnt(" #n ")" ::: "memory")
; #define PG8_BAR __builtin_amdgcn_s_barrier()
; #define PG8_SCHED __builtin_amdgcn_sched_barrier(0)
; template <class Epi, class Sched>
; __device__ __forceinline__ void gemm_phase(LAS unsigned char* lds, const Gemm g, const Sched& S, const Epi& E) {
;     ...
;             PG8_STAGE(PG8_SB(0, 1), b2 + hstep, voffB);
;             PG8_WAIT_V(6); PG8_BAR; PG8_MMA(1, 1, At, B1); PG8_BAR;
;             PG8_LDB(B0, 1, 0); PG8_SCHED; PG8_LDA(At, 1, 0); PG8_STAGE(PG8_SA(0, 1), a2 + hstep, voffA);
;             PG8_WAIT_L(8); PG8_BAR; PG8_WAIT_L(0); PG8_MMA(0, 0, At, B0); PG8_BAR; PG8_SCHED;
;             PG8_LDB(B1, 1, 1); PG8_STAGE(PG8_SB(1, 0), b3, voffB);
;             PG8_BAR; PG8_WAIT_L(0); PG8_MMA(0, 1, At, B1); PG8_BAR;
	s_add_u32 s28, s58, 0x80000
	s_addc_u32 s29, s59, 0
	s_add_i32 s38, s39, s67
	v_lshl_add_u64 v[98:99], s[28:29], 0, v[0:1]
	s_mov_b32 m0, s38
	s_nop 0
	global_load_lds_dwordx4 v[98:99], off
	v_lshl_add_u64 v[98:99], s[28:29], 0, v[146:147]
	s_add_i32 m0, s38, 0x2000
	s_nop 0
	global_load_lds_dwordx4 v[98:99], off
	s_add_u32 s28, s60, 0x80000
	s_addc_u32 s29, s61, 0
	s_mov_b32 m0, s69
	v_lshl_add_u64 v[192:193], s[28:29], 0, v[0:1]
	global_load_lds_dwordx4 v[192:193], off
	v_lshl_add_u64 v[192:193], s[28:29], 0, v[146:147]
	s_mov_b32 m0, s70
	s_nop 0
	global_load_lds_dwordx4 v[192:193], off
	s_add_i32 s38, 0, 0x18000
	v_add_u32_e32 v110, s38, v169
	ds_read_b128 v[98:101], v110
	ds_read_b128 v[102:105], v110 offset:1024
	ds_read_b128 v[106:109], v110 offset:2048
	ds_read_b128 v[110:113], v110 offset:3072
	ds_read_b128 v[152:155], v171 offset:32768
	ds_read_b128 v[160:163], v171 offset:33792
	ds_read_b128 v[164:167], v171 offset:34816
	ds_read_b128 v[172:175], v171 offset:35840
	ds_read_b128 v[176:179], v171 offset:36864
	ds_read_b128 v[180:183], v171 offset:37888
	ds_read_b128 v[184:187], v171 offset:38912
	ds_read_b128 v[188:191], v171 offset:39936
	s_add_i32 s39, 0, 0x1c000
	v_add_u32_e32 v204, s39, v169
	ds_read_b128 v[192:195], v204
	ds_read_b128 v[196:199], v204 offset:1024
	ds_read_b128 v[200:203], v204 offset:2048
	ds_read_b128 v[204:207], v204 offset:3072
	s_waitcnt vmcnt(8)
	s_waitcnt lgkmcnt(4)
	s_barrier
	s_waitcnt lgkmcnt(0)
	s_setprio 1
	v_mfma_f32_16x16x32_bf16 v[142:145], v[98:101], v[152:155], v[142:145]
	v_mfma_f32_16x16x32_bf16 v[138:141], v[106:109], v[152:155], v[138:141]
	v_mfma_f32_16x16x32_bf16 v[126:129], v[98:101], v[164:167], v[126:129]
	v_mfma_f32_16x16x32_bf16 v[122:125], v[106:109], v[164:167], v[122:125]
	v_mfma_f32_16x16x32_bf16 v[94:97], v[98:101], v[176:179], v[94:97]
	v_mfma_f32_16x16x32_bf16 v[90:93], v[106:109], v[176:179], v[90:93]
	v_mfma_f32_16x16x32_bf16 v[86:89], v[98:101], v[184:187], v[86:89]
	v_mfma_f32_16x16x32_bf16 v[82:85], v[106:109], v[184:187], v[82:85]
	v_mfma_f32_16x16x32_bf16 v[142:145], v[102:105], v[160:163], v[142:145]
	v_mfma_f32_16x16x32_bf16 v[138:141], v[110:113], v[160:163], v[138:141]
	v_mfma_f32_16x16x32_bf16 v[126:129], v[102:105], v[172:175], v[126:129]
	v_mfma_f32_16x16x32_bf16 v[122:125], v[110:113], v[172:175], v[122:125]
	v_mfma_f32_16x16x32_bf16 v[94:97], v[102:105], v[180:183], v[94:97]
	v_mfma_f32_16x16x32_bf16 v[90:93], v[110:113], v[180:183], v[90:93]
	v_mfma_f32_16x16x32_bf16 v[86:89], v[102:105], v[188:191], v[86:89]
	v_mfma_f32_16x16x32_bf16 v[82:85], v[110:113], v[188:191], v[82:85]
	v_mfma_f32_16x16x32_bf16 v[134:137], v[192:195], v[152:155], v[134:137]
	v_mfma_f32_16x16x32_bf16 v[130:133], v[200:203], v[152:155], v[130:133]
	v_mfma_f32_16x16x32_bf16 v[118:121], v[192:195], v[164:167], v[118:121]
	v_mfma_f32_16x16x32_bf16 v[114:117], v[200:203], v[164:167], v[114:117]
	v_mfma_f32_16x16x32_bf16 v[78:81], v[192:195], v[176:179], v[78:81]
	v_mfma_f32_16x16x32_bf16 v[74:77], v[200:203], v[176:179], v[74:77]
	v_mfma_f32_16x16x32_bf16 v[70:73], v[192:195], v[184:187], v[70:73]
	v_mfma_f32_16x16x32_bf16 v[66:69], v[200:203], v[184:187], v[66:69]
	v_mfma_f32_16x16x32_bf16 v[134:137], v[196:199], v[160:163], v[134:137]
	v_mfma_f32_16x16x32_bf16 v[130:133], v[204:207], v[160:163], v[130:133]
	v_mfma_f32_16x16x32_bf16 v[118:121], v[196:199], v[172:175], v[118:121]
	v_mfma_f32_16x16x32_bf16 v[114:117], v[204:207], v[172:175], v[114:117]
	v_mfma_f32_16x16x32_bf16 v[78:81], v[196:199], v[180:183], v[78:81]
	v_mfma_f32_16x16x32_bf16 v[74:77], v[204:207], v[180:183], v[74:77]
	v_mfma_f32_16x16x32_bf16 v[70:73], v[196:199], v[188:191], v[70:73]
	v_mfma_f32_16x16x32_bf16 v[66:69], v[204:207], v[188:191], v[66:69]
	s_setprio 0
	s_barrier
; #define PG8_STAGE(bufoff, gbase, voff) do { _Pragma("unroll") for (int _i = 0; _i < 2; ++_i) \
;         __builtin_amdgcn_global_load_lds((const unsigned*)((const char*)(gbase) + (voff)[_i]), (LAS unsigned*)(lds + (bufoff) + ldsw + _i * 8192), 16, 0, 0); } while (0)
; #define PG8_LDA(dst, b, h) do { _Pragma("unroll") for (int m = 0; m < 4; ++m) _Pragma("unroll") for (int k = 0; k < 2; ++k) dst[m][k] = *(const LAS bf16x8*)(lds + PG8_SA(b, h) + aoff + m * 2048 + k * 1024); } while (0)
; #define PG8_MMA(ai, bj, At, Bt) do { __builtin_amdgcn_s_setprio(1); _Pragma("unroll") for (int m = 0; m < 4; ++m) _Pragma("unroll") for (int n = 0; n < 2; ++n) _Pragma("unroll") for (int k = 0; k < 2; ++k) \
;         acc[ai][bj][m][n] = __builtin_amdgcn_mfma_f32_16x16x32_bf16(Bt[n][k], At[m][k], acc[ai][bj][m][n], 0, 0, 0); __builtin_amdgcn_s_setprio(0); } while (0)
; #define PG8_WAIT_V(n) asm volatile("s_waitcnt vmcnt(" #n ")" ::: "memory")
; #define PG8_WAIT_L(n) asm volatile("s_waitcnt lgkmcnt(" #n ")" ::: "memory")
; #define PG8_BAR __builtin_amdgcn_s_barrier()
; #define PG8_SCHED __builtin_amdgcn_sched_barrier(0)
; template <class Epi, class Sched>
; __device__ __forceinline__ void gemm_phase(LAS unsigned char* lds, const Gemm g, const Sched& S, const Epi& E) {
;     ...
;             PG8_LDA(At, 1, 1); PG8_STAGE(PG8_SA(1, 0), a3, voffA);
;             PG8_BAR; PG8_WAIT_L(0); PG8_MMA(1, 0, At, B0); PG8_BAR; PG8_SCHED;
;             PG8_STAGE(PG8_SB(1, 1), b3 + hstep, voffB);
;             PG8_WAIT_V(6); PG8_BAR; PG8_MMA(1, 1, At, B1); PG8_BAR;
;         }
;         E(acc, cur, wr, wc, fr, fq);
;         if (!has_next) break;
	s_add_i32 s28, s38, s67
	v_lshl_add_u64 v[156:157], v[156:157], 0, s[36:37]
	s_mov_b32 m0, s28
	s_nop 0
	global_load_lds_dwordx4 v[156:157], off
	v_lshl_add_u64 v[156:157], v[210:211], 0, s[36:37]
	s_add_i32 m0, s28, 0x2000
	s_nop 0
	global_load_lds_dwordx4 v[156:157], off
	s_mov_b32 m0, s72
	v_lshl_add_u64 v[156:157], v[212:213], 0, s[36:37]
	global_load_lds_dwordx4 v[156:157], off
	v_lshl_add_u64 v[156:157], v[214:215], 0, s[36:37]
	s_mov_b32 m0, s73
	s_nop 0
	global_load_lds_dwordx4 v[156:157], off
	ds_read_b128 v[152:155], v171 offset:49152
	ds_read_b128 v[160:163], v171 offset:50176
	ds_read_b128 v[164:167], v171 offset:51200
	ds_read_b128 v[172:175], v171 offset:52224
	ds_read_b128 v[176:179], v171 offset:53248
	ds_read_b128 v[180:183], v171 offset:54272
	ds_read_b128 v[184:187], v171 offset:55296
	ds_read_b128 v[188:191], v171 offset:56320
	s_waitcnt vmcnt(6)
	s_waitcnt lgkmcnt(0)
	s_barrier
	s_setprio 1
	v_mfma_f32_16x16x32_bf16 v[62:65], v[98:101], v[152:155], v[62:65]
	v_mfma_f32_16x16x32_bf16 v[58:61], v[106:109], v[152:155], v[58:61]
	v_mfma_f32_16x16x32_bf16 v[46:49], v[98:101], v[164:167], v[46:49]
	v_mfma_f32_16x16x32_bf16 v[42:45], v[106:109], v[164:167], v[42:45]
	v_mfma_f32_16x16x32_bf16 v[30:33], v[98:101], v[176:179], v[30:33]
	v_mfma_f32_16x16x32_bf16 v[26:29], v[106:109], v[176:179], v[26:29]
	v_mfma_f32_16x16x32_bf16 v[22:25], v[98:101], v[184:187], v[22:25]
	v_mfma_f32_16x16x32_bf16 v[18:21], v[106:109], v[184:187], v[18:21]
	v_mfma_f32_16x16x32_bf16 v[62:65], v[102:105], v[160:163], v[62:65]
	v_mfma_f32_16x16x32_bf16 v[58:61], v[110:113], v[160:163], v[58:61]
	v_mfma_f32_16x16x32_bf16 v[46:49], v[102:105], v[172:175], v[46:49]
	v_mfma_f32_16x16x32_bf16 v[42:45], v[110:113], v[172:175], v[42:45]
	v_mfma_f32_16x16x32_bf16 v[30:33], v[102:105], v[180:183], v[30:33]
	v_mfma_f32_16x16x32_bf16 v[26:29], v[110:113], v[180:183], v[26:29]
	v_mfma_f32_16x16x32_bf16 v[22:25], v[102:105], v[188:191], v[22:25]
	v_mfma_f32_16x16x32_bf16 v[18:21], v[110:113], v[188:191], v[18:21]
	s_add_u32 s28, s58, 0x80080
	s_addc_u32 s29, s59, 0
	s_add_i32 s38, s39, s67
	v_lshl_add_u64 v[98:99], s[28:29], 0, v[0:1]
	s_mov_b32 m0, s38
	s_nop 0
	global_load_lds_dwordx4 v[98:99], off
	v_lshl_add_u64 v[98:99], s[28:29], 0, v[146:147]
	s_add_i32 m0, s38, 0x2000
	s_nop 0
	global_load_lds_dwordx4 v[98:99], off
	v_mfma_f32_16x16x32_bf16 v[54:57], v[192:195], v[152:155], v[54:57]
	v_mfma_f32_16x16x32_bf16 v[50:53], v[200:203], v[152:155], v[50:53]
	v_mfma_f32_16x16x32_bf16 v[38:41], v[192:195], v[164:167], v[38:41]
	v_mfma_f32_16x16x32_bf16 v[34:37], v[200:203], v[164:167], v[34:37]
	v_mfma_f32_16x16x32_bf16 v[14:17], v[192:195], v[176:179], v[14:17]
	v_mfma_f32_16x16x32_bf16 v[10:13], v[200:203], v[176:179], v[10:13]
	v_mfma_f32_16x16x32_bf16 v[6:9], v[192:195], v[184:187], v[6:9]
	v_mfma_f32_16x16x32_bf16 v[2:5], v[200:203], v[184:187], v[2:5]
	v_mfma_f32_16x16x32_bf16 v[54:57], v[196:199], v[160:163], v[54:57]
	v_mfma_f32_16x16x32_bf16 v[50:53], v[204:207], v[160:163], v[50:53]
	v_mfma_f32_16x16x32_bf16 v[38:41], v[196:199], v[172:175], v[38:41]
	v_mfma_f32_16x16x32_bf16 v[34:37], v[204:207], v[172:175], v[34:37]
	v_mfma_f32_16x16x32_bf16 v[14:17], v[196:199], v[180:183], v[14:17]
	v_mfma_f32_16x16x32_bf16 v[10:13], v[204:207], v[180:183], v[10:13]
	v_mfma_f32_16x16x32_bf16 v[6:9], v[196:199], v[188:191], v[6:9]
	v_mfma_f32_16x16x32_bf16 v[2:5], v[204:207], v[188:191], v[2:5]
	s_setprio 0
	s_add_i32 s81, s81, 2
	s_add_u32 s79, s79, 0x100
	s_addc_u32 s80, s80, 0
	s_cmp_gt_u32 s81, 29
	s_mov_b64 s[28:29], s[56:57]
	s_barrier
	s_cbranch_scc0 .LBB0_99
	s_cmp_lt_i32 s8, 64
	s_cselect_b64 s[58:59], -1, 0
	s_cmp_gt_i32 s8, 63
	s_cbranch_scc0 .LBB0_90
	s_mov_b64 s[60:61], 0x18000
	s_mov_b64 s[28:29], s[46:47]
	s_mov_b64 s[56:57], s[24:25]
	s_branch .LBB0_91

; #define PG8_STAGE(bufoff, gbase, voff) do { _Pragma("unroll") for (int _i = 0; _i < 2; ++_i) \
;         __builtin_amdgcn_global_load_lds((const unsigned*)((const char*)(gbase) + (voff)[_i]), (LAS unsigned*)(lds + (bufoff) + ldsw + _i * 8192), 16, 0, 0); } while (0)
; #define PG8_LDA(dst, b, h) do { _Pragma("unroll") for (int m = 0; m < 4; ++m) _Pragma("unroll") for (int k = 0; k < 2; ++k) dst[m][k] = *(const LAS bf16x8*)(lds + PG8_SA(b, h) + aoff + m * 2048 + k * 1024); } while (0)
; #define PG8_LDB(dst, b, h) do { _Pragma("unroll") for (int n = 0; n < 2; ++n) _Pragma("unroll") for (int k = 0; k < 2; ++k) dst[n][k] = *(const LAS bf16x8*)(lds + PG8_SB(b, h) + boff + n * 2048 + k * 1024); } while (0)
; #define PG8_MMA(ai, bj, At, Bt) do { __builtin_amdgcn_s_setprio(1); _Pragma("unroll") for (int m = 0; m < 4; ++m) _Pragma("unroll") for (int n = 0; n < 2; ++n) _Pragma("unroll") for (int k = 0; k < 2; ++k) \
;         acc[ai][bj][m][n] = __builtin_amdgcn_mfma_f32_16x16x32_bf16(Bt[n][k], At[m][k], acc[ai][bj][m][n], 0, 0, 0); __builtin_amdgcn_s_setprio(0); } while (0)
; #define PG8_WAIT_V(n) asm volatile("s_waitcnt vmcnt(" #n ")" ::: "memory")
; #define PG8_WAIT_L(n) asm volatile("s_waitcnt lgkmcnt(" #n ")" ::: "memory")
; #define PG8_BAR __builtin_amdgcn_s_barrier()
; template <class Epi, class Sched>
; __device__ __forceinline__ void gemm_phase(LAS unsigned char* lds, const Gemm g, const Sched& S, const Epi& E) {
;     ...
;             const bool last = (t == nt - 2);
;             const char* a1 = cA + (size_t)(t + 1) * kstep;
;             const char* a2 = last ? nA : cA + (size_t)(t + 2) * kstep; const char* b2 = last ? nB : cB + (size_t)(t + 2) * kstep;
;             const char* a3 = a2 + kstep; const char* b3 = b2 + kstep;
;             PG8_LDB(B0, 0, 0); PG8_SCHED; PG8_LDA(At, 0, 0); PG8_STAGE(PG8_SA(1, 1), a1 + hstep, voffA);
;             PG8_WAIT_L(8); PG8_BAR; PG8_WAIT_L(0); PG8_MMA(0, 0, At, B0); PG8_BAR; PG8_SCHED;
;             PG8_LDB(B1, 0, 1); PG8_STAGE(PG8_SB(0, 0), b2, voffB);
;             PG8_BAR; PG8_WAIT_L(0); PG8_MMA(0, 1, At, B1); PG8_BAR;
;             PG8_LDA(At, 0, 1); PG8_STAGE(PG8_SA(0, 0), a2, voffA);
;             PG8_BAR; PG8_WAIT_L(0); PG8_MMA(1, 0, At, B0); PG8_BAR; PG8_SCHED;
;             PG8_STAGE(PG8_SB(0, 1), b2 + hstep, voffB);
;             PG8_WAIT_V(6); PG8_BAR; PG8_MMA(1, 1, At, B1); PG8_BAR;
.LBB0_113:
	s_add_u32 s54, s52, 0x100
	s_addc_u32 s55, s53, 0
	s_cmp_eq_u32 s73, 4
	s_cselect_b32 s59, s11, s55
	s_cselect_b32 s58, s29, s54
	s_cselect_b32 s57, s41, s72
	s_cselect_b32 s56, s45, s71
	v_lshl_add_u64 v[156:157], s[52:53], 0, v[134:135]
	s_add_i32 m0, s25, 0xc000
	s_nop 0
	global_load_lds_dwordx4 v[156:157], off
	v_lshl_add_u64 v[156:157], s[52:53], 0, v[132:133]
	s_add_i32 m0, s25, 0xe000
	s_nop 0
	global_load_lds_dwordx4 v[156:157], off
	s_add_i32 s38, 0, 0x10000
	v_add_u32_e32 v152, s38, v137
	ds_read_b128 v[140:143], v152
	ds_read_b128 v[144:147], v152 offset:1024
	ds_read_b128 v[148:151], v152 offset:2048
	ds_read_b128 v[152:155], v152 offset:3072
	ds_read_b128 v[160:163], v139
	ds_read_b128 v[164:167], v139 offset:1024
	ds_read_b128 v[168:171], v139 offset:2048
	ds_read_b128 v[172:175], v139 offset:3072
	ds_read_b128 v[176:179], v139 offset:4096
	ds_read_b128 v[180:183], v139 offset:5120
	ds_read_b128 v[184:187], v139 offset:6144
	ds_read_b128 v[188:191], v139 offset:7168
	s_add_i32 s52, 0, 0x14000
	v_add_u32_e32 v156, s52, v137
	ds_read_b128 v[192:195], v156
	ds_read_b128 v[196:199], v156 offset:1024
	ds_read_b128 v[200:203], v156 offset:2048
	ds_read_b128 v[204:207], v156 offset:3072
	s_waitcnt vmcnt(8)
	s_waitcnt lgkmcnt(4)
	s_barrier
	s_waitcnt lgkmcnt(0)
	s_setprio 1
	v_mfma_f32_16x16x32_bf16 v[126:129], v[140:143], v[160:163], v[126:129]
	v_mfma_f32_16x16x32_bf16 v[122:125], v[148:151], v[160:163], v[122:125]
	v_mfma_f32_16x16x32_bf16 v[118:121], v[140:143], v[168:171], v[118:121]
	v_mfma_f32_16x16x32_bf16 v[114:117], v[148:151], v[168:171], v[114:117]
	v_mfma_f32_16x16x32_bf16 v[106:109], v[140:143], v[176:179], v[106:109]
	v_mfma_f32_16x16x32_bf16 v[98:101], v[148:151], v[176:179], v[98:101]
	v_mfma_f32_16x16x32_bf16 v[90:93], v[140:143], v[184:187], v[90:93]
	v_mfma_f32_16x16x32_bf16 v[82:85], v[148:151], v[184:187], v[82:85]
	v_mfma_f32_16x16x32_bf16 v[126:129], v[144:147], v[164:167], v[126:129]
	v_mfma_f32_16x16x32_bf16 v[122:125], v[152:155], v[164:167], v[122:125]
	v_mfma_f32_16x16x32_bf16 v[118:121], v[144:147], v[172:175], v[118:121]
	v_mfma_f32_16x16x32_bf16 v[114:117], v[152:155], v[172:175], v[114:117]
	v_mfma_f32_16x16x32_bf16 v[106:109], v[144:147], v[180:183], v[106:109]
	v_mfma_f32_16x16x32_bf16 v[98:101], v[152:155], v[180:183], v[98:101]
	v_mfma_f32_16x16x32_bf16 v[90:93], v[144:147], v[188:191], v[90:93]
	v_mfma_f32_16x16x32_bf16 v[82:85], v[152:155], v[188:191], v[82:85]
	v_mfma_f32_16x16x32_bf16 v[110:113], v[192:195], v[160:163], v[110:113]
	v_mfma_f32_16x16x32_bf16 v[102:105], v[200:203], v[160:163], v[102:105]
	v_mfma_f32_16x16x32_bf16 v[94:97], v[192:195], v[168:171], v[94:97]
	v_mfma_f32_16x16x32_bf16 v[86:89], v[200:203], v[168:171], v[86:89]
	v_mfma_f32_16x16x32_bf16 v[78:81], v[192:195], v[176:179], v[78:81]
	v_mfma_f32_16x16x32_bf16 v[74:77], v[200:203], v[176:179], v[74:77]
	v_mfma_f32_16x16x32_bf16 v[70:73], v[192:195], v[184:187], v[70:73]
	v_mfma_f32_16x16x32_bf16 v[66:69], v[200:203], v[184:187], v[66:69]
	v_mfma_f32_16x16x32_bf16 v[110:113], v[196:199], v[164:167], v[110:113]
	v_mfma_f32_16x16x32_bf16 v[102:105], v[204:207], v[164:167], v[102:105]
	v_mfma_f32_16x16x32_bf16 v[94:97], v[196:199], v[172:175], v[94:97]
	v_mfma_f32_16x16x32_bf16 v[86:89], v[204:207], v[172:175], v[86:89]
	v_mfma_f32_16x16x32_bf16 v[78:81], v[196:199], v[180:183], v[78:81]
	v_mfma_f32_16x16x32_bf16 v[74:77], v[204:207], v[180:183], v[74:77]
	v_mfma_f32_16x16x32_bf16 v[70:73], v[196:199], v[188:191], v[70:73]
	v_mfma_f32_16x16x32_bf16 v[66:69], v[204:207], v[188:191], v[66:69]
	s_setprio 0
	s_barrier
	s_add_i32 s38, s38, s65
	v_lshl_add_u64 v[156:157], s[56:57], 0, v[0:1]
	s_mov_b32 m0, s38
	v_lshl_add_u64 v[210:211], s[56:57], 0, v[130:131]
	global_load_lds_dwordx4 v[156:157], off
	s_add_i32 m0, s38, 0x2000
	s_nop 0
	global_load_lds_dwordx4 v[210:211], off
	s_mov_b32 m0, s25
	v_lshl_add_u64 v[212:213], s[58:59], 0, v[0:1]
	global_load_lds_dwordx4 v[212:213], off
	v_lshl_add_u64 v[214:215], s[58:59], 0, v[130:131]
	s_mov_b32 m0, s27
	s_nop 0
	global_load_lds_dwordx4 v[214:215], off
	ds_read_b128 v[160:163], v139 offset:16384
	ds_read_b128 v[164:167], v139 offset:17408
	ds_read_b128 v[168:171], v139 offset:18432
	ds_read_b128 v[172:175], v139 offset:19456
	ds_read_b128 v[176:179], v139 offset:20480
	ds_read_b128 v[180:183], v139 offset:21504
	ds_read_b128 v[184:187], v139 offset:22528
	ds_read_b128 v[188:191], v139 offset:23552
	s_waitcnt vmcnt(6)
	s_waitcnt lgkmcnt(0)
	s_barrier
	s_setprio 1
	v_mfma_f32_16x16x32_bf16 v[62:65], v[140:143], v[160:163], v[62:65]
	v_mfma_f32_16x16x32_bf16 v[58:61], v[148:151], v[160:163], v[58:61]
	v_mfma_f32_16x16x32_bf16 v[54:57], v[140:143], v[168:171], v[54:57]
	v_mfma_f32_16x16x32_bf16 v[50:53], v[148:151], v[168:171], v[50:53]
	v_mfma_f32_16x16x32_bf16 v[38:41], v[140:143], v[176:179], v[38:41]
	v_mfma_f32_16x16x32_bf16 v[34:37], v[148:151], v[176:179], v[34:37]
	v_mfma_f32_16x16x32_bf16 v[22:25], v[140:143], v[184:187], v[22:25]
	v_mfma_f32_16x16x32_bf16 v[18:21], v[148:151], v[184:187], v[18:21]
	v_mfma_f32_16x16x32_bf16 v[62:65], v[144:147], v[164:167], v[62:65]
	v_mfma_f32_16x16x32_bf16 v[58:61], v[152:155], v[164:167], v[58:61]
	v_mfma_f32_16x16x32_bf16 v[54:57], v[144:147], v[172:175], v[54:57]
	v_mfma_f32_16x16x32_bf16 v[50:53], v[152:155], v[172:175], v[50:53]
	v_mfma_f32_16x16x32_bf16 v[38:41], v[144:147], v[180:183], v[38:41]
	v_mfma_f32_16x16x32_bf16 v[34:37], v[152:155], v[180:183], v[34:37]
	v_mfma_f32_16x16x32_bf16 v[22:25], v[144:147], v[188:191], v[22:25]
	v_mfma_f32_16x16x32_bf16 v[18:21], v[152:155], v[188:191], v[18:21]
	v_mfma_f32_16x16x32_bf16 v[46:49], v[192:195], v[160:163], v[46:49]
	v_mfma_f32_16x16x32_bf16 v[42:45], v[200:203], v[160:163], v[42:45]
	v_mfma_f32_16x16x32_bf16 v[30:33], v[192:195], v[168:171], v[30:33]
	v_mfma_f32_16x16x32_bf16 v[26:29], v[200:203], v[168:171], v[26:29]
	v_mfma_f32_16x16x32_bf16 v[14:17], v[192:195], v[176:179], v[14:17]
	v_mfma_f32_16x16x32_bf16 v[10:13], v[200:203], v[176:179], v[10:13]
	v_mfma_f32_16x16x32_bf16 v[6:9], v[192:195], v[184:187], v[6:9]
	v_mfma_f32_16x16x32_bf16 v[2:5], v[200:203], v[184:187], v[2:5]
	v_mfma_f32_16x16x32_bf16 v[46:49], v[196:199], v[164:167], v[46:49]
	v_mfma_f32_16x16x32_bf16 v[42:45], v[204:207], v[164:167], v[42:45]
	v_mfma_f32_16x16x32_bf16 v[30:33], v[196:199], v[172:175], v[30:33]
	v_mfma_f32_16x16x32_bf16 v[26:29], v[204:207], v[172:175], v[26:29]
	v_mfma_f32_16x16x32_bf16 v[14:17], v[196:199], v[180:183], v[14:17]
	v_mfma_f32_16x16x32_bf16 v[10:13], v[204:207], v[180:183], v[10:13]
	v_mfma_f32_16x16x32_bf16 v[6:9], v[196:199], v[188:191], v[6:9]
	v_mfma_f32_16x16x32_bf16 v[2:5], v[204:207], v[188:191], v[2:5]
	s_setprio 0
	s_barrier
; #define PG8_STAGE(bufoff, gbase, voff) do { _Pragma("unroll") for (int _i = 0; _i < 2; ++_i) \
;         __builtin_amdgcn_global_load_lds((const unsigned*)((const char*)(gbase) + (voff)[_i]), (LAS unsigned*)(lds + (bufoff) + ldsw + _i * 8192), 16, 0, 0); } while (0)
; #define PG8_LDA(dst, b, h) do { _Pragma("unroll") for (int m = 0; m < 4; ++m) _Pragma("unroll") for (int k = 0; k < 2; ++k) dst[m][k] = *(const LAS bf16x8*)(lds + PG8_SA(b, h) + aoff + m * 2048 + k * 1024); } while (0)
; #define PG8_LDB(dst, b, h) do { _Pragma("unroll") for (int n = 0; n < 2; ++n) _Pragma("unroll") for (int k = 0; k < 2; ++k) dst[n][k] = *(const LAS bf16x8*)(lds + PG8_SB(b, h) + boff + n * 2048 + k * 1024); } while (0)
; #define PG8_MMA(ai, bj, At, Bt) do { __builtin_amdgcn_s_setprio(1); _Pragma("unroll") for (int m = 0; m < 4; ++m) _Pragma("unroll") for (int n = 0; n < 2; ++n) _Pragma("unroll") for (int k = 0; k < 2; ++k) \
;         acc[ai][bj][m][n] = __builtin_amdgcn_mfma_f32_16x16x32_bf16(Bt[n][k], At[m][k], acc[ai][bj][m][n], 0, 0, 0); __builtin_amdgcn_s_setprio(0); } while (0)
; #define PG8_WAIT_V(n) asm volatile("s_waitcnt vmcnt(" #n ")" ::: "memory")
; #define PG8_WAIT_L(n) asm volatile("s_waitcnt lgkmcnt(" #n ")" ::: "memory")
; #define PG8_BAR __builtin_amdgcn_s_barrier()
; #define PG8_SCHED __builtin_amdgcn_sched_barrier(0)
; template <class Epi, class Sched>
; __device__ __forceinline__ void gemm_phase(LAS unsigned char* lds, const Gemm g, const Sched& S, const Epi& E) {
;     ...
;             PG8_STAGE(PG8_SB(0, 1), b2 + hstep, voffB);
;             PG8_WAIT_V(6); PG8_BAR; PG8_MMA(1, 1, At, B1); PG8_BAR;
;             PG8_LDB(B0, 1, 0); PG8_SCHED; PG8_LDA(At, 1, 0); PG8_STAGE(PG8_SA(0, 1), a2 + hstep, voffA);
;             PG8_WAIT_L(8); PG8_BAR; PG8_WAIT_L(0); PG8_MMA(0, 0, At, B0); PG8_BAR; PG8_SCHED;
;             PG8_LDB(B1, 1, 1); PG8_STAGE(PG8_SB(1, 0), b3, voffB);
;             PG8_BAR; PG8_WAIT_L(0); PG8_MMA(0, 1, At, B1); PG8_BAR;
;             PG8_LDA(At, 1, 1); PG8_STAGE(PG8_SA(1, 0), a3, voffA);
;             PG8_BAR; PG8_WAIT_L(0); PG8_MMA(1, 0, At, B0); PG8_BAR; PG8_SCHED;
;             PG8_STAGE(PG8_SB(1, 1), b3 + hstep, voffB);
;             PG8_WAIT_V(6); PG8_BAR; PG8_MMA(1, 1, At, B1); PG8_BAR;
	s_add_u32 s38, s56, 0x80000
	s_addc_u32 s39, s57, 0
	s_add_i32 s52, s52, s65
	v_lshl_add_u64 v[140:141], s[38:39], 0, v[0:1]
	s_mov_b32 m0, s52
	s_nop 0
	global_load_lds_dwordx4 v[140:141], off
	v_lshl_add_u64 v[140:141], s[38:39], 0, v[130:131]
	s_add_i32 m0, s52, 0x2000
	s_nop 0
	global_load_lds_dwordx4 v[140:141], off
	s_add_u32 s38, s58, 0x80000
	s_addc_u32 s39, s59, 0
	s_mov_b32 m0, s66
	v_lshl_add_u64 v[192:193], s[38:39], 0, v[0:1]
	global_load_lds_dwordx4 v[192:193], off
	v_lshl_add_u64 v[192:193], s[38:39], 0, v[130:131]
	s_mov_b32 m0, s67
	s_nop 0
	global_load_lds_dwordx4 v[192:193], off
	s_add_i32 s52, 0, 0x18000
	v_add_u32_e32 v152, s52, v137
	ds_read_b128 v[140:143], v152
	ds_read_b128 v[144:147], v152 offset:1024
	ds_read_b128 v[148:151], v152 offset:2048
	ds_read_b128 v[152:155], v152 offset:3072
	ds_read_b128 v[160:163], v139 offset:32768
	ds_read_b128 v[164:167], v139 offset:33792
	ds_read_b128 v[168:171], v139 offset:34816
	ds_read_b128 v[172:175], v139 offset:35840
	ds_read_b128 v[176:179], v139 offset:36864
	ds_read_b128 v[180:183], v139 offset:37888
	ds_read_b128 v[184:187], v139 offset:38912
	ds_read_b128 v[188:191], v139 offset:39936
	s_add_i32 s53, 0, 0x1c000
	v_add_u32_e32 v204, s53, v137
	ds_read_b128 v[192:195], v204
	ds_read_b128 v[196:199], v204 offset:1024
	ds_read_b128 v[200:203], v204 offset:2048
	ds_read_b128 v[204:207], v204 offset:3072
	s_waitcnt vmcnt(8)
	s_waitcnt lgkmcnt(4)
	s_barrier
	s_waitcnt lgkmcnt(0)
	s_setprio 1
	v_mfma_f32_16x16x32_bf16 v[126:129], v[140:143], v[160:163], v[126:129]
	v_mfma_f32_16x16x32_bf16 v[122:125], v[148:151], v[160:163], v[122:125]
	v_mfma_f32_16x16x32_bf16 v[118:121], v[140:143], v[168:171], v[118:121]
	v_mfma_f32_16x16x32_bf16 v[114:117], v[148:151], v[168:171], v[114:117]
	v_mfma_f32_16x16x32_bf16 v[106:109], v[140:143], v[176:179], v[106:109]
	v_mfma_f32_16x16x32_bf16 v[98:101], v[148:151], v[176:179], v[98:101]
	v_mfma_f32_16x16x32_bf16 v[90:93], v[140:143], v[184:187], v[90:93]
	v_mfma_f32_16x16x32_bf16 v[82:85], v[148:151], v[184:187], v[82:85]
	v_mfma_f32_16x16x32_bf16 v[126:129], v[144:147], v[164:167], v[126:129]
	v_mfma_f32_16x16x32_bf16 v[122:125], v[152:155], v[164:167], v[122:125]
	v_mfma_f32_16x16x32_bf16 v[118:121], v[144:147], v[172:175], v[118:121]
	v_mfma_f32_16x16x32_bf16 v[114:117], v[152:155], v[172:175], v[114:117]
	v_mfma_f32_16x16x32_bf16 v[106:109], v[144:147], v[180:183], v[106:109]
	v_mfma_f32_16x16x32_bf16 v[98:101], v[152:155], v[180:183], v[98:101]
	v_mfma_f32_16x16x32_bf16 v[90:93], v[144:147], v[188:191], v[90:93]
	v_mfma_f32_16x16x32_bf16 v[82:85], v[152:155], v[188:191], v[82:85]
	v_mfma_f32_16x16x32_bf16 v[110:113], v[192:195], v[160:163], v[110:113]
	v_mfma_f32_16x16x32_bf16 v[102:105], v[200:203], v[160:163], v[102:105]
	v_mfma_f32_16x16x32_bf16 v[94:97], v[192:195], v[168:171], v[94:97]
	v_mfma_f32_16x16x32_bf16 v[86:89], v[200:203], v[168:171], v[86:89]
	v_mfma_f32_16x16x32_bf16 v[78:81], v[192:195], v[176:179], v[78:81]
	v_mfma_f32_16x16x32_bf16 v[74:77], v[200:203], v[176:179], v[74:77]
	v_mfma_f32_16x16x32_bf16 v[70:73], v[192:195], v[184:187], v[70:73]
	v_mfma_f32_16x16x32_bf16 v[66:69], v[200:203], v[184:187], v[66:69]
	v_mfma_f32_16x16x32_bf16 v[110:113], v[196:199], v[164:167], v[110:113]
	v_mfma_f32_16x16x32_bf16 v[102:105], v[204:207], v[164:167], v[102:105]
	v_mfma_f32_16x16x32_bf16 v[94:97], v[196:199], v[172:175], v[94:97]
	v_mfma_f32_16x16x32_bf16 v[86:89], v[204:207], v[172:175], v[86:89]
	v_mfma_f32_16x16x32_bf16 v[78:81], v[196:199], v[180:183], v[78:81]
	v_mfma_f32_16x16x32_bf16 v[74:77], v[204:207], v[180:183], v[74:77]
	v_mfma_f32_16x16x32_bf16 v[70:73], v[196:199], v[188:191], v[70:73]
	v_mfma_f32_16x16x32_bf16 v[66:69], v[204:207], v[188:191], v[66:69]
	s_setprio 0
	s_barrier
	s_add_i32 s38, s52, s65
	v_lshl_add_u64 v[156:157], v[156:157], 0, s[36:37]
	s_mov_b32 m0, s38
	s_nop 0
	global_load_lds_dwordx4 v[156:157], off
	v_lshl_add_u64 v[156:157], v[210:211], 0, s[36:37]
	s_add_i32 m0, s38, 0x2000
	s_nop 0
	global_load_lds_dwordx4 v[156:157], off
	s_mov_b32 m0, s68
	v_lshl_add_u64 v[156:157], v[212:213], 0, s[36:37]
	global_load_lds_dwordx4 v[156:157], off
	v_lshl_add_u64 v[156:157], v[214:215], 0, s[36:37]
	s_mov_b32 m0, s69
	s_nop 0
	global_load_lds_dwordx4 v[156:157], off
	ds_read_b128 v[160:163], v139 offset:49152
	ds_read_b128 v[164:167], v139 offset:50176
	ds_read_b128 v[168:171], v139 offset:51200
	ds_read_b128 v[172:175], v139 offset:52224
	ds_read_b128 v[176:179], v139 offset:53248
	ds_read_b128 v[180:183], v139 offset:54272
	ds_read_b128 v[184:187], v139 offset:55296
	ds_read_b128 v[188:191], v139 offset:56320
	s_waitcnt vmcnt(6)
	s_waitcnt lgkmcnt(0)
	s_barrier
; #define PG8_STAGE(bufoff, gbase, voff) do { _Pragma("unroll") for (int _i = 0; _i < 2; ++_i) \
;         __builtin_amdgcn_global_load_lds((const unsigned*)((const char*)(gbase) + (voff)[_i]), (LAS unsigned*)(lds + (bufoff) + ldsw + _i * 8192), 16, 0, 0); } while (0)
; #define PG8_LDA(dst, b, h) do { _Pragma("unroll") for (int m = 0; m < 4; ++m) _Pragma("unroll") for (int k = 0; k < 2; ++k) dst[m][k] = *(const LAS bf16x8*)(lds + PG8_SA(b, h) + aoff + m * 2048 + k * 1024); } while (0)
; #define PG8_MMA(ai, bj, At, Bt) do { __builtin_amdgcn_s_setprio(1); _Pragma("unroll") for (int m = 0; m < 4; ++m) _Pragma("unroll") for (int n = 0; n < 2; ++n) _Pragma("unroll") for (int k = 0; k < 2; ++k) \
;         acc[ai][bj][m][n] = __builtin_amdgcn_mfma_f32_16x16x32_bf16(Bt[n][k], At[m][k], acc[ai][bj][m][n], 0, 0, 0); __builtin_amdgcn_s_setprio(0); } while (0)
; #define PG8_WAIT_V(n) asm volatile("s_waitcnt vmcnt(" #n ")" ::: "memory")
; #define PG8_WAIT_L(n) asm volatile("s_waitcnt lgkmcnt(" #n ")" ::: "memory")
; #define PG8_BAR __builtin_amdgcn_s_barrier()
; #define PG8_SCHED __builtin_amdgcn_sched_barrier(0)
;     __device__ __forceinline__ void operator()(const f32x4 (&acc)[2][2][4][2], const Unit& u, int wr, int wc, int fr, int fq) const {
;         const int row0 = u.pm * BM + wr * 64 + fr, col0 = u.pn * BM + wc * 32 + 4 * fq;
;         float* base = part + (size_t)u.ks * Mp * ldc;
; #pragma unroll
;         for (int ai = 0; ai < 2; ++ai)
; #pragma unroll
;             for (int m = 0; m < 4; ++m) { float* rowp = base + (size_t)(row0 + ai * HALF + m * 16) * ldc + col0;
; #pragma unroll
;                 for (int bj = 0; bj < 2; ++bj)
; #pragma unroll
;                     for (int n = 0; n < 2; ++n) *(f32x4*)(rowp + bj * HALF + n * 16) = acc[ai][bj][m][n]; }
;     }
; template <class Epi, class Sched>
; __device__ __forceinline__ void gemm_phase(LAS unsigned char* lds, const Gemm g, const Sched& S, const Epi& E) {
;     ...
;             PG8_LDA(At, 1, 1); PG8_STAGE(PG8_SA(1, 0), a3, voffA);
;             PG8_BAR; PG8_WAIT_L(0); PG8_MMA(1, 0, At, B0); PG8_BAR; PG8_SCHED;
;             PG8_STAGE(PG8_SB(1, 1), b3 + hstep, voffB);
;             PG8_WAIT_V(6); PG8_BAR; PG8_MMA(1, 1, At, B1); PG8_BAR;
;         }
;         E(acc, cur, wr, wc, fr, fq);
;         if (!has_next) break;
	s_setprio 1
	v_mfma_f32_16x16x32_bf16 v[62:65], v[140:143], v[160:163], v[62:65]
	v_mfma_f32_16x16x32_bf16 v[58:61], v[148:151], v[160:163], v[58:61]
	v_mfma_f32_16x16x32_bf16 v[54:57], v[140:143], v[168:171], v[54:57]
	v_mfma_f32_16x16x32_bf16 v[50:53], v[148:151], v[168:171], v[50:53]
	v_mfma_f32_16x16x32_bf16 v[38:41], v[140:143], v[176:179], v[38:41]
	v_mfma_f32_16x16x32_bf16 v[34:37], v[148:151], v[176:179], v[34:37]
	v_mfma_f32_16x16x32_bf16 v[22:25], v[140:143], v[184:187], v[22:25]
	v_mfma_f32_16x16x32_bf16 v[18:21], v[148:151], v[184:187], v[18:21]
	v_mfma_f32_16x16x32_bf16 v[62:65], v[144:147], v[164:167], v[62:65]
	v_mfma_f32_16x16x32_bf16 v[58:61], v[152:155], v[164:167], v[58:61]
	v_mfma_f32_16x16x32_bf16 v[54:57], v[144:147], v[172:175], v[54:57]
	v_mfma_f32_16x16x32_bf16 v[50:53], v[152:155], v[172:175], v[50:53]
	v_mfma_f32_16x16x32_bf16 v[38:41], v[144:147], v[180:183], v[38:41]
	v_mfma_f32_16x16x32_bf16 v[34:37], v[152:155], v[180:183], v[34:37]
	v_mfma_f32_16x16x32_bf16 v[22:25], v[144:147], v[188:191], v[22:25]
	v_mfma_f32_16x16x32_bf16 v[18:21], v[152:155], v[188:191], v[18:21]
	s_add_u32 s38, s56, 0x80080
	s_addc_u32 s39, s57, 0
	s_add_i32 s52, s53, s65
	v_lshl_add_u64 v[140:141], s[38:39], 0, v[0:1]
	s_mov_b32 m0, s52
	s_nop 0
	global_load_lds_dwordx4 v[140:141], off
	v_lshl_add_u64 v[140:141], s[38:39], 0, v[130:131]
	s_add_i32 m0, s52, 0x2000
	s_nop 0
	global_load_lds_dwordx4 v[140:141], off
	v_mfma_f32_16x16x32_bf16 v[46:49], v[192:195], v[160:163], v[46:49]
	v_mfma_f32_16x16x32_bf16 v[42:45], v[200:203], v[160:163], v[42:45]
	v_mfma_f32_16x16x32_bf16 v[30:33], v[192:195], v[168:171], v[30:33]
	v_mfma_f32_16x16x32_bf16 v[26:29], v[200:203], v[168:171], v[26:29]
	v_mfma_f32_16x16x32_bf16 v[14:17], v[192:195], v[176:179], v[14:17]
	v_mfma_f32_16x16x32_bf16 v[10:13], v[200:203], v[176:179], v[10:13]
	v_mfma_f32_16x16x32_bf16 v[6:9], v[192:195], v[184:187], v[6:9]
	v_mfma_f32_16x16x32_bf16 v[2:5], v[200:203], v[184:187], v[2:5]
	v_mfma_f32_16x16x32_bf16 v[46:49], v[196:199], v[164:167], v[46:49]
	v_mfma_f32_16x16x32_bf16 v[42:45], v[204:207], v[164:167], v[42:45]
	v_mfma_f32_16x16x32_bf16 v[30:33], v[196:199], v[172:175], v[30:33]
	v_mfma_f32_16x16x32_bf16 v[26:29], v[204:207], v[172:175], v[26:29]
	v_mfma_f32_16x16x32_bf16 v[14:17], v[196:199], v[180:183], v[14:17]
	v_mfma_f32_16x16x32_bf16 v[10:13], v[204:207], v[180:183], v[10:13]
	v_mfma_f32_16x16x32_bf16 v[6:9], v[196:199], v[188:191], v[6:9]
	v_mfma_f32_16x16x32_bf16 v[2:5], v[204:207], v[188:191], v[2:5]
	s_setprio 0
	s_add_i32 s73, s73, 2
	s_add_u32 s71, s71, 0x100
	s_addc_u32 s72, s72, 0
	s_cmp_gt_u32 s73, 5
	s_mov_b64 s[52:53], s[54:55]
	s_barrier
	s_cbranch_scc0 .LBB0_113
	s_ashr_i32 s11, s10, 31
	s_lshl_b64 s[10:11], s[10:11], 24
	v_lshl_or_b32 v140, s26, 8, v138
	s_add_u32 s10, s8, s10
	v_lshl_add_u32 v142, s24, 8, v136
	s_addc_u32 s11, s9, s11
	v_ashrrev_i32_e32 v141, 31, v140
	v_ashrrev_i32_e32 v143, 31, v142
	v_lshl_add_u64 v[140:141], v[140:141], 2, s[10:11]
	v_lshlrev_b64 v[144:145], 13, v[142:143]
	v_lshl_add_u64 v[144:145], v[140:141], 0, v[144:145]
	global_store_dwordx4 v[144:145], v[126:129], off
	global_store_dwordx4 v[144:145], v[122:125], off offset:64
	global_store_dwordx4 v[144:145], v[110:113], off offset:512
	global_store_dwordx4 v[144:145], v[102:105], off offset:576
	s_mov_b64 s[10:11], 0x100000
	s_mov_b32 s26, s40
	v_or_b32_e32 v102, 16, v142
	v_ashrrev_i32_e32 v103, 31, v102
	v_lshlrev_b64 v[102:103], 13, v[102:103]
	v_lshl_add_u64 v[102:103], v[140:141], 0, v[102:103]
	global_store_dwordx4 v[102:103], v[118:121], off
	global_store_dwordx4 v[102:103], v[114:117], off offset:64
	global_store_dwordx4 v[102:103], v[94:97], off offset:512
	global_store_dwordx4 v[102:103], v[86:89], off offset:576
	s_mov_b32 s24, s44
	s_mov_b64 s[54:55], s[50:51]
	v_or_b32_e32 v86, 32, v142
	v_ashrrev_i32_e32 v87, 31, v86
	v_lshlrev_b64 v[86:87], 13, v[86:87]
	v_lshl_add_u64 v[86:87], v[140:141], 0, v[86:87]
	global_store_dwordx4 v[86:87], v[106:109], off
	global_store_dwordx4 v[86:87], v[98:101], off offset:64
	global_store_dwordx4 v[86:87], v[78:81], off offset:512
	global_store_dwordx4 v[86:87], v[74:77], off offset:576
	s_mov_b64 s[52:53], s[48:49]
	s_nop 0
	v_or_b32_e32 v74, 48, v142
	v_ashrrev_i32_e32 v75, 31, v74
	v_lshlrev_b64 v[74:75], 13, v[74:75]
	v_lshl_add_u64 v[74:75], v[140:141], 0, v[74:75]
	global_store_dwordx4 v[74:75], v[90:93], off
	global_store_dwordx4 v[74:75], v[82:85], off offset:64
	global_store_dwordx4 v[74:75], v[70:73], off offset:512
	global_store_dwordx4 v[74:75], v[66:69], off offset:576
	s_nop 1
	v_add_co_u32_e32 v68, vcc, s93, v144
	v_lshl_add_u64 v[66:67], v[144:145], 0, s[10:11]
	s_nop 0
	v_addc_co_u32_e32 v69, vcc, 0, v145, vcc
	s_mov_b64 s[10:11], 0x120000
	global_store_dwordx4 v[68:69], v[62:65], off
	global_store_dwordx4 v[66:67], v[58:61], off offset:64
	global_store_dwordx4 v[66:67], v[46:49], off offset:512
	global_store_dwordx4 v[66:67], v[42:45], off offset:576
	s_nop 1
	v_lshl_add_u64 v[42:43], v[144:145], 0, s[10:11]
	s_mov_b32 s10, 0x120000
	v_add_co_u32_e32 v44, vcc, s10, v144
	s_mov_b64 s[10:11], 0x140000
	s_nop 0
	v_addc_co_u32_e32 v45, vcc, 0, v145, vcc
	global_store_dwordx4 v[44:45], v[54:57], off
	global_store_dwordx4 v[42:43], v[50:53], off offset:64
	global_store_dwordx4 v[42:43], v[30:33], off offset:512
	global_store_dwordx4 v[42:43], v[26:29], off offset:576
	s_nop 1
	v_lshl_add_u64 v[26:27], v[144:145], 0, s[10:11]
	s_mov_b32 s10, 0x140000
	v_add_co_u32_e32 v28, vcc, s10, v144
	s_mov_b64 s[10:11], 0x160000
	s_nop 0
	v_addc_co_u32_e32 v29, vcc, 0, v145, vcc
	global_store_dwordx4 v[28:29], v[38:41], off
	global_store_dwordx4 v[26:27], v[34:37], off offset:64
	global_store_dwordx4 v[26:27], v[14:17], off offset:512
	global_store_dwordx4 v[26:27], v[10:13], off offset:576
	s_nop 1
	v_add_co_u32_e32 v12, vcc, 0x160000, v144
	v_lshl_add_u64 v[10:11], v[144:145], 0, s[10:11]
	s_nop 0
	v_addc_co_u32_e32 v13, vcc, 0, v145, vcc
	s_and_b64 vcc, exec, s[46:47]
	s_mov_b32 s10, s28
	global_store_dwordx4 v[12:13], v[22:25], off
	global_store_dwordx4 v[10:11], v[18:21], off offset:64
	global_store_dwordx4 v[10:11], v[6:9], off offset:512
	global_store_dwordx4 v[10:11], v[2:5], off offset:576
	s_cbranch_vccz .LBB0_110
	s_waitcnt vmcnt(0)
	s_cmpk_gt_u32 s60, 0xff
	s_cbranch_scc1 .LBB0_117
	s_barrier

; #define PG8_STAGE(bufoff, gbase, voff) do { _Pragma("unroll") for (int _i = 0; _i < 2; ++_i) \
;         __builtin_amdgcn_global_load_lds((const unsigned*)((const char*)(gbase) + (voff)[_i]), (LAS unsigned*)(lds + (bufoff) + ldsw + _i * 8192), 16, 0, 0); } while (0)
; #define PG8_LDA(dst, b, h) do { _Pragma("unroll") for (int m = 0; m < 4; ++m) _Pragma("unroll") for (int k = 0; k < 2; ++k) dst[m][k] = *(const LAS bf16x8*)(lds + PG8_SA(b, h) + aoff + m * 2048 + k * 1024); } while (0)
; #define PG8_LDB(dst, b, h) do { _Pragma("unroll") for (int n = 0; n < 2; ++n) _Pragma("unroll") for (int k = 0; k < 2; ++k) dst[n][k] = *(const LAS bf16x8*)(lds + PG8_SB(b, h) + boff + n * 2048 + k * 1024); } while (0)
; #define PG8_MMA(ai, bj, At, Bt) do { __builtin_amdgcn_s_setprio(1); _Pragma("unroll") for (int m = 0; m < 4; ++m) _Pragma("unroll") for (int n = 0; n < 2; ++n) _Pragma("unroll") for (int k = 0; k < 2; ++k) \
;         acc[ai][bj][m][n] = __builtin_amdgcn_mfma_f32_16x16x32_bf16(Bt[n][k], At[m][k], acc[ai][bj][m][n], 0, 0, 0); __builtin_amdgcn_s_setprio(0); } while (0)
; #define PG8_WAIT_V(n) asm volatile("s_waitcnt vmcnt(" #n ")" ::: "memory")
; #define PG8_WAIT_L(n) asm volatile("s_waitcnt lgkmcnt(" #n ")" ::: "memory")
; #define PG8_BAR __builtin_amdgcn_s_barrier()
; template <class Epi, class Sched>
; __device__ __forceinline__ void gemm_phase(LAS unsigned char* lds, const Gemm g, const Sched& S, const Epi& E) {
;     ...
;             const bool last = (t == nt - 2);
;             const char* a1 = cA + (size_t)(t + 1) * kstep;
;             const char* a2 = last ? nA : cA + (size_t)(t + 2) * kstep; const char* b2 = last ? nB : cB + (size_t)(t + 2) * kstep;
;             const char* a3 = a2 + kstep; const char* b3 = b2 + kstep;
;             PG8_LDB(B0, 0, 0); PG8_SCHED; PG8_LDA(At, 0, 0); PG8_STAGE(PG8_SA(1, 1), a1 + hstep, voffA);
;             PG8_WAIT_L(8); PG8_BAR; PG8_WAIT_L(0); PG8_MMA(0, 0, At, B0); PG8_BAR; PG8_SCHED;
;             PG8_LDB(B1, 0, 1); PG8_STAGE(PG8_SB(0, 0), b2, voffB);
;             PG8_BAR; PG8_WAIT_L(0); PG8_MMA(0, 1, At, B1); PG8_BAR;
;             PG8_LDA(At, 0, 1); PG8_STAGE(PG8_SA(0, 0), a2, voffA);
;             PG8_BAR; PG8_WAIT_L(0); PG8_MMA(1, 0, At, B0); PG8_BAR; PG8_SCHED;
;             PG8_STAGE(PG8_SB(0, 1), b2 + hstep, voffB);
;             PG8_WAIT_V(6); PG8_BAR; PG8_MMA(1, 1, At, B1); PG8_BAR;
.LBB0_354:
	s_add_u32 s38, s50, 0xfff80080
	s_addc_u32 s39, s51, -1
	s_cmp_eq_u32 s70, 28
	s_cselect_b32 s55, s9, s39
	s_cselect_b32 s54, s66, s38
	s_cselect_b32 s53, s43, s69
	s_cselect_b32 s52, s67, s68
	v_lshl_add_u64 v[156:157], s[50:51], 0, v[138:139]
	s_add_i32 m0, s29, 0xc000
	s_nop 0
	global_load_lds_dwordx4 v[156:157], off
	v_lshl_add_u64 v[156:157], s[50:51], 0, v[136:137]
	s_add_i32 m0, s29, 0xe000
	s_nop 0
	global_load_lds_dwordx4 v[156:157], off
	s_add_i32 s71, 0, 0x10000
	v_add_u32_e32 v156, s71, v145
	ds_read_b128 v[140:143], v156
	ds_read_b128 v[148:151], v156 offset:1024
	ds_read_b128 v[152:155], v156 offset:2048
	ds_read_b128 v[160:163], v156 offset:3072
	ds_read_b128 v[164:167], v147
	ds_read_b128 v[168:171], v147 offset:1024
	ds_read_b128 v[172:175], v147 offset:2048
	ds_read_b128 v[176:179], v147 offset:3072
	ds_read_b128 v[180:183], v147 offset:4096
	ds_read_b128 v[184:187], v147 offset:5120
	ds_read_b128 v[188:191], v147 offset:6144
	ds_read_b128 v[192:195], v147 offset:7168
	s_add_i32 s38, 0, 0x14000
	v_add_u32_e32 v156, s38, v145
	ds_read_b128 v[196:199], v156
	ds_read_b128 v[200:203], v156 offset:1024
	ds_read_b128 v[204:207], v156 offset:2048
	ds_read_b128 v[210:213], v156 offset:3072
	s_waitcnt vmcnt(8)
	s_waitcnt lgkmcnt(4)
	s_barrier
	s_waitcnt lgkmcnt(0)
	s_setprio 1
	v_mfma_f32_16x16x32_bf16 v[126:129], v[140:143], v[164:167], v[126:129]
	v_mfma_f32_16x16x32_bf16 v[122:125], v[152:155], v[164:167], v[122:125]
	v_mfma_f32_16x16x32_bf16 v[118:121], v[140:143], v[172:175], v[118:121]
	v_mfma_f32_16x16x32_bf16 v[110:113], v[152:155], v[172:175], v[110:113]
	v_mfma_f32_16x16x32_bf16 v[102:105], v[140:143], v[180:183], v[102:105]
	v_mfma_f32_16x16x32_bf16 v[94:97], v[152:155], v[180:183], v[94:97]
	v_mfma_f32_16x16x32_bf16 v[86:89], v[140:143], v[188:191], v[86:89]
	v_mfma_f32_16x16x32_bf16 v[78:81], v[152:155], v[188:191], v[78:81]
	v_mfma_f32_16x16x32_bf16 v[126:129], v[148:151], v[168:171], v[126:129]
	v_mfma_f32_16x16x32_bf16 v[122:125], v[160:163], v[168:171], v[122:125]
	v_mfma_f32_16x16x32_bf16 v[118:121], v[148:151], v[176:179], v[118:121]
	v_mfma_f32_16x16x32_bf16 v[110:113], v[160:163], v[176:179], v[110:113]
	v_mfma_f32_16x16x32_bf16 v[102:105], v[148:151], v[184:187], v[102:105]
	v_mfma_f32_16x16x32_bf16 v[94:97], v[160:163], v[184:187], v[94:97]
	v_mfma_f32_16x16x32_bf16 v[86:89], v[148:151], v[192:195], v[86:89]
	v_mfma_f32_16x16x32_bf16 v[78:81], v[160:163], v[192:195], v[78:81]
	v_mfma_f32_16x16x32_bf16 v[114:117], v[196:199], v[164:167], v[114:117]
	v_mfma_f32_16x16x32_bf16 v[106:109], v[204:207], v[164:167], v[106:109]
	v_mfma_f32_16x16x32_bf16 v[98:101], v[196:199], v[172:175], v[98:101]
	v_mfma_f32_16x16x32_bf16 v[90:93], v[204:207], v[172:175], v[90:93]
	v_mfma_f32_16x16x32_bf16 v[82:85], v[196:199], v[180:183], v[82:85]
	v_mfma_f32_16x16x32_bf16 v[74:77], v[204:207], v[180:183], v[74:77]
	v_mfma_f32_16x16x32_bf16 v[70:73], v[196:199], v[188:191], v[70:73]
	v_mfma_f32_16x16x32_bf16 v[66:69], v[204:207], v[188:191], v[66:69]
	v_mfma_f32_16x16x32_bf16 v[114:117], v[200:203], v[168:171], v[114:117]
	v_mfma_f32_16x16x32_bf16 v[106:109], v[210:213], v[168:171], v[106:109]
	v_mfma_f32_16x16x32_bf16 v[98:101], v[200:203], v[176:179], v[98:101]
	v_mfma_f32_16x16x32_bf16 v[90:93], v[210:213], v[176:179], v[90:93]
	v_mfma_f32_16x16x32_bf16 v[82:85], v[200:203], v[184:187], v[82:85]
	v_mfma_f32_16x16x32_bf16 v[74:77], v[210:213], v[184:187], v[74:77]
	v_mfma_f32_16x16x32_bf16 v[70:73], v[200:203], v[192:195], v[70:73]
	v_mfma_f32_16x16x32_bf16 v[66:69], v[210:213], v[192:195], v[66:69]
	s_setprio 0
	s_barrier
	s_add_i32 s39, s71, s56
	v_lshl_add_u64 v[156:157], s[52:53], 0, v[0:1]
	s_mov_b32 m0, s39
	v_lshl_add_u64 v[214:215], s[52:53], 0, v[134:135]
	global_load_lds_dwordx4 v[156:157], off
	s_add_i32 m0, s39, 0x2000
	s_nop 0
	global_load_lds_dwordx4 v[214:215], off
	s_mov_b32 m0, s29
	v_lshl_add_u64 v[216:217], s[54:55], 0, v[130:131]
	global_load_lds_dwordx4 v[216:217], off
	v_lshl_add_u64 v[224:225], s[54:55], 0, v[132:133]
	s_mov_b32 m0, s41
	s_nop 0
	global_load_lds_dwordx4 v[224:225], off
	ds_read_b128 v[164:167], v147 offset:16384
	ds_read_b128 v[168:171], v147 offset:17408
	ds_read_b128 v[172:175], v147 offset:18432
	ds_read_b128 v[176:179], v147 offset:19456
	ds_read_b128 v[180:183], v147 offset:20480
	ds_read_b128 v[184:187], v147 offset:21504
	ds_read_b128 v[188:191], v147 offset:22528
	ds_read_b128 v[192:195], v147 offset:23552
	s_waitcnt vmcnt(6)
	s_waitcnt lgkmcnt(0)
	s_barrier
	s_setprio 1
	v_mfma_f32_16x16x32_bf16 v[62:65], v[140:143], v[164:167], v[62:65]
	v_mfma_f32_16x16x32_bf16 v[58:61], v[152:155], v[164:167], v[58:61]
	v_mfma_f32_16x16x32_bf16 v[54:57], v[140:143], v[172:175], v[54:57]
	v_mfma_f32_16x16x32_bf16 v[46:49], v[152:155], v[172:175], v[46:49]
	v_mfma_f32_16x16x32_bf16 v[38:41], v[140:143], v[180:183], v[38:41]
	v_mfma_f32_16x16x32_bf16 v[30:33], v[152:155], v[180:183], v[30:33]
	v_mfma_f32_16x16x32_bf16 v[22:25], v[140:143], v[188:191], v[22:25]
	v_mfma_f32_16x16x32_bf16 v[14:17], v[152:155], v[188:191], v[14:17]
	v_mfma_f32_16x16x32_bf16 v[62:65], v[148:151], v[168:171], v[62:65]
	v_mfma_f32_16x16x32_bf16 v[58:61], v[160:163], v[168:171], v[58:61]
	v_mfma_f32_16x16x32_bf16 v[54:57], v[148:151], v[176:179], v[54:57]
	v_mfma_f32_16x16x32_bf16 v[46:49], v[160:163], v[176:179], v[46:49]
	v_mfma_f32_16x16x32_bf16 v[38:41], v[148:151], v[184:187], v[38:41]
	v_mfma_f32_16x16x32_bf16 v[30:33], v[160:163], v[184:187], v[30:33]
	v_mfma_f32_16x16x32_bf16 v[22:25], v[148:151], v[192:195], v[22:25]
	v_mfma_f32_16x16x32_bf16 v[14:17], v[160:163], v[192:195], v[14:17]
	v_mfma_f32_16x16x32_bf16 v[50:53], v[196:199], v[164:167], v[50:53]
	v_mfma_f32_16x16x32_bf16 v[42:45], v[204:207], v[164:167], v[42:45]
	v_mfma_f32_16x16x32_bf16 v[34:37], v[196:199], v[172:175], v[34:37]
	v_mfma_f32_16x16x32_bf16 v[26:29], v[204:207], v[172:175], v[26:29]
	v_mfma_f32_16x16x32_bf16 v[18:21], v[196:199], v[180:183], v[18:21]
	v_mfma_f32_16x16x32_bf16 v[10:13], v[204:207], v[180:183], v[10:13]
	v_mfma_f32_16x16x32_bf16 v[6:9], v[196:199], v[188:191], v[6:9]
	v_mfma_f32_16x16x32_bf16 v[2:5], v[204:207], v[188:191], v[2:5]
	v_mfma_f32_16x16x32_bf16 v[50:53], v[200:203], v[168:171], v[50:53]
	v_mfma_f32_16x16x32_bf16 v[42:45], v[210:213], v[168:171], v[42:45]
	v_mfma_f32_16x16x32_bf16 v[34:37], v[200:203], v[176:179], v[34:37]
	v_mfma_f32_16x16x32_bf16 v[26:29], v[210:213], v[176:179], v[26:29]
	v_mfma_f32_16x16x32_bf16 v[18:21], v[200:203], v[184:187], v[18:21]
	v_mfma_f32_16x16x32_bf16 v[10:13], v[210:213], v[184:187], v[10:13]
	v_mfma_f32_16x16x32_bf16 v[6:9], v[200:203], v[192:195], v[6:9]
	v_mfma_f32_16x16x32_bf16 v[2:5], v[210:213], v[192:195], v[2:5]
	s_setprio 0
	s_barrier
; #define PG8_STAGE(bufoff, gbase, voff) do { _Pragma("unroll") for (int _i = 0; _i < 2; ++_i) \
;         __builtin_amdgcn_global_load_lds((const unsigned*)((const char*)(gbase) + (voff)[_i]), (LAS unsigned*)(lds + (bufoff) + ldsw + _i * 8192), 16, 0, 0); } while (0)
; #define PG8_LDA(dst, b, h) do { _Pragma("unroll") for (int m = 0; m < 4; ++m) _Pragma("unroll") for (int k = 0; k < 2; ++k) dst[m][k] = *(const LAS bf16x8*)(lds + PG8_SA(b, h) + aoff + m * 2048 + k * 1024); } while (0)
; #define PG8_LDB(dst, b, h) do { _Pragma("unroll") for (int n = 0; n < 2; ++n) _Pragma("unroll") for (int k = 0; k < 2; ++k) dst[n][k] = *(const LAS bf16x8*)(lds + PG8_SB(b, h) + boff + n * 2048 + k * 1024); } while (0)
; #define PG8_MMA(ai, bj, At, Bt) do { __builtin_amdgcn_s_setprio(1); _Pragma("unroll") for (int m = 0; m < 4; ++m) _Pragma("unroll") for (int n = 0; n < 2; ++n) _Pragma("unroll") for (int k = 0; k < 2; ++k) \
;         acc[ai][bj][m][n] = __builtin_amdgcn_mfma_f32_16x16x32_bf16(Bt[n][k], At[m][k], acc[ai][bj][m][n], 0, 0, 0); __builtin_amdgcn_s_setprio(0); } while (0)
; #define PG8_WAIT_V(n) asm volatile("s_waitcnt vmcnt(" #n ")" ::: "memory")
; #define PG8_WAIT_L(n) asm volatile("s_waitcnt lgkmcnt(" #n ")" ::: "memory")
; #define PG8_BAR __builtin_amdgcn_s_barrier()
; #define PG8_SCHED __builtin_amdgcn_sched_barrier(0)
; template <class Epi, class Sched>
; __device__ __forceinline__ void gemm_phase(LAS unsigned char* lds, const Gemm g, const Sched& S, const Epi& E) {
;     ...
;             PG8_STAGE(PG8_SB(0, 1), b2 + hstep, voffB);
;             PG8_WAIT_V(6); PG8_BAR; PG8_MMA(1, 1, At, B1); PG8_BAR;
;             PG8_LDB(B0, 1, 0); PG8_SCHED; PG8_LDA(At, 1, 0); PG8_STAGE(PG8_SA(0, 1), a2 + hstep, voffA);
;             PG8_WAIT_L(8); PG8_BAR; PG8_WAIT_L(0); PG8_MMA(0, 0, At, B0); PG8_BAR; PG8_SCHED;
;             PG8_LDB(B1, 1, 1); PG8_STAGE(PG8_SB(1, 0), b3, voffB);
;             PG8_BAR; PG8_WAIT_L(0); PG8_MMA(0, 1, At, B1); PG8_BAR;
;             PG8_LDA(At, 1, 1); PG8_STAGE(PG8_SA(1, 0), a3, voffA);
;             PG8_BAR; PG8_WAIT_L(0); PG8_MMA(1, 0, At, B0); PG8_BAR; PG8_SCHED;
;             PG8_STAGE(PG8_SB(1, 1), b3 + hstep, voffB);
;             PG8_WAIT_V(6); PG8_BAR; PG8_MMA(1, 1, At, B1); PG8_BAR;
	s_add_u32 s72, s52, 0x80000
	s_addc_u32 s73, s53, 0
	s_add_i32 s38, s38, s56
	v_lshl_add_u64 v[140:141], s[72:73], 0, v[0:1]
	s_mov_b32 m0, s38
	s_nop 0
	global_load_lds_dwordx4 v[140:141], off
	v_lshl_add_u64 v[140:141], s[72:73], 0, v[134:135]
	s_add_i32 m0, s38, 0x2000
	s_nop 0
	global_load_lds_dwordx4 v[140:141], off
	s_add_u32 s54, s54, 0x80000
	s_addc_u32 s55, s55, 0
	s_mov_b32 m0, s57
	v_lshl_add_u64 v[196:197], s[54:55], 0, v[130:131]
	global_load_lds_dwordx4 v[196:197], off
	v_lshl_add_u64 v[196:197], s[54:55], 0, v[132:133]
	s_mov_b32 m0, s58
	s_nop 0
	global_load_lds_dwordx4 v[196:197], off
	s_add_i32 s38, 0, 0x18000
	v_add_u32_e32 v160, s38, v145
	ds_read_b128 v[140:143], v160
	ds_read_b128 v[148:151], v160 offset:1024
	ds_read_b128 v[152:155], v160 offset:2048
	ds_read_b128 v[160:163], v160 offset:3072
	ds_read_b128 v[164:167], v147 offset:32768
	ds_read_b128 v[168:171], v147 offset:33792
	ds_read_b128 v[172:175], v147 offset:34816
	ds_read_b128 v[176:179], v147 offset:35840
	ds_read_b128 v[180:183], v147 offset:36864
	ds_read_b128 v[184:187], v147 offset:37888
	ds_read_b128 v[188:191], v147 offset:38912
	ds_read_b128 v[192:195], v147 offset:39936
	s_add_i32 s39, 0, 0x1c000
	v_add_u32_e32 v210, s39, v145
	ds_read_b128 v[196:199], v210
	ds_read_b128 v[200:203], v210 offset:1024
	ds_read_b128 v[204:207], v210 offset:2048
	ds_read_b128 v[210:213], v210 offset:3072
	s_waitcnt vmcnt(8)
	s_waitcnt lgkmcnt(4)
	s_barrier
	s_waitcnt lgkmcnt(0)
	s_setprio 1
	v_mfma_f32_16x16x32_bf16 v[126:129], v[140:143], v[164:167], v[126:129]
	v_mfma_f32_16x16x32_bf16 v[122:125], v[152:155], v[164:167], v[122:125]
	v_mfma_f32_16x16x32_bf16 v[118:121], v[140:143], v[172:175], v[118:121]
	v_mfma_f32_16x16x32_bf16 v[110:113], v[152:155], v[172:175], v[110:113]
	v_mfma_f32_16x16x32_bf16 v[102:105], v[140:143], v[180:183], v[102:105]
	v_mfma_f32_16x16x32_bf16 v[94:97], v[152:155], v[180:183], v[94:97]
	v_mfma_f32_16x16x32_bf16 v[86:89], v[140:143], v[188:191], v[86:89]
	v_mfma_f32_16x16x32_bf16 v[78:81], v[152:155], v[188:191], v[78:81]
	v_mfma_f32_16x16x32_bf16 v[126:129], v[148:151], v[168:171], v[126:129]
	v_mfma_f32_16x16x32_bf16 v[122:125], v[160:163], v[168:171], v[122:125]
	v_mfma_f32_16x16x32_bf16 v[118:121], v[148:151], v[176:179], v[118:121]
	v_mfma_f32_16x16x32_bf16 v[110:113], v[160:163], v[176:179], v[110:113]
	v_mfma_f32_16x16x32_bf16 v[102:105], v[148:151], v[184:187], v[102:105]
	v_mfma_f32_16x16x32_bf16 v[94:97], v[160:163], v[184:187], v[94:97]
	v_mfma_f32_16x16x32_bf16 v[86:89], v[148:151], v[192:195], v[86:89]
	v_mfma_f32_16x16x32_bf16 v[78:81], v[160:163], v[192:195], v[78:81]
	v_mfma_f32_16x16x32_bf16 v[114:117], v[196:199], v[164:167], v[114:117]
	v_mfma_f32_16x16x32_bf16 v[106:109], v[204:207], v[164:167], v[106:109]
	v_mfma_f32_16x16x32_bf16 v[98:101], v[196:199], v[172:175], v[98:101]
	v_mfma_f32_16x16x32_bf16 v[90:93], v[204:207], v[172:175], v[90:93]
	v_mfma_f32_16x16x32_bf16 v[82:85], v[196:199], v[180:183], v[82:85]
	v_mfma_f32_16x16x32_bf16 v[74:77], v[204:207], v[180:183], v[74:77]
	v_mfma_f32_16x16x32_bf16 v[70:73], v[196:199], v[188:191], v[70:73]
	v_mfma_f32_16x16x32_bf16 v[66:69], v[204:207], v[188:191], v[66:69]
	v_mfma_f32_16x16x32_bf16 v[114:117], v[200:203], v[168:171], v[114:117]
	v_mfma_f32_16x16x32_bf16 v[106:109], v[210:213], v[168:171], v[106:109]
	v_mfma_f32_16x16x32_bf16 v[98:101], v[200:203], v[176:179], v[98:101]
	v_mfma_f32_16x16x32_bf16 v[90:93], v[210:213], v[176:179], v[90:93]
	v_mfma_f32_16x16x32_bf16 v[82:85], v[200:203], v[184:187], v[82:85]
	v_mfma_f32_16x16x32_bf16 v[74:77], v[210:213], v[184:187], v[74:77]
	v_mfma_f32_16x16x32_bf16 v[70:73], v[200:203], v[192:195], v[70:73]
	v_mfma_f32_16x16x32_bf16 v[66:69], v[210:213], v[192:195], v[66:69]
	s_setprio 0
	s_barrier
	s_add_i32 s38, s38, s56
	v_lshl_add_u64 v[156:157], v[156:157], 0, s[36:37]
	s_mov_b32 m0, s38
	s_nop 0
	global_load_lds_dwordx4 v[156:157], off
	v_lshl_add_u64 v[156:157], v[214:215], 0, s[36:37]
	s_add_i32 m0, s38, 0x2000
	s_nop 0
	global_load_lds_dwordx4 v[156:157], off
	s_mov_b32 m0, s59
	v_lshl_add_u64 v[156:157], v[216:217], 0, s[36:37]
	global_load_lds_dwordx4 v[156:157], off
	v_lshl_add_u64 v[156:157], v[224:225], 0, s[36:37]
	s_mov_b32 m0, s60
	s_nop 0
	global_load_lds_dwordx4 v[156:157], off
	ds_read_b128 v[164:167], v147 offset:49152
	ds_read_b128 v[168:171], v147 offset:50176
	ds_read_b128 v[172:175], v147 offset:51200
	ds_read_b128 v[176:179], v147 offset:52224
	ds_read_b128 v[180:183], v147 offset:53248
	ds_read_b128 v[184:187], v147 offset:54272
	ds_read_b128 v[188:191], v147 offset:55296
	ds_read_b128 v[192:195], v147 offset:56320
	s_waitcnt vmcnt(6)
	s_waitcnt lgkmcnt(0)
	s_barrier
; #define PG8_STAGE(bufoff, gbase, voff) do { _Pragma("unroll") for (int _i = 0; _i < 2; ++_i) \
;         __builtin_amdgcn_global_load_lds((const unsigned*)((const char*)(gbase) + (voff)[_i]), (LAS unsigned*)(lds + (bufoff) + ldsw + _i * 8192), 16, 0, 0); } while (0)
; #define PG8_MMA(ai, bj, At, Bt) do { __builtin_amdgcn_s_setprio(1); _Pragma("unroll") for (int m = 0; m < 4; ++m) _Pragma("unroll") for (int n = 0; n < 2; ++n) _Pragma("unroll") for (int k = 0; k < 2; ++k) \
;         acc[ai][bj][m][n] = __builtin_amdgcn_mfma_f32_16x16x32_bf16(Bt[n][k], At[m][k], acc[ai][bj][m][n], 0, 0, 0); __builtin_amdgcn_s_setprio(0); } while (0)
; #define PG8_WAIT_V(n) asm volatile("s_waitcnt vmcnt(" #n ")" ::: "memory")
; #define PG8_WAIT_L(n) asm volatile("s_waitcnt lgkmcnt(" #n ")" ::: "memory")
; #define PG8_BAR __builtin_amdgcn_s_barrier()
; #define PG8_SCHED __builtin_amdgcn_sched_barrier(0)
; template <class Epi, class Sched>
; __device__ __forceinline__ void gemm_phase(LAS unsigned char* lds, const Gemm g, const Sched& S, const Epi& E) {
;     ...
;             PG8_BAR; PG8_WAIT_L(0); PG8_MMA(1, 0, At, B0); PG8_BAR; PG8_SCHED;
;             PG8_STAGE(PG8_SB(1, 1), b3 + hstep, voffB);
;             PG8_WAIT_V(6); PG8_BAR; PG8_MMA(1, 1, At, B1); PG8_BAR;
;         }
	s_setprio 1
	v_mfma_f32_16x16x32_bf16 v[62:65], v[140:143], v[164:167], v[62:65]
	v_mfma_f32_16x16x32_bf16 v[58:61], v[152:155], v[164:167], v[58:61]
	v_mfma_f32_16x16x32_bf16 v[54:57], v[140:143], v[172:175], v[54:57]
	v_mfma_f32_16x16x32_bf16 v[46:49], v[152:155], v[172:175], v[46:49]
	v_mfma_f32_16x16x32_bf16 v[38:41], v[140:143], v[180:183], v[38:41]
	v_mfma_f32_16x16x32_bf16 v[30:33], v[152:155], v[180:183], v[30:33]
	v_mfma_f32_16x16x32_bf16 v[22:25], v[140:143], v[188:191], v[22:25]
	v_mfma_f32_16x16x32_bf16 v[14:17], v[152:155], v[188:191], v[14:17]
	v_mfma_f32_16x16x32_bf16 v[62:65], v[148:151], v[168:171], v[62:65]
	v_mfma_f32_16x16x32_bf16 v[58:61], v[160:163], v[168:171], v[58:61]
	v_mfma_f32_16x16x32_bf16 v[54:57], v[148:151], v[176:179], v[54:57]
	v_mfma_f32_16x16x32_bf16 v[46:49], v[160:163], v[176:179], v[46:49]
	v_mfma_f32_16x16x32_bf16 v[38:41], v[148:151], v[184:187], v[38:41]
	v_mfma_f32_16x16x32_bf16 v[30:33], v[160:163], v[184:187], v[30:33]
	v_mfma_f32_16x16x32_bf16 v[22:25], v[148:151], v[192:195], v[22:25]
	v_mfma_f32_16x16x32_bf16 v[14:17], v[160:163], v[192:195], v[14:17]
	s_add_u32 s52, s52, 0x80080
	s_addc_u32 s53, s53, 0
	s_add_i32 s38, s39, s56
	v_lshl_add_u64 v[140:141], s[52:53], 0, v[0:1]
	s_mov_b32 m0, s38
	s_nop 0
	global_load_lds_dwordx4 v[140:141], off
	v_lshl_add_u64 v[140:141], s[52:53], 0, v[134:135]
	s_add_i32 m0, s38, 0x2000
	s_nop 0
	global_load_lds_dwordx4 v[140:141], off
	v_mfma_f32_16x16x32_bf16 v[50:53], v[196:199], v[164:167], v[50:53]
	v_mfma_f32_16x16x32_bf16 v[42:45], v[204:207], v[164:167], v[42:45]
	v_mfma_f32_16x16x32_bf16 v[34:37], v[196:199], v[172:175], v[34:37]
	v_mfma_f32_16x16x32_bf16 v[26:29], v[204:207], v[172:175], v[26:29]
	v_mfma_f32_16x16x32_bf16 v[18:21], v[196:199], v[180:183], v[18:21]
	v_mfma_f32_16x16x32_bf16 v[10:13], v[204:207], v[180:183], v[10:13]
	v_mfma_f32_16x16x32_bf16 v[6:9], v[196:199], v[188:191], v[6:9]
	v_mfma_f32_16x16x32_bf16 v[2:5], v[204:207], v[188:191], v[2:5]
	v_mfma_f32_16x16x32_bf16 v[50:53], v[200:203], v[168:171], v[50:53]
	v_mfma_f32_16x16x32_bf16 v[42:45], v[210:213], v[168:171], v[42:45]
	v_mfma_f32_16x16x32_bf16 v[34:37], v[200:203], v[176:179], v[34:37]
	v_mfma_f32_16x16x32_bf16 v[26:29], v[210:213], v[176:179], v[26:29]
	v_mfma_f32_16x16x32_bf16 v[18:21], v[200:203], v[184:187], v[18:21]
	v_mfma_f32_16x16x32_bf16 v[10:13], v[210:213], v[184:187], v[10:13]
	v_mfma_f32_16x16x32_bf16 v[6:9], v[200:203], v[192:195], v[6:9]
	v_mfma_f32_16x16x32_bf16 v[2:5], v[210:213], v[192:195], v[2:5]
	s_setprio 0
	s_add_i32 s70, s70, 2
	s_add_u32 s68, s68, 0x100
	s_addc_u32 s69, s69, 0
	s_add_u32 s50, s50, 0x100
	s_addc_u32 s51, s51, 0
	s_cmp_gt_u32 s70, 29
	s_barrier
	s_cbranch_scc0 .LBB0_354
; __device__ __forceinline__ unsigned cvt_pk_bf16(float lo, float hi) { unsigned r; asm("v_cvt_pk_bf16_f32 %0, %1, %2" : "=v"(r) : "v"(lo), "v"(hi)); return r; }
;     __device__ __forceinline__ void operator()(const f32x4 (&acc)[2][2][4][2], const Unit& u, int wr, int wc, int fr, int fq) const {
;         const int row0 = u.pm * BM + wr * 64 + fr, col0 = u.pn * BM + wc * 32 + 8 * fq;
; #pragma unroll
;         for (int ai = 0; ai < 2; ++ai)
; #pragma unroll
;             for (int m = 0; m < 4; ++m) { bf16_t* rowp = O + (size_t)(row0 + ai * HALF + m * 16) * ldc + col0;
; #pragma unroll
;                 for (int bj = 0; bj < 2; ++bj) { f32x4 v0 = acc[ai][bj][m][0], v1 = acc[ai][bj][m][1];
;                     if (ACT == 1) {
; #pragma unroll
;                         for (int j = 0; j < 4; ++j) { float a = fmaxf(v0[j], 0.f), b = fmaxf(v1[j], 0.f); v0[j] = a * a; v1[j] = b * b; } }
;                     u32x4 w; w.x = cvt_pk_bf16(v0[0], v0[1]); w.y = cvt_pk_bf16(v0[2], v0[3]); w.z = cvt_pk_bf16(v1[0], v1[1]); w.w = cvt_pk_bf16(v1[2], v1[3]);
;                     if (ACT == 1) __builtin_nontemporal_store(w, (u32x4*)(rowp + bj * HALF));
;                     else *(u32x4*)(rowp + bj * HALF) = w; } }
;     }
	s_load_dwordx2 s[50:51], s[0:1], 0xc0
	v_lshl_add_u32 v150, s28, 8, v144
	v_lshl_or_b32 v142, s40, 8, v146
	v_ashrrev_i32_e32 v143, 31, v142
	v_cvt_pk_bf16_f32 v70, v70, v71
	s_waitcnt lgkmcnt(0)
	v_mov_b64_e32 v[140:141], s[50:51]
	v_cvt_pk_bf16_f32 v71, v72, v73
	v_cvt_pk_bf16_f32 v72, v66, v67
	v_add_u32_e32 v66, 0x80, v150
	v_mad_i64_i32 v[148:149], s[50:51], v150, s17, v[140:141]
	v_lshlrev_b64 v[142:143], 1, v[142:143]
	v_cvt_pk_bf16_f32 v114, v114, v115
	v_cvt_pk_bf16_f32 v115, v116, v117
	v_cvt_pk_bf16_f32 v116, v106, v107
	v_or_b32_e32 v106, 16, v150
	v_mad_i64_i32 v[66:67], s[50:51], v66, s17, v[140:141]
	v_cvt_pk_bf16_f32 v50, v50, v51
	v_cvt_pk_bf16_f32 v51, v52, v53
	v_cvt_pk_bf16_f32 v52, v42, v43
	v_add_u32_e32 v42, 0x90, v150
	v_lshl_add_u64 v[148:149], v[148:149], 0, v[142:143]
	v_mad_i64_i32 v[106:107], s[50:51], v106, s17, v[140:141]
	v_cvt_pk_bf16_f32 v98, v98, v99
	v_cvt_pk_bf16_f32 v99, v100, v101
	v_cvt_pk_bf16_f32 v100, v90, v91
	v_or_b32_e32 v90, 32, v150
	v_lshl_add_u64 v[66:67], v[66:67], 0, v[142:143]
	v_mad_i64_i32 v[42:43], s[50:51], v42, s17, v[140:141]
	v_cvt_pk_bf16_f32 v34, v34, v35
	v_cvt_pk_bf16_f32 v35, v36, v37
	v_cvt_pk_bf16_f32 v36, v26, v27
	v_add_u32_e32 v26, 0xa0, v150
	v_cvt_pk_bf16_f32 v117, v108, v109
	global_store_dwordx4 v[148:149], v[114:117], off offset:256
	v_mad_i64_i32 v[90:91], s[50:51], v90, s17, v[140:141]
	s_nop 0
	v_lshl_add_u64 v[114:115], v[106:107], 0, v[142:143]
	v_cvt_pk_bf16_f32 v82, v82, v83
	v_cvt_pk_bf16_f32 v83, v84, v85
	v_cvt_pk_bf16_f32 v84, v74, v75
	v_or_b32_e32 v74, 48, v150
	v_cvt_pk_bf16_f32 v53, v44, v45
	global_store_dwordx4 v[66:67], v[50:53], off offset:256
	v_mad_i64_i32 v[26:27], s[50:51], v26, s17, v[140:141]
	s_nop 0
	v_lshl_add_u64 v[50:51], v[42:43], 0, v[142:143]
	v_cvt_pk_bf16_f32 v18, v18, v19
	v_cvt_pk_bf16_f32 v19, v20, v21
	v_cvt_pk_bf16_f32 v20, v10, v11
	v_add_u32_e32 v10, 0xb0, v150
	v_cvt_pk_bf16_f32 v101, v92, v93
	global_store_dwordx4 v[114:115], v[98:101], off offset:256
	v_mad_i64_i32 v[74:75], s[50:51], v74, s17, v[140:141]
	s_nop 0
	v_lshl_add_u64 v[98:99], v[90:91], 0, v[142:143]
	v_cvt_pk_bf16_f32 v37, v28, v29
	global_store_dwordx4 v[50:51], v[34:37], off offset:256
	v_mad_i64_i32 v[10:11], s[50:51], v10, s17, v[140:141]
	s_nop 0
	v_lshl_add_u64 v[34:35], v[26:27], 0, v[142:143]
	v_cvt_pk_bf16_f32 v85, v76, v77
	global_store_dwordx4 v[98:99], v[82:85], off offset:256
	v_cvt_pk_bf16_f32 v21, v12, v13
	global_store_dwordx4 v[34:35], v[18:21], off offset:256
	s_and_b64 vcc, exec, s[46:47]
	v_lshl_add_u64 v[82:83], v[74:75], 0, v[142:143]
	v_lshl_add_u64 v[18:19], v[10:11], 0, v[142:143]
	s_mov_b32 s40, s42
	s_mov_b32 s28, s8
	s_mov_b32 s43, s42
	s_mov_b32 s46, s8
	s_mov_b64 s[50:51], s[48:49]
	s_mov_b64 s[52:53], s[44:45]
	v_cvt_pk_bf16_f32 v126, v126, v127
	v_cvt_pk_bf16_f32 v127, v128, v129
	v_cvt_pk_bf16_f32 v128, v122, v123
	v_cvt_pk_bf16_f32 v129, v124, v125
	global_store_dwordx4 v[148:149], v[126:129], off
	v_cvt_pk_bf16_f32 v106, v118, v119
	v_cvt_pk_bf16_f32 v107, v120, v121
	v_cvt_pk_bf16_f32 v108, v110, v111
	v_cvt_pk_bf16_f32 v109, v112, v113
	global_store_dwordx4 v[114:115], v[106:109], off
	v_cvt_pk_bf16_f32 v90, v102, v103
	v_cvt_pk_bf16_f32 v91, v104, v105
	v_cvt_pk_bf16_f32 v92, v94, v95
	v_cvt_pk_bf16_f32 v93, v96, v97
	global_store_dwordx4 v[98:99], v[90:93], off
	v_cvt_pk_bf16_f32 v74, v86, v87
	v_cvt_pk_bf16_f32 v75, v88, v89
	v_cvt_pk_bf16_f32 v76, v78, v79
	v_cvt_pk_bf16_f32 v77, v80, v81
	global_store_dwordx4 v[82:83], v[74:77], off
	v_cvt_pk_bf16_f32 v73, v68, v69
	global_store_dwordx4 v[82:83], v[70:73], off offset:256
	v_cvt_pk_bf16_f32 v62, v62, v63
	v_cvt_pk_bf16_f32 v63, v64, v65
	v_cvt_pk_bf16_f32 v64, v58, v59
	v_cvt_pk_bf16_f32 v65, v60, v61
	global_store_dwordx4 v[66:67], v[62:65], off
	v_cvt_pk_bf16_f32 v42, v54, v55
	v_cvt_pk_bf16_f32 v43, v56, v57
	v_cvt_pk_bf16_f32 v44, v46, v47
	v_cvt_pk_bf16_f32 v45, v48, v49
	global_store_dwordx4 v[50:51], v[42:45], off
	v_cvt_pk_bf16_f32 v26, v38, v39
	v_cvt_pk_bf16_f32 v27, v40, v41
	v_cvt_pk_bf16_f32 v28, v30, v31
	v_cvt_pk_bf16_f32 v29, v32, v33
	global_store_dwordx4 v[34:35], v[26:29], off
	v_cvt_pk_bf16_f32 v10, v22, v23
	v_cvt_pk_bf16_f32 v11, v24, v25
	v_cvt_pk_bf16_f32 v12, v14, v15
	v_cvt_pk_bf16_f32 v13, v16, v17
	global_store_dwordx4 v[18:19], v[10:13], off
	v_cvt_pk_bf16_f32 v6, v6, v7
	v_cvt_pk_bf16_f32 v7, v8, v9
	v_cvt_pk_bf16_f32 v8, v2, v3
	v_cvt_pk_bf16_f32 v9, v4, v5
	global_store_dwordx4 v[18:19], v[6:9], off offset:256
	s_cbranch_vccz .LBB0_346
	s_waitcnt vmcnt(0)
	s_cmpk_gt_u32 s25, 0xff
	s_cbranch_scc1 .LBB0_358
	s_barrier
